# inverted s_setprio toggles in the seven big GEMM loops (priority 1 during load-issue segments, 0 during MFMA clusters)
# baseline (speedup 1.0000x reference)
;     DI bool next(int i, Unit& u) const { const int L = i * 32 + rank; if (L >= ppg * nN) return false; u.pm = ppg * grp + (L % ppg); const int p0 = L / ppg, p1 = p0 + rot; u.pn = rev ? nN - 1 - p0 : (p1 >= nN ? p1 - nN : p1); return true; }
; #define PG8_STAGE(bufoff, gbase, voff) do { _Pragma("unroll") for (int _i = 0; _i < 2; ++_i) \
;         __builtin_amdgcn_global_load_lds((const unsigned*)((const char*)(gbase) + (voff)[_i]), (PG8_LAS unsigned*)(lds + (bufoff) + ldsw + _i * 8192), 16, 0, 0); } while (0)
; #define PG8_LDA(dst, b, h) do { _Pragma("unroll") for (int m = 0; m < 4; ++m) _Pragma("unroll") for (int k = 0; k < 2; ++k) dst[m][k] = *(const PG8_LAS bf16x8*)(lds + PG8_SA(b, h) + aoff + m * 2048 + k * 1024); } while (0)
; #define PG8_LDB(dst, b, h) do { _Pragma("unroll") for (int n = 0; n < 2; ++n) _Pragma("unroll") for (int k = 0; k < 2; ++k) dst[n][k] = *(const PG8_LAS bf16x8*)(lds + PG8_SB(b, h) + boff + n * 2048 + k * 1024); } while (0)
; #define PG8_BAR __builtin_amdgcn_s_barrier()
; template <class Epi, class Sched, bool ALIGN_EPI = false, bool SP2 = false>
; __device__ __forceinline__ void gemm_phase(PG8_LAS unsigned char* lds, const Gemm g, const Sched& S, const Epi& E, const int tid) {
;     ...
;         const bool has_next = S.next(ui + 1, nxt);
;         const char* nA = has_next ? (const char*)g.A + (size_t)nxt.pm * tstep : cA; const char* nB = has_next ? (const char*)g.Bt + (size_t)nxt.pn * tstep : cB;
;         for (int t = 0; t < nt; t += 2) {
;             const bool last = (t == nt - 2);
;             const char* a1 = cA + (size_t)(t + 1) * kstep;
;             const char* a2 = last ? nA : cA + (size_t)(t + 2) * kstep; const char* b2 = last ? nB : cB + (size_t)(t + 2) * kstep;
;             const char* a3 = a2 + kstep; const char* b3 = b2 + kstep;
;             if (last && has_next) S.a_ready(nxt);
;             if constexpr (SP2) {
;             PG8_LDB(B0, 0, 0); PG8_LDB(B1, 0, 1); PG8_SCHED; PG8_LDA(At, 0, 0); PG8_STAGE(PG8_SA(1, 1), a1 + hstep, voffA);
;             PG8_WAIT_V(8); PG8_WAIT_L(0); PG8_BAR; PG8_MMA(0, 0, At, B0); PG8_MMA(0, 1, At, B1); PG8_BAR; PG8_SCHED;
;             PG8_LDA(At, 0, 1); PG8_STAGE(PG8_SB(0, 0), b2, voffB); PG8_STAGE(PG8_SB(0, 1), b2 + hstepB, voffB); PG8_STAGE(PG8_SA(0, 0), a2, voffA);
;             PG8_WAIT_V(8); PG8_WAIT_L(0); PG8_BAR; PG8_MMA(1, 0, At, B0); PG8_MMA(1, 1, At, B1); PG8_BAR; PG8_SCHED;
.LBB0_185:
	s_add_u32 s40, s38, 0xfffc0080
	s_addc_u32 s41, s39, -1
	s_add_i32 s82, 0, 0x10000
	s_cmp_eq_u32 s67, 12
	s_cselect_b32 s43, s3, s41
	s_cselect_b32 s42, s5, s40
	v_add_u32_e32 v154, s82, v163
	s_cselect_b32 s41, s21, s66
	s_cselect_b32 s40, s23, s37
	s_cmp_eq_u32 s67, 12
	s_cselect_b32 s32, 1, 0
	s_andn2_b32 s32, s32, s28
	s_add_i32 s84, 0, 0x14000
	ds_read_b128 v[146:149], v154
	ds_read_b128 v[150:153], v154 offset:1024
	ds_read_b128 v[170:173], v154 offset:2048
	ds_read_b128 v[174:177], v154 offset:3072
	v_add_u32_e32 v154, s84, v163
	ds_read_b128 v[178:181], v154
	ds_read_b128 v[182:185], v154 offset:1024
	ds_read_b128 v[186:189], v154 offset:2048
	ds_read_b128 v[190:193], v154 offset:3072
	v_lshl_add_u64 v[154:155], s[38:39], 0, v[142:143]
	s_add_i32 m0, s63, 0xc000
	ds_read_b128 v[194:197], v166
	ds_read_b128 v[198:201], v166 offset:1024
	ds_read_b128 v[212:215], v166 offset:2048
	ds_read_b128 v[216:219], v166 offset:3072
	ds_read_b128 v[220:223], v166 offset:4096
	ds_read_b128 v[224:227], v166 offset:5120
	ds_read_b128 v[228:231], v166 offset:6144
	ds_read_b128 v[232:235], v166 offset:7168
	global_load_lds_dwordx4 v[154:155], off
	v_lshl_add_u64 v[154:155], s[38:39], 0, v[144:145]
	s_add_i32 m0, s63, 0xe000
	s_nop 0
	global_load_lds_dwordx4 v[154:155], off
	s_waitcnt vmcnt(8)
	s_waitcnt lgkmcnt(0)
	s_barrier
	s_setprio 0
	s_waitcnt lgkmcnt(0)
	v_mfma_f32_16x16x32_bf16 v[128:131], v[146:149], v[194:197], v[128:131]
	v_mfma_f32_16x16x32_bf16 v[124:127], v[170:173], v[194:197], v[124:127]
	v_mfma_f32_16x16x32_bf16 v[112:115], v[146:149], v[212:215], v[112:115]
	v_mfma_f32_16x16x32_bf16 v[108:111], v[170:173], v[212:215], v[108:111]
	v_mfma_f32_16x16x32_bf16 v[96:99], v[146:149], v[220:223], v[96:99]
	v_mfma_f32_16x16x32_bf16 v[92:95], v[170:173], v[220:223], v[92:95]
	v_mfma_f32_16x16x32_bf16 v[80:83], v[146:149], v[228:231], v[80:83]
	v_mfma_f32_16x16x32_bf16 v[76:79], v[170:173], v[228:231], v[76:79]
	v_mfma_f32_16x16x32_bf16 v[128:131], v[150:153], v[198:201], v[128:131]
	v_mfma_f32_16x16x32_bf16 v[124:127], v[174:177], v[198:201], v[124:127]
	v_mfma_f32_16x16x32_bf16 v[112:115], v[150:153], v[216:219], v[112:115]
	v_mfma_f32_16x16x32_bf16 v[108:111], v[174:177], v[216:219], v[108:111]
	v_mfma_f32_16x16x32_bf16 v[96:99], v[150:153], v[224:227], v[96:99]
	v_mfma_f32_16x16x32_bf16 v[92:95], v[174:177], v[224:227], v[92:95]
	v_mfma_f32_16x16x32_bf16 v[80:83], v[150:153], v[232:235], v[80:83]
	v_mfma_f32_16x16x32_bf16 v[76:79], v[174:177], v[232:235], v[76:79]
	s_setprio 1
	s_setprio 0
	v_mfma_f32_16x16x32_bf16 v[120:123], v[178:181], v[194:197], v[120:123]
	v_mfma_f32_16x16x32_bf16 v[116:119], v[186:189], v[194:197], v[116:119]
	v_mfma_f32_16x16x32_bf16 v[104:107], v[178:181], v[212:215], v[104:107]
	v_mfma_f32_16x16x32_bf16 v[100:103], v[186:189], v[212:215], v[100:103]
	v_mfma_f32_16x16x32_bf16 v[88:91], v[178:181], v[220:223], v[88:91]
	v_mfma_f32_16x16x32_bf16 v[84:87], v[186:189], v[220:223], v[84:87]
	v_mfma_f32_16x16x32_bf16 v[72:75], v[178:181], v[228:231], v[72:75]
	v_mfma_f32_16x16x32_bf16 v[68:71], v[186:189], v[228:231], v[68:71]
	v_mfma_f32_16x16x32_bf16 v[120:123], v[182:185], v[198:201], v[120:123]
	v_mfma_f32_16x16x32_bf16 v[116:119], v[190:193], v[198:201], v[116:119]
	v_mfma_f32_16x16x32_bf16 v[104:107], v[182:185], v[216:219], v[104:107]
	v_mfma_f32_16x16x32_bf16 v[100:103], v[190:193], v[216:219], v[100:103]
	v_mfma_f32_16x16x32_bf16 v[88:91], v[182:185], v[224:227], v[88:91]
	v_mfma_f32_16x16x32_bf16 v[84:87], v[190:193], v[224:227], v[84:87]
	v_mfma_f32_16x16x32_bf16 v[72:75], v[182:185], v[232:235], v[72:75]
	v_mfma_f32_16x16x32_bf16 v[68:71], v[190:193], v[232:235], v[68:71]
	s_setprio 1
	s_barrier
	s_add_i32 s82, s82, s62
	v_lshl_add_u64 v[154:155], s[40:41], 0, v[136:137]
	s_mov_b32 m0, s82
	ds_read_b128 v[194:197], v166 offset:16384
	ds_read_b128 v[198:201], v166 offset:17408
	ds_read_b128 v[212:215], v166 offset:18432
	ds_read_b128 v[216:219], v166 offset:19456
	ds_read_b128 v[220:223], v166 offset:20480
	ds_read_b128 v[224:227], v166 offset:21504
	ds_read_b128 v[228:231], v166 offset:22528
	ds_read_b128 v[232:235], v166 offset:23552
	s_cmp_lg_u32 s32, 0
	s_cbranch_scc1 .Lbt0_0
	global_load_lds_dwordx4 v[154:155], off

; #define PG8_STAGE(bufoff, gbase, voff) do { _Pragma("unroll") for (int _i = 0; _i < 2; ++_i) \
;         __builtin_amdgcn_global_load_lds((const unsigned*)((const char*)(gbase) + (voff)[_i]), (PG8_LAS unsigned*)(lds + (bufoff) + ldsw + _i * 8192), 16, 0, 0); } while (0)
; #define PG8_LDA(dst, b, h) do { _Pragma("unroll") for (int m = 0; m < 4; ++m) _Pragma("unroll") for (int k = 0; k < 2; ++k) dst[m][k] = *(const PG8_LAS bf16x8*)(lds + PG8_SA(b, h) + aoff + m * 2048 + k * 1024); } while (0)
; #define PG8_LDB(dst, b, h) do { _Pragma("unroll") for (int n = 0; n < 2; ++n) _Pragma("unroll") for (int k = 0; k < 2; ++k) dst[n][k] = *(const PG8_LAS bf16x8*)(lds + PG8_SB(b, h) + boff + n * 2048 + k * 1024); } while (0)
; #define PG8_MMA(ai, bj, At, Bt) do { __builtin_amdgcn_s_setprio(1); _Pragma("unroll") for (int m = 0; m < 4; ++m) _Pragma("unroll") for (int n = 0; n < 2; ++n) _Pragma("unroll") for (int k = 0; k < 2; ++k) \
;         acc[ai][bj][m][n] = __builtin_amdgcn_mfma_f32_16x16x32_bf16(Bt[n][k], At[m][k], acc[ai][bj][m][n], 0, 0, 0); __builtin_amdgcn_s_setprio(0); } while (0)
; template <class Epi, class Sched, bool ALIGN_EPI = false, bool SP2 = false>
; __device__ __forceinline__ void gemm_phase(PG8_LAS unsigned char* lds, const Gemm g, const Sched& S, const Epi& E, const int tid) {
;     ...
;             if constexpr (SP2) {
;             PG8_LDB(B0, 0, 0); PG8_LDB(B1, 0, 1); PG8_SCHED; PG8_LDA(At, 0, 0); PG8_STAGE(PG8_SA(1, 1), a1 + hstep, voffA);
;             PG8_WAIT_V(8); PG8_WAIT_L(0); PG8_BAR; PG8_MMA(0, 0, At, B0); PG8_MMA(0, 1, At, B1); PG8_BAR; PG8_SCHED;
;             PG8_LDA(At, 0, 1); PG8_STAGE(PG8_SB(0, 0), b2, voffB); PG8_STAGE(PG8_SB(0, 1), b2 + hstepB, voffB); PG8_STAGE(PG8_SA(0, 0), a2, voffA);
;             PG8_WAIT_V(8); PG8_WAIT_L(0); PG8_BAR; PG8_MMA(1, 0, At, B0); PG8_MMA(1, 1, At, B1); PG8_BAR; PG8_SCHED;
;             PG8_LDB(B0, 1, 0); PG8_LDB(B1, 1, 1); PG8_SCHED; PG8_LDA(At, 1, 0); PG8_STAGE(PG8_SA(0, 1), a2 + hstep, voffA);
;             PG8_WAIT_V(8); PG8_WAIT_L(0); PG8_BAR; PG8_MMA(0, 0, At, B0); PG8_MMA(0, 1, At, B1); PG8_BAR; PG8_SCHED;
;             PG8_LDA(At, 1, 1); PG8_STAGE(PG8_SB(1, 0), b3, voffB); PG8_STAGE(PG8_SB(1, 1), b3 + hstepB, voffB); PG8_STAGE(PG8_SA(1, 0), a3, voffA);
;             PG8_WAIT_V(8); PG8_WAIT_L(0); PG8_BAR; PG8_MMA(1, 0, At, B0); PG8_MMA(1, 1, At, B1); PG8_BAR; PG8_SCHED;
.Lbw0_2:
	s_waitcnt lgkmcnt(0)
	s_barrier
	s_setprio 0
	s_waitcnt lgkmcnt(0)
	v_mfma_f32_16x16x32_bf16 v[64:67], v[146:149], v[194:197], v[64:67]
	v_mfma_f32_16x16x32_bf16 v[60:63], v[170:173], v[194:197], v[60:63]
	v_mfma_f32_16x16x32_bf16 v[48:51], v[146:149], v[212:215], v[48:51]
	v_mfma_f32_16x16x32_bf16 v[44:47], v[170:173], v[212:215], v[44:47]
	v_mfma_f32_16x16x32_bf16 v[32:35], v[146:149], v[220:223], v[32:35]
	v_mfma_f32_16x16x32_bf16 v[28:31], v[170:173], v[220:223], v[28:31]
	v_mfma_f32_16x16x32_bf16 v[16:19], v[146:149], v[228:231], v[16:19]
	v_mfma_f32_16x16x32_bf16 v[12:15], v[170:173], v[228:231], v[12:15]
	v_mfma_f32_16x16x32_bf16 v[64:67], v[150:153], v[198:201], v[64:67]
	v_mfma_f32_16x16x32_bf16 v[60:63], v[174:177], v[198:201], v[60:63]
	v_mfma_f32_16x16x32_bf16 v[48:51], v[150:153], v[216:219], v[48:51]
	v_mfma_f32_16x16x32_bf16 v[44:47], v[174:177], v[216:219], v[44:47]
	v_mfma_f32_16x16x32_bf16 v[32:35], v[150:153], v[224:227], v[32:35]
	v_mfma_f32_16x16x32_bf16 v[28:31], v[174:177], v[224:227], v[28:31]
	v_mfma_f32_16x16x32_bf16 v[16:19], v[150:153], v[232:235], v[16:19]
	v_mfma_f32_16x16x32_bf16 v[12:15], v[174:177], v[232:235], v[12:15]
	s_setprio 1
	s_setprio 0
	v_mfma_f32_16x16x32_bf16 v[56:59], v[178:181], v[194:197], v[56:59]
	v_mfma_f32_16x16x32_bf16 v[52:55], v[186:189], v[194:197], v[52:55]
	v_mfma_f32_16x16x32_bf16 v[40:43], v[178:181], v[212:215], v[40:43]
	v_mfma_f32_16x16x32_bf16 v[36:39], v[186:189], v[212:215], v[36:39]
	v_mfma_f32_16x16x32_bf16 v[24:27], v[178:181], v[220:223], v[24:27]
	v_mfma_f32_16x16x32_bf16 v[20:23], v[186:189], v[220:223], v[20:23]
	v_mfma_f32_16x16x32_bf16 v[8:11], v[178:181], v[228:231], v[8:11]
	v_mfma_f32_16x16x32_bf16 v[4:7], v[186:189], v[228:231], v[4:7]
	v_mfma_f32_16x16x32_bf16 v[56:59], v[182:185], v[198:201], v[56:59]
	v_mfma_f32_16x16x32_bf16 v[52:55], v[190:193], v[198:201], v[52:55]
	v_mfma_f32_16x16x32_bf16 v[40:43], v[182:185], v[216:219], v[40:43]
	v_mfma_f32_16x16x32_bf16 v[36:39], v[190:193], v[216:219], v[36:39]
	v_mfma_f32_16x16x32_bf16 v[24:27], v[182:185], v[224:227], v[24:27]
	v_mfma_f32_16x16x32_bf16 v[20:23], v[190:193], v[224:227], v[20:23]
	v_mfma_f32_16x16x32_bf16 v[8:11], v[182:185], v[232:235], v[8:11]
	v_mfma_f32_16x16x32_bf16 v[4:7], v[190:193], v[232:235], v[4:7]
	s_setprio 1
	s_barrier
	s_add_i32 s82, 0, 0x18000
	v_add_u32_e32 v167, s82, v163
	s_add_i32 s83, 0, 0x1c000
	ds_read_b128 v[146:149], v167
	ds_read_b128 v[150:153], v167 offset:1024
	ds_read_b128 v[170:173], v167 offset:2048
	ds_read_b128 v[174:177], v167 offset:3072
	v_add_u32_e32 v167, s83, v163
	ds_read_b128 v[178:181], v167
	ds_read_b128 v[182:185], v167 offset:1024
	ds_read_b128 v[186:189], v167 offset:2048
	ds_read_b128 v[190:193], v167 offset:3072
	s_add_u32 s42, s42, 0x40000
	s_addc_u32 s43, s43, 0
	s_mov_b32 m0, s65
	v_lshl_add_u64 v[242:243], s[42:43], 0, v[134:135]
	ds_read_b128 v[194:197], v166 offset:32768
	ds_read_b128 v[198:201], v166 offset:33792
	ds_read_b128 v[212:215], v166 offset:34816
	ds_read_b128 v[216:219], v166 offset:35840
	ds_read_b128 v[220:223], v166 offset:36864
	ds_read_b128 v[224:227], v166 offset:37888
	ds_read_b128 v[228:231], v166 offset:38912
	ds_read_b128 v[232:235], v166 offset:39936
	s_cmp_lg_u32 s32, 0
	s_cbranch_scc1 .Lbt0_6
	global_load_lds_dwordx4 v[242:243], off

; #define PG8_STAGE(bufoff, gbase, voff) do { _Pragma("unroll") for (int _i = 0; _i < 2; ++_i) \
;         __builtin_amdgcn_global_load_lds((const unsigned*)((const char*)(gbase) + (voff)[_i]), (PG8_LAS unsigned*)(lds + (bufoff) + ldsw + _i * 8192), 16, 0, 0); } while (0)
; #define PG8_LDA(dst, b, h) do { _Pragma("unroll") for (int m = 0; m < 4; ++m) _Pragma("unroll") for (int k = 0; k < 2; ++k) dst[m][k] = *(const PG8_LAS bf16x8*)(lds + PG8_SA(b, h) + aoff + m * 2048 + k * 1024); } while (0)
; #define PG8_LDB(dst, b, h) do { _Pragma("unroll") for (int n = 0; n < 2; ++n) _Pragma("unroll") for (int k = 0; k < 2; ++k) dst[n][k] = *(const PG8_LAS bf16x8*)(lds + PG8_SB(b, h) + boff + n * 2048 + k * 1024); } while (0)
; #define PG8_MMA(ai, bj, At, Bt) do { __builtin_amdgcn_s_setprio(1); _Pragma("unroll") for (int m = 0; m < 4; ++m) _Pragma("unroll") for (int n = 0; n < 2; ++n) _Pragma("unroll") for (int k = 0; k < 2; ++k) \
;         acc[ai][bj][m][n] = __builtin_amdgcn_mfma_f32_16x16x32_bf16(Bt[n][k], At[m][k], acc[ai][bj][m][n], 0, 0, 0); __builtin_amdgcn_s_setprio(0); } while (0)
; template <class Epi, class Sched, bool ALIGN_EPI = false, bool SP2 = false>
; __device__ __forceinline__ void gemm_phase(PG8_LAS unsigned char* lds, const Gemm g, const Sched& S, const Epi& E, const int tid) {
;     ...
;             if constexpr (SP2) {
;             PG8_LDB(B0, 0, 0); PG8_LDB(B1, 0, 1); PG8_SCHED; PG8_LDA(At, 0, 0); PG8_STAGE(PG8_SA(1, 1), a1 + hstep, voffA);
;             PG8_WAIT_V(8); PG8_WAIT_L(0); PG8_BAR; PG8_MMA(0, 0, At, B0); PG8_MMA(0, 1, At, B1); PG8_BAR; PG8_SCHED;
;             PG8_LDA(At, 0, 1); PG8_STAGE(PG8_SB(0, 0), b2, voffB); PG8_STAGE(PG8_SB(0, 1), b2 + hstepB, voffB); PG8_STAGE(PG8_SA(0, 0), a2, voffA);
;             PG8_WAIT_V(8); PG8_WAIT_L(0); PG8_BAR; PG8_MMA(1, 0, At, B0); PG8_MMA(1, 1, At, B1); PG8_BAR; PG8_SCHED;
;             PG8_LDB(B0, 1, 0); PG8_LDB(B1, 1, 1); PG8_SCHED; PG8_LDA(At, 1, 0); PG8_STAGE(PG8_SA(0, 1), a2 + hstep, voffA);
;             PG8_WAIT_V(8); PG8_WAIT_L(0); PG8_BAR; PG8_MMA(0, 0, At, B0); PG8_MMA(0, 1, At, B1); PG8_BAR; PG8_SCHED;
;             PG8_LDA(At, 1, 1); PG8_STAGE(PG8_SB(1, 0), b3, voffB); PG8_STAGE(PG8_SB(1, 1), b3 + hstepB, voffB); PG8_STAGE(PG8_SA(1, 0), a3, voffA);
;             PG8_WAIT_V(8); PG8_WAIT_L(0); PG8_BAR; PG8_MMA(1, 0, At, B0); PG8_MMA(1, 1, At, B1); PG8_BAR; PG8_SCHED;
.Lbw0_0:
	s_waitcnt lgkmcnt(0)
	s_barrier
	s_setprio 0
	s_waitcnt lgkmcnt(0)
	v_mfma_f32_16x16x32_bf16 v[128:131], v[146:149], v[194:197], v[128:131]
	v_mfma_f32_16x16x32_bf16 v[124:127], v[170:173], v[194:197], v[124:127]
	v_mfma_f32_16x16x32_bf16 v[112:115], v[146:149], v[212:215], v[112:115]
	v_mfma_f32_16x16x32_bf16 v[108:111], v[170:173], v[212:215], v[108:111]
	v_mfma_f32_16x16x32_bf16 v[96:99], v[146:149], v[220:223], v[96:99]
	v_mfma_f32_16x16x32_bf16 v[92:95], v[170:173], v[220:223], v[92:95]
	v_mfma_f32_16x16x32_bf16 v[80:83], v[146:149], v[228:231], v[80:83]
	v_mfma_f32_16x16x32_bf16 v[76:79], v[170:173], v[228:231], v[76:79]
	v_mfma_f32_16x16x32_bf16 v[128:131], v[150:153], v[198:201], v[128:131]
	v_mfma_f32_16x16x32_bf16 v[124:127], v[174:177], v[198:201], v[124:127]
	v_mfma_f32_16x16x32_bf16 v[112:115], v[150:153], v[216:219], v[112:115]
	v_mfma_f32_16x16x32_bf16 v[108:111], v[174:177], v[216:219], v[108:111]
	v_mfma_f32_16x16x32_bf16 v[96:99], v[150:153], v[224:227], v[96:99]
	v_mfma_f32_16x16x32_bf16 v[92:95], v[174:177], v[224:227], v[92:95]
	v_mfma_f32_16x16x32_bf16 v[80:83], v[150:153], v[232:235], v[80:83]
	v_mfma_f32_16x16x32_bf16 v[76:79], v[174:177], v[232:235], v[76:79]
	s_setprio 1
	s_setprio 0
	v_mfma_f32_16x16x32_bf16 v[120:123], v[178:181], v[194:197], v[120:123]
	v_mfma_f32_16x16x32_bf16 v[116:119], v[186:189], v[194:197], v[116:119]
	v_mfma_f32_16x16x32_bf16 v[104:107], v[178:181], v[212:215], v[104:107]
	v_mfma_f32_16x16x32_bf16 v[100:103], v[186:189], v[212:215], v[100:103]
	v_mfma_f32_16x16x32_bf16 v[88:91], v[178:181], v[220:223], v[88:91]
	v_mfma_f32_16x16x32_bf16 v[84:87], v[186:189], v[220:223], v[84:87]
	v_mfma_f32_16x16x32_bf16 v[72:75], v[178:181], v[228:231], v[72:75]
	v_mfma_f32_16x16x32_bf16 v[68:71], v[186:189], v[228:231], v[68:71]
	v_mfma_f32_16x16x32_bf16 v[120:123], v[182:185], v[198:201], v[120:123]
	v_mfma_f32_16x16x32_bf16 v[116:119], v[190:193], v[198:201], v[116:119]
	v_mfma_f32_16x16x32_bf16 v[104:107], v[182:185], v[216:219], v[104:107]
	v_mfma_f32_16x16x32_bf16 v[100:103], v[190:193], v[216:219], v[100:103]
	v_mfma_f32_16x16x32_bf16 v[88:91], v[182:185], v[224:227], v[88:91]
	v_mfma_f32_16x16x32_bf16 v[84:87], v[190:193], v[224:227], v[84:87]
	v_mfma_f32_16x16x32_bf16 v[72:75], v[182:185], v[232:235], v[72:75]
	v_mfma_f32_16x16x32_bf16 v[68:71], v[190:193], v[232:235], v[68:71]
	s_setprio 1
	s_barrier
	s_add_i32 s42, s82, s62
	v_lshl_add_u64 v[154:155], v[154:155], 0, s[52:53]
	s_mov_b32 m0, s42
	ds_read_b128 v[194:197], v166 offset:49152
	ds_read_b128 v[198:201], v166 offset:50176
	ds_read_b128 v[212:215], v166 offset:51200
	ds_read_b128 v[216:219], v166 offset:52224
	ds_read_b128 v[220:223], v166 offset:53248
	ds_read_b128 v[224:227], v166 offset:54272
	ds_read_b128 v[228:231], v166 offset:55296
	ds_read_b128 v[232:235], v166 offset:56320
	s_cmp_lg_u32 s32, 0
	s_cbranch_scc1 .Lbt0_8
	global_load_lds_dwordx4 v[154:155], off

; #define PG8_STAGE(bufoff, gbase, voff) do { _Pragma("unroll") for (int _i = 0; _i < 2; ++_i) \
;         __builtin_amdgcn_global_load_lds((const unsigned*)((const char*)(gbase) + (voff)[_i]), (PG8_LAS unsigned*)(lds + (bufoff) + ldsw + _i * 8192), 16, 0, 0); } while (0)
; #define PG8_LDA(dst, b, h) do { _Pragma("unroll") for (int m = 0; m < 4; ++m) _Pragma("unroll") for (int k = 0; k < 2; ++k) dst[m][k] = *(const PG8_LAS bf16x8*)(lds + PG8_SA(b, h) + aoff + m * 2048 + k * 1024); } while (0)
; #define PG8_WAIT_V(n) asm volatile("s_waitcnt vmcnt(" #n ")" ::: "memory")
; #define PG8_WAIT_L(n) asm volatile("s_waitcnt lgkmcnt(" #n ")" ::: "memory")
; template <class Epi, class Sched, bool ALIGN_EPI = false, bool SP2 = false>
; __device__ __forceinline__ void gemm_phase(PG8_LAS unsigned char* lds, const Gemm g, const Sched& S, const Epi& E, const int tid) {
;     ...
;         for (int t = 0; t < nt; t += 2) {
;             const bool last = (t == nt - 2);
;             const char* a1 = cA + (size_t)(t + 1) * kstep;
;             const char* a2 = last ? nA : cA + (size_t)(t + 2) * kstep; const char* b2 = last ? nB : cB + (size_t)(t + 2) * kstep;
;             const char* a3 = a2 + kstep; const char* b3 = b2 + kstep;
;             if (last && has_next) S.a_ready(nxt);
;             if constexpr (SP2) {
;             PG8_LDB(B0, 0, 0); PG8_LDB(B1, 0, 1); PG8_SCHED; PG8_LDA(At, 0, 0); PG8_STAGE(PG8_SA(1, 1), a1 + hstep, voffA);
;             PG8_WAIT_V(8); PG8_WAIT_L(0); PG8_BAR; PG8_MMA(0, 0, At, B0); PG8_MMA(0, 1, At, B1); PG8_BAR; PG8_SCHED;
;             PG8_LDA(At, 0, 1); PG8_STAGE(PG8_SB(0, 0), b2, voffB); PG8_STAGE(PG8_SB(0, 1), b2 + hstepB, voffB); PG8_STAGE(PG8_SA(0, 0), a2, voffA);
;             PG8_WAIT_V(8); PG8_WAIT_L(0); PG8_BAR; PG8_MMA(1, 0, At, B0); PG8_MMA(1, 1, At, B1); PG8_BAR; PG8_SCHED;
;             PG8_LDB(B0, 1, 0); PG8_LDB(B1, 1, 1); PG8_SCHED; PG8_LDA(At, 1, 0); PG8_STAGE(PG8_SA(0, 1), a2 + hstep, voffA);
;             PG8_WAIT_V(8); PG8_WAIT_L(0); PG8_BAR; PG8_MMA(0, 0, At, B0); PG8_MMA(0, 1, At, B1); PG8_BAR; PG8_SCHED;
;             PG8_LDA(At, 1, 1); PG8_STAGE(PG8_SB(1, 0), b3, voffB); PG8_STAGE(PG8_SB(1, 1), b3 + hstepB, voffB); PG8_STAGE(PG8_SA(1, 0), a3, voffA);
;             PG8_WAIT_V(8); PG8_WAIT_L(0); PG8_BAR; PG8_MMA(1, 0, At, B0); PG8_MMA(1, 1, At, B1); PG8_BAR; PG8_SCHED;
;     ...
;         if constexpr (ALIGN_EPI) { if (wr == 0) PG8_BAR; }
.Lbt0_13:
	s_waitcnt vmcnt(8)
	s_waitcnt lgkmcnt(0)
	s_barrier
	s_setprio 0
	s_waitcnt lgkmcnt(0)
	v_mfma_f32_16x16x32_bf16 v[64:67], v[146:149], v[194:197], v[64:67]
	v_mfma_f32_16x16x32_bf16 v[60:63], v[170:173], v[194:197], v[60:63]
	v_mfma_f32_16x16x32_bf16 v[48:51], v[146:149], v[212:215], v[48:51]
	v_mfma_f32_16x16x32_bf16 v[44:47], v[170:173], v[212:215], v[44:47]
	v_mfma_f32_16x16x32_bf16 v[32:35], v[146:149], v[220:223], v[32:35]
	v_mfma_f32_16x16x32_bf16 v[28:31], v[170:173], v[220:223], v[28:31]
	v_mfma_f32_16x16x32_bf16 v[16:19], v[146:149], v[228:231], v[16:19]
	v_mfma_f32_16x16x32_bf16 v[12:15], v[170:173], v[228:231], v[12:15]
	v_mfma_f32_16x16x32_bf16 v[64:67], v[150:153], v[198:201], v[64:67]
	v_mfma_f32_16x16x32_bf16 v[60:63], v[174:177], v[198:201], v[60:63]
	v_mfma_f32_16x16x32_bf16 v[48:51], v[150:153], v[216:219], v[48:51]
	v_mfma_f32_16x16x32_bf16 v[44:47], v[174:177], v[216:219], v[44:47]
	v_mfma_f32_16x16x32_bf16 v[32:35], v[150:153], v[224:227], v[32:35]
	v_mfma_f32_16x16x32_bf16 v[28:31], v[174:177], v[224:227], v[28:31]
	v_mfma_f32_16x16x32_bf16 v[16:19], v[150:153], v[232:235], v[16:19]
	v_mfma_f32_16x16x32_bf16 v[12:15], v[174:177], v[232:235], v[12:15]
	s_setprio 1
	s_setprio 0
	v_mfma_f32_16x16x32_bf16 v[56:59], v[178:181], v[194:197], v[56:59]
	v_mfma_f32_16x16x32_bf16 v[52:55], v[186:189], v[194:197], v[52:55]
	v_mfma_f32_16x16x32_bf16 v[40:43], v[178:181], v[212:215], v[40:43]
	v_mfma_f32_16x16x32_bf16 v[36:39], v[186:189], v[212:215], v[36:39]
	v_mfma_f32_16x16x32_bf16 v[24:27], v[178:181], v[220:223], v[24:27]
	v_mfma_f32_16x16x32_bf16 v[20:23], v[186:189], v[220:223], v[20:23]
	v_mfma_f32_16x16x32_bf16 v[8:11], v[178:181], v[228:231], v[8:11]
	v_mfma_f32_16x16x32_bf16 v[4:7], v[186:189], v[228:231], v[4:7]
	v_mfma_f32_16x16x32_bf16 v[56:59], v[182:185], v[198:201], v[56:59]
	v_mfma_f32_16x16x32_bf16 v[52:55], v[190:193], v[198:201], v[52:55]
	v_mfma_f32_16x16x32_bf16 v[40:43], v[182:185], v[216:219], v[40:43]
	v_mfma_f32_16x16x32_bf16 v[36:39], v[190:193], v[216:219], v[36:39]
	v_mfma_f32_16x16x32_bf16 v[24:27], v[182:185], v[224:227], v[24:27]
	v_mfma_f32_16x16x32_bf16 v[20:23], v[190:193], v[224:227], v[20:23]
	v_mfma_f32_16x16x32_bf16 v[8:11], v[182:185], v[232:235], v[8:11]
	v_mfma_f32_16x16x32_bf16 v[4:7], v[190:193], v[232:235], v[4:7]
	s_setprio 1
	s_barrier
	s_add_i32 s67, s67, 2
	s_add_u32 s38, s38, 0x100
	s_addc_u32 s39, s39, 0
	s_add_u32 s37, s37, 0x100
	s_addc_u32 s66, s66, 0
	s_cmp_gt_u32 s67, 13
	s_cbranch_scc0 .LBB0_185
	s_and_b64 vcc, exec, s[18:19]
	s_cbranch_vccz .LBB0_188
	s_barrier

;     DI bool next(int i, Unit& u) const { const int L = i * 32 + rank; if (L >= ppg * nN) return false; u.pm = ppg * grp + (L % ppg); const int p0 = L / ppg, p1 = p0 + rot; u.pn = rev ? nN - 1 - p0 : (p1 >= nN ? p1 - nN : p1); return true; }
; #define PG8_LDA(dst, b, h) do { _Pragma("unroll") for (int m = 0; m < 4; ++m) _Pragma("unroll") for (int k = 0; k < 2; ++k) dst[m][k] = *(const PG8_LAS bf16x8*)(lds + PG8_SA(b, h) + aoff + m * 2048 + k * 1024); } while (0)
; template <class Epi, class Sched, bool ALIGN_EPI = false, bool SP2 = false>
; __device__ __forceinline__ void gemm_phase(PG8_LAS unsigned char* lds, const Gemm g, const Sched& S, const Epi& E, const int tid) {
;     ...
;         const bool has_next = S.next(ui + 1, nxt);
;         const char* nA = has_next ? (const char*)g.A + (size_t)nxt.pm * tstep : cA; const char* nB = has_next ? (const char*)g.Bt + (size_t)nxt.pn * tstep : cB;
;         for (int t = 0; t < nt; t += 2) {
;             const bool last = (t == nt - 2);
;             const char* a1 = cA + (size_t)(t + 1) * kstep;
;             const char* a2 = last ? nA : cA + (size_t)(t + 2) * kstep; const char* b2 = last ? nB : cB + (size_t)(t + 2) * kstep;
;             const char* a3 = a2 + kstep; const char* b3 = b2 + kstep;
;             if (last && has_next) S.a_ready(nxt);
;             if constexpr (SP2) {
;             PG8_LDB(B0, 0, 0); PG8_LDB(B1, 0, 1); PG8_SCHED; PG8_LDA(At, 0, 0); PG8_STAGE(PG8_SA(1, 1), a1 + hstep, voffA);
;             PG8_WAIT_V(8); PG8_WAIT_L(0); PG8_BAR; PG8_MMA(0, 0, At, B0); PG8_MMA(0, 1, At, B1); PG8_BAR; PG8_SCHED;
;             PG8_LDA(At, 0, 1); PG8_STAGE(PG8_SB(0, 0), b2, voffB); PG8_STAGE(PG8_SB(0, 1), b2 + hstepB, voffB); PG8_STAGE(PG8_SA(0, 0), a2, voffA);
;             PG8_WAIT_V(8); PG8_WAIT_L(0); PG8_BAR; PG8_MMA(1, 0, At, B0); PG8_MMA(1, 1, At, B1); PG8_BAR; PG8_SCHED;
;             PG8_LDB(B0, 1, 0); PG8_LDB(B1, 1, 1); PG8_SCHED; PG8_LDA(At, 1, 0); PG8_STAGE(PG8_SA(0, 1), a2 + hstep, voffA);
;             PG8_WAIT_V(8); PG8_WAIT_L(0); PG8_BAR; PG8_MMA(0, 0, At, B0); PG8_MMA(0, 1, At, B1); PG8_BAR; PG8_SCHED;
;             PG8_LDA(At, 1, 1); PG8_STAGE(PG8_SB(1, 0), b3, voffB); PG8_STAGE(PG8_SB(1, 1), b3 + hstepB, voffB); PG8_STAGE(PG8_SA(1, 0), a3, voffA);
;             PG8_WAIT_V(8); PG8_WAIT_L(0); PG8_BAR; PG8_MMA(1, 0, At, B0); PG8_MMA(1, 1, At, B1); PG8_BAR; PG8_SCHED;
.LBB0_616:
	s_add_u32 s12, s10, 0xfffc0080
	s_addc_u32 s13, s11, -1
	s_add_i32 s79, 0, 0x10000
	s_cmp_eq_u32 s67, 12
	s_cselect_b32 s41, s3, s13
	s_cselect_b32 s40, s7, s12
	s_cselect_b32 s13, s9, s66
	s_cselect_b32 s12, s42, s43
	s_cmp_eq_u32 s67, 12
	s_cselect_b32 s32, 1, 0
	s_andn2_b32 s32, s32, s82
	s_add_i32 s88, 0, 0x14000
	v_add_u32_e32 v160, s79, v174
	v_add_u32_e32 v186, s88, v174
	ds_read_b128 v[148:151], v160
	ds_read_b128 v[152:155], v160 offset:1024
	ds_read_b128 v[156:159], v160 offset:2048
	ds_read_b128 v[160:163], v160 offset:3072
	ds_read_b128 v[164:167], v186
	ds_read_b128 v[178:181], v186 offset:1024
	ds_read_b128 v[182:185], v186 offset:2048
	ds_read_b128 v[186:189], v186 offset:3072
	v_lshl_add_u64 v[232:233], s[10:11], 0, v[144:145]
	s_add_i32 m0, s64, 0xc000
	ds_read_b128 v[190:193], v177
	ds_read_b128 v[194:197], v177 offset:1024
	ds_read_b128 v[198:201], v177 offset:2048
	ds_read_b128 v[212:215], v177 offset:3072
	ds_read_b128 v[216:219], v177 offset:4096
	ds_read_b128 v[220:223], v177 offset:5120
	ds_read_b128 v[224:227], v177 offset:6144
	ds_read_b128 v[228:231], v177 offset:7168
	global_load_lds_dwordx4 v[232:233], off
	v_lshl_add_u64 v[232:233], s[10:11], 0, v[146:147]
	s_add_i32 m0, s64, 0xe000
	s_nop 0
	global_load_lds_dwordx4 v[232:233], off
	s_waitcnt vmcnt(8)
	s_waitcnt lgkmcnt(0)
	s_barrier
	s_setprio 0
	s_waitcnt lgkmcnt(0)
	v_mfma_f32_16x16x32_bf16 v[128:131], v[148:151], v[190:193], v[128:131]
	v_mfma_f32_16x16x32_bf16 v[124:127], v[156:159], v[190:193], v[124:127]
	v_mfma_f32_16x16x32_bf16 v[112:115], v[148:151], v[198:201], v[112:115]
	v_mfma_f32_16x16x32_bf16 v[108:111], v[156:159], v[198:201], v[108:111]
	v_mfma_f32_16x16x32_bf16 v[96:99], v[148:151], v[216:219], v[96:99]
	v_mfma_f32_16x16x32_bf16 v[92:95], v[156:159], v[216:219], v[92:95]
	v_mfma_f32_16x16x32_bf16 v[80:83], v[148:151], v[224:227], v[80:83]
	v_mfma_f32_16x16x32_bf16 v[76:79], v[156:159], v[224:227], v[76:79]
	v_mfma_f32_16x16x32_bf16 v[128:131], v[152:155], v[194:197], v[128:131]
	v_mfma_f32_16x16x32_bf16 v[124:127], v[160:163], v[194:197], v[124:127]
	v_mfma_f32_16x16x32_bf16 v[112:115], v[152:155], v[212:215], v[112:115]
	v_mfma_f32_16x16x32_bf16 v[108:111], v[160:163], v[212:215], v[108:111]
	v_mfma_f32_16x16x32_bf16 v[96:99], v[152:155], v[220:223], v[96:99]
	v_mfma_f32_16x16x32_bf16 v[92:95], v[160:163], v[220:223], v[92:95]
	v_mfma_f32_16x16x32_bf16 v[80:83], v[152:155], v[228:231], v[80:83]
	v_mfma_f32_16x16x32_bf16 v[76:79], v[160:163], v[228:231], v[76:79]
	s_setprio 1
	s_setprio 0
	v_mfma_f32_16x16x32_bf16 v[120:123], v[164:167], v[190:193], v[120:123]
	v_mfma_f32_16x16x32_bf16 v[116:119], v[182:185], v[190:193], v[116:119]
	v_mfma_f32_16x16x32_bf16 v[104:107], v[164:167], v[198:201], v[104:107]
	v_mfma_f32_16x16x32_bf16 v[100:103], v[182:185], v[198:201], v[100:103]
	v_mfma_f32_16x16x32_bf16 v[88:91], v[164:167], v[216:219], v[88:91]
	v_mfma_f32_16x16x32_bf16 v[84:87], v[182:185], v[216:219], v[84:87]
	v_mfma_f32_16x16x32_bf16 v[72:75], v[164:167], v[224:227], v[72:75]
	v_mfma_f32_16x16x32_bf16 v[68:71], v[182:185], v[224:227], v[68:71]
	v_mfma_f32_16x16x32_bf16 v[120:123], v[178:181], v[194:197], v[120:123]
	v_mfma_f32_16x16x32_bf16 v[116:119], v[186:189], v[194:197], v[116:119]
	v_mfma_f32_16x16x32_bf16 v[104:107], v[178:181], v[212:215], v[104:107]
	v_mfma_f32_16x16x32_bf16 v[100:103], v[186:189], v[212:215], v[100:103]
	v_mfma_f32_16x16x32_bf16 v[88:91], v[178:181], v[220:223], v[88:91]
	v_mfma_f32_16x16x32_bf16 v[84:87], v[186:189], v[220:223], v[84:87]
	v_mfma_f32_16x16x32_bf16 v[72:75], v[178:181], v[228:231], v[72:75]
	v_mfma_f32_16x16x32_bf16 v[68:71], v[186:189], v[228:231], v[68:71]
	s_setprio 1
	s_barrier
	s_add_i32 s79, s79, s63
	v_lshl_add_u64 v[232:233], s[12:13], 0, v[136:137]
	s_mov_b32 m0, s79
	ds_read_b128 v[190:193], v177 offset:16384
	ds_read_b128 v[194:197], v177 offset:17408
	ds_read_b128 v[198:201], v177 offset:18432
	ds_read_b128 v[212:215], v177 offset:19456
	ds_read_b128 v[216:219], v177 offset:20480
	ds_read_b128 v[220:223], v177 offset:21504
	ds_read_b128 v[224:227], v177 offset:22528
	ds_read_b128 v[228:231], v177 offset:23552
	s_cmp_lg_u32 s32, 0
	s_cbranch_scc1 .Lbt1_0
	global_load_lds_dwordx4 v[232:233], off

; #define PG8_STAGE(bufoff, gbase, voff) do { _Pragma("unroll") for (int _i = 0; _i < 2; ++_i) \
;         __builtin_amdgcn_global_load_lds((const unsigned*)((const char*)(gbase) + (voff)[_i]), (PG8_LAS unsigned*)(lds + (bufoff) + ldsw + _i * 8192), 16, 0, 0); } while (0)
; #define PG8_LDA(dst, b, h) do { _Pragma("unroll") for (int m = 0; m < 4; ++m) _Pragma("unroll") for (int k = 0; k < 2; ++k) dst[m][k] = *(const PG8_LAS bf16x8*)(lds + PG8_SA(b, h) + aoff + m * 2048 + k * 1024); } while (0)
; #define PG8_LDB(dst, b, h) do { _Pragma("unroll") for (int n = 0; n < 2; ++n) _Pragma("unroll") for (int k = 0; k < 2; ++k) dst[n][k] = *(const PG8_LAS bf16x8*)(lds + PG8_SB(b, h) + boff + n * 2048 + k * 1024); } while (0)
; #define PG8_MMA(ai, bj, At, Bt) do { __builtin_amdgcn_s_setprio(1); _Pragma("unroll") for (int m = 0; m < 4; ++m) _Pragma("unroll") for (int n = 0; n < 2; ++n) _Pragma("unroll") for (int k = 0; k < 2; ++k) \
;         acc[ai][bj][m][n] = __builtin_amdgcn_mfma_f32_16x16x32_bf16(Bt[n][k], At[m][k], acc[ai][bj][m][n], 0, 0, 0); __builtin_amdgcn_s_setprio(0); } while (0)
; template <class Epi, class Sched, bool ALIGN_EPI = false, bool SP2 = false>
; __device__ __forceinline__ void gemm_phase(PG8_LAS unsigned char* lds, const Gemm g, const Sched& S, const Epi& E, const int tid) {
;     ...
;             if constexpr (SP2) {
;             PG8_LDB(B0, 0, 0); PG8_LDB(B1, 0, 1); PG8_SCHED; PG8_LDA(At, 0, 0); PG8_STAGE(PG8_SA(1, 1), a1 + hstep, voffA);
;             PG8_WAIT_V(8); PG8_WAIT_L(0); PG8_BAR; PG8_MMA(0, 0, At, B0); PG8_MMA(0, 1, At, B1); PG8_BAR; PG8_SCHED;
;             PG8_LDA(At, 0, 1); PG8_STAGE(PG8_SB(0, 0), b2, voffB); PG8_STAGE(PG8_SB(0, 1), b2 + hstepB, voffB); PG8_STAGE(PG8_SA(0, 0), a2, voffA);
;             PG8_WAIT_V(8); PG8_WAIT_L(0); PG8_BAR; PG8_MMA(1, 0, At, B0); PG8_MMA(1, 1, At, B1); PG8_BAR; PG8_SCHED;
;             PG8_LDB(B0, 1, 0); PG8_LDB(B1, 1, 1); PG8_SCHED; PG8_LDA(At, 1, 0); PG8_STAGE(PG8_SA(0, 1), a2 + hstep, voffA);
;             PG8_WAIT_V(8); PG8_WAIT_L(0); PG8_BAR; PG8_MMA(0, 0, At, B0); PG8_MMA(0, 1, At, B1); PG8_BAR; PG8_SCHED;
;             PG8_LDA(At, 1, 1); PG8_STAGE(PG8_SB(1, 0), b3, voffB); PG8_STAGE(PG8_SB(1, 1), b3 + hstepB, voffB); PG8_STAGE(PG8_SA(1, 0), a3, voffA);
;             PG8_WAIT_V(8); PG8_WAIT_L(0); PG8_BAR; PG8_MMA(1, 0, At, B0); PG8_MMA(1, 1, At, B1); PG8_BAR; PG8_SCHED;
.Lbw1_2:
	s_waitcnt lgkmcnt(0)
	s_barrier
	s_setprio 0
	s_waitcnt lgkmcnt(0)
	v_mfma_f32_16x16x32_bf16 v[64:67], v[148:151], v[190:193], v[64:67]
	v_mfma_f32_16x16x32_bf16 v[60:63], v[156:159], v[190:193], v[60:63]
	v_mfma_f32_16x16x32_bf16 v[48:51], v[148:151], v[198:201], v[48:51]
	v_mfma_f32_16x16x32_bf16 v[44:47], v[156:159], v[198:201], v[44:47]
	v_mfma_f32_16x16x32_bf16 v[32:35], v[148:151], v[216:219], v[32:35]
	v_mfma_f32_16x16x32_bf16 v[28:31], v[156:159], v[216:219], v[28:31]
	v_mfma_f32_16x16x32_bf16 v[16:19], v[148:151], v[224:227], v[16:19]
	v_mfma_f32_16x16x32_bf16 v[12:15], v[156:159], v[224:227], v[12:15]
	v_mfma_f32_16x16x32_bf16 v[64:67], v[152:155], v[194:197], v[64:67]
	v_mfma_f32_16x16x32_bf16 v[60:63], v[160:163], v[194:197], v[60:63]
	v_mfma_f32_16x16x32_bf16 v[48:51], v[152:155], v[212:215], v[48:51]
	v_mfma_f32_16x16x32_bf16 v[44:47], v[160:163], v[212:215], v[44:47]
	v_mfma_f32_16x16x32_bf16 v[32:35], v[152:155], v[220:223], v[32:35]
	v_mfma_f32_16x16x32_bf16 v[28:31], v[160:163], v[220:223], v[28:31]
	v_mfma_f32_16x16x32_bf16 v[16:19], v[152:155], v[228:231], v[16:19]
	v_mfma_f32_16x16x32_bf16 v[12:15], v[160:163], v[228:231], v[12:15]
	s_setprio 1
	s_setprio 0
	v_mfma_f32_16x16x32_bf16 v[56:59], v[164:167], v[190:193], v[56:59]
	v_mfma_f32_16x16x32_bf16 v[52:55], v[182:185], v[190:193], v[52:55]
	v_mfma_f32_16x16x32_bf16 v[40:43], v[164:167], v[198:201], v[40:43]
	v_mfma_f32_16x16x32_bf16 v[36:39], v[182:185], v[198:201], v[36:39]
	v_mfma_f32_16x16x32_bf16 v[24:27], v[164:167], v[216:219], v[24:27]
	v_mfma_f32_16x16x32_bf16 v[20:23], v[182:185], v[216:219], v[20:23]
	v_mfma_f32_16x16x32_bf16 v[8:11], v[164:167], v[224:227], v[8:11]
	v_mfma_f32_16x16x32_bf16 v[4:7], v[182:185], v[224:227], v[4:7]
	v_mfma_f32_16x16x32_bf16 v[56:59], v[178:181], v[194:197], v[56:59]
	v_mfma_f32_16x16x32_bf16 v[52:55], v[186:189], v[194:197], v[52:55]
	v_mfma_f32_16x16x32_bf16 v[40:43], v[178:181], v[212:215], v[40:43]
	v_mfma_f32_16x16x32_bf16 v[36:39], v[186:189], v[212:215], v[36:39]
	v_mfma_f32_16x16x32_bf16 v[24:27], v[178:181], v[220:223], v[24:27]
	v_mfma_f32_16x16x32_bf16 v[20:23], v[186:189], v[220:223], v[20:23]
	v_mfma_f32_16x16x32_bf16 v[8:11], v[178:181], v[228:231], v[8:11]
	v_mfma_f32_16x16x32_bf16 v[4:7], v[186:189], v[228:231], v[4:7]
	s_setprio 1
	s_barrier
	s_add_i32 s79, 0, 0x18000
	s_add_i32 s88, 0, 0x1c000
	v_add_u32_e32 v160, s79, v174
	v_add_u32_e32 v186, s88, v174
	ds_read_b128 v[148:151], v160
	ds_read_b128 v[152:155], v160 offset:1024
	ds_read_b128 v[156:159], v160 offset:2048
	ds_read_b128 v[160:163], v160 offset:3072
	ds_read_b128 v[164:167], v186
	ds_read_b128 v[178:181], v186 offset:1024
	ds_read_b128 v[182:185], v186 offset:2048
	ds_read_b128 v[186:189], v186 offset:3072
	s_add_u32 s40, s40, 0x40000
	s_addc_u32 s41, s41, 0
	s_mov_b32 m0, s86
	v_lshl_add_u64 v[240:241], s[40:41], 0, v[134:135]
	ds_read_b128 v[190:193], v177 offset:32768
	ds_read_b128 v[194:197], v177 offset:33792
	ds_read_b128 v[198:201], v177 offset:34816
	ds_read_b128 v[212:215], v177 offset:35840
	ds_read_b128 v[216:219], v177 offset:36864
	ds_read_b128 v[220:223], v177 offset:37888
	ds_read_b128 v[224:227], v177 offset:38912
	ds_read_b128 v[228:231], v177 offset:39936
	s_cmp_lg_u32 s32, 0
	s_cbranch_scc1 .Lbt1_6
	global_load_lds_dwordx4 v[240:241], off

; #define PG8_STAGE(bufoff, gbase, voff) do { _Pragma("unroll") for (int _i = 0; _i < 2; ++_i) \
;         __builtin_amdgcn_global_load_lds((const unsigned*)((const char*)(gbase) + (voff)[_i]), (PG8_LAS unsigned*)(lds + (bufoff) + ldsw + _i * 8192), 16, 0, 0); } while (0)
; #define PG8_LDA(dst, b, h) do { _Pragma("unroll") for (int m = 0; m < 4; ++m) _Pragma("unroll") for (int k = 0; k < 2; ++k) dst[m][k] = *(const PG8_LAS bf16x8*)(lds + PG8_SA(b, h) + aoff + m * 2048 + k * 1024); } while (0)
; #define PG8_LDB(dst, b, h) do { _Pragma("unroll") for (int n = 0; n < 2; ++n) _Pragma("unroll") for (int k = 0; k < 2; ++k) dst[n][k] = *(const PG8_LAS bf16x8*)(lds + PG8_SB(b, h) + boff + n * 2048 + k * 1024); } while (0)
; #define PG8_MMA(ai, bj, At, Bt) do { __builtin_amdgcn_s_setprio(1); _Pragma("unroll") for (int m = 0; m < 4; ++m) _Pragma("unroll") for (int n = 0; n < 2; ++n) _Pragma("unroll") for (int k = 0; k < 2; ++k) \
;         acc[ai][bj][m][n] = __builtin_amdgcn_mfma_f32_16x16x32_bf16(Bt[n][k], At[m][k], acc[ai][bj][m][n], 0, 0, 0); __builtin_amdgcn_s_setprio(0); } while (0)
; template <class Epi, class Sched, bool ALIGN_EPI = false, bool SP2 = false>
; __device__ __forceinline__ void gemm_phase(PG8_LAS unsigned char* lds, const Gemm g, const Sched& S, const Epi& E, const int tid) {
;     ...
;             if constexpr (SP2) {
;             PG8_LDB(B0, 0, 0); PG8_LDB(B1, 0, 1); PG8_SCHED; PG8_LDA(At, 0, 0); PG8_STAGE(PG8_SA(1, 1), a1 + hstep, voffA);
;             PG8_WAIT_V(8); PG8_WAIT_L(0); PG8_BAR; PG8_MMA(0, 0, At, B0); PG8_MMA(0, 1, At, B1); PG8_BAR; PG8_SCHED;
;             PG8_LDA(At, 0, 1); PG8_STAGE(PG8_SB(0, 0), b2, voffB); PG8_STAGE(PG8_SB(0, 1), b2 + hstepB, voffB); PG8_STAGE(PG8_SA(0, 0), a2, voffA);
;             PG8_WAIT_V(8); PG8_WAIT_L(0); PG8_BAR; PG8_MMA(1, 0, At, B0); PG8_MMA(1, 1, At, B1); PG8_BAR; PG8_SCHED;
;             PG8_LDB(B0, 1, 0); PG8_LDB(B1, 1, 1); PG8_SCHED; PG8_LDA(At, 1, 0); PG8_STAGE(PG8_SA(0, 1), a2 + hstep, voffA);
;             PG8_WAIT_V(8); PG8_WAIT_L(0); PG8_BAR; PG8_MMA(0, 0, At, B0); PG8_MMA(0, 1, At, B1); PG8_BAR; PG8_SCHED;
;             PG8_LDA(At, 1, 1); PG8_STAGE(PG8_SB(1, 0), b3, voffB); PG8_STAGE(PG8_SB(1, 1), b3 + hstepB, voffB); PG8_STAGE(PG8_SA(1, 0), a3, voffA);
;             PG8_WAIT_V(8); PG8_WAIT_L(0); PG8_BAR; PG8_MMA(1, 0, At, B0); PG8_MMA(1, 1, At, B1); PG8_BAR; PG8_SCHED;
.Lbw1_0:
	s_waitcnt lgkmcnt(0)
	s_barrier
	s_setprio 0
	s_waitcnt lgkmcnt(0)
	v_mfma_f32_16x16x32_bf16 v[128:131], v[148:151], v[190:193], v[128:131]
	v_mfma_f32_16x16x32_bf16 v[124:127], v[156:159], v[190:193], v[124:127]
	v_mfma_f32_16x16x32_bf16 v[112:115], v[148:151], v[198:201], v[112:115]
	v_mfma_f32_16x16x32_bf16 v[108:111], v[156:159], v[198:201], v[108:111]
	v_mfma_f32_16x16x32_bf16 v[96:99], v[148:151], v[216:219], v[96:99]
	v_mfma_f32_16x16x32_bf16 v[92:95], v[156:159], v[216:219], v[92:95]
	v_mfma_f32_16x16x32_bf16 v[80:83], v[148:151], v[224:227], v[80:83]
	v_mfma_f32_16x16x32_bf16 v[76:79], v[156:159], v[224:227], v[76:79]
	v_mfma_f32_16x16x32_bf16 v[128:131], v[152:155], v[194:197], v[128:131]
	v_mfma_f32_16x16x32_bf16 v[124:127], v[160:163], v[194:197], v[124:127]
	v_mfma_f32_16x16x32_bf16 v[112:115], v[152:155], v[212:215], v[112:115]
	v_mfma_f32_16x16x32_bf16 v[108:111], v[160:163], v[212:215], v[108:111]
	v_mfma_f32_16x16x32_bf16 v[96:99], v[152:155], v[220:223], v[96:99]
	v_mfma_f32_16x16x32_bf16 v[92:95], v[160:163], v[220:223], v[92:95]
	v_mfma_f32_16x16x32_bf16 v[80:83], v[152:155], v[228:231], v[80:83]
	v_mfma_f32_16x16x32_bf16 v[76:79], v[160:163], v[228:231], v[76:79]
	s_setprio 1
	s_setprio 0
	v_mfma_f32_16x16x32_bf16 v[120:123], v[164:167], v[190:193], v[120:123]
	v_mfma_f32_16x16x32_bf16 v[116:119], v[182:185], v[190:193], v[116:119]
	v_mfma_f32_16x16x32_bf16 v[104:107], v[164:167], v[198:201], v[104:107]
	v_mfma_f32_16x16x32_bf16 v[100:103], v[182:185], v[198:201], v[100:103]
	v_mfma_f32_16x16x32_bf16 v[88:91], v[164:167], v[216:219], v[88:91]
	v_mfma_f32_16x16x32_bf16 v[84:87], v[182:185], v[216:219], v[84:87]
	v_mfma_f32_16x16x32_bf16 v[72:75], v[164:167], v[224:227], v[72:75]
	v_mfma_f32_16x16x32_bf16 v[68:71], v[182:185], v[224:227], v[68:71]
	v_mfma_f32_16x16x32_bf16 v[120:123], v[178:181], v[194:197], v[120:123]
	v_mfma_f32_16x16x32_bf16 v[116:119], v[186:189], v[194:197], v[116:119]
	v_mfma_f32_16x16x32_bf16 v[104:107], v[178:181], v[212:215], v[104:107]
	v_mfma_f32_16x16x32_bf16 v[100:103], v[186:189], v[212:215], v[100:103]
	v_mfma_f32_16x16x32_bf16 v[88:91], v[178:181], v[220:223], v[88:91]
	v_mfma_f32_16x16x32_bf16 v[84:87], v[186:189], v[220:223], v[84:87]
	v_mfma_f32_16x16x32_bf16 v[72:75], v[178:181], v[228:231], v[72:75]
	v_mfma_f32_16x16x32_bf16 v[68:71], v[186:189], v[228:231], v[68:71]
	s_setprio 1
	s_barrier
	s_add_i32 s40, s79, s63
	v_lshl_add_u64 v[232:233], v[232:233], 0, s[52:53]
	s_mov_b32 m0, s40
	ds_read_b128 v[190:193], v177 offset:49152
	ds_read_b128 v[194:197], v177 offset:50176
	ds_read_b128 v[198:201], v177 offset:51200
	ds_read_b128 v[212:215], v177 offset:52224
	ds_read_b128 v[216:219], v177 offset:53248
	ds_read_b128 v[220:223], v177 offset:54272
	ds_read_b128 v[224:227], v177 offset:55296
	ds_read_b128 v[228:231], v177 offset:56320
	s_cmp_lg_u32 s32, 0
	s_cbranch_scc1 .Lbt1_8
	global_load_lds_dwordx4 v[232:233], off

; #define PG8_STAGE(bufoff, gbase, voff) do { _Pragma("unroll") for (int _i = 0; _i < 2; ++_i) \
;         __builtin_amdgcn_global_load_lds((const unsigned*)((const char*)(gbase) + (voff)[_i]), (PG8_LAS unsigned*)(lds + (bufoff) + ldsw + _i * 8192), 16, 0, 0); } while (0)
; #define PG8_LDA(dst, b, h) do { _Pragma("unroll") for (int m = 0; m < 4; ++m) _Pragma("unroll") for (int k = 0; k < 2; ++k) dst[m][k] = *(const PG8_LAS bf16x8*)(lds + PG8_SA(b, h) + aoff + m * 2048 + k * 1024); } while (0)
; #define PG8_WAIT_V(n) asm volatile("s_waitcnt vmcnt(" #n ")" ::: "memory")
; #define PG8_WAIT_L(n) asm volatile("s_waitcnt lgkmcnt(" #n ")" ::: "memory")
; template <class Epi, class Sched, bool ALIGN_EPI = false, bool SP2 = false>
; __device__ __forceinline__ void gemm_phase(PG8_LAS unsigned char* lds, const Gemm g, const Sched& S, const Epi& E, const int tid) {
;     ...
;         for (int t = 0; t < nt; t += 2) {
;             const bool last = (t == nt - 2);
;             const char* a1 = cA + (size_t)(t + 1) * kstep;
;             const char* a2 = last ? nA : cA + (size_t)(t + 2) * kstep; const char* b2 = last ? nB : cB + (size_t)(t + 2) * kstep;
;             const char* a3 = a2 + kstep; const char* b3 = b2 + kstep;
;             if (last && has_next) S.a_ready(nxt);
;             if constexpr (SP2) {
;             PG8_LDB(B0, 0, 0); PG8_LDB(B1, 0, 1); PG8_SCHED; PG8_LDA(At, 0, 0); PG8_STAGE(PG8_SA(1, 1), a1 + hstep, voffA);
;             PG8_WAIT_V(8); PG8_WAIT_L(0); PG8_BAR; PG8_MMA(0, 0, At, B0); PG8_MMA(0, 1, At, B1); PG8_BAR; PG8_SCHED;
;             PG8_LDA(At, 0, 1); PG8_STAGE(PG8_SB(0, 0), b2, voffB); PG8_STAGE(PG8_SB(0, 1), b2 + hstepB, voffB); PG8_STAGE(PG8_SA(0, 0), a2, voffA);
;             PG8_WAIT_V(8); PG8_WAIT_L(0); PG8_BAR; PG8_MMA(1, 0, At, B0); PG8_MMA(1, 1, At, B1); PG8_BAR; PG8_SCHED;
;             PG8_LDB(B0, 1, 0); PG8_LDB(B1, 1, 1); PG8_SCHED; PG8_LDA(At, 1, 0); PG8_STAGE(PG8_SA(0, 1), a2 + hstep, voffA);
;             PG8_WAIT_V(8); PG8_WAIT_L(0); PG8_BAR; PG8_MMA(0, 0, At, B0); PG8_MMA(0, 1, At, B1); PG8_BAR; PG8_SCHED;
;             PG8_LDA(At, 1, 1); PG8_STAGE(PG8_SB(1, 0), b3, voffB); PG8_STAGE(PG8_SB(1, 1), b3 + hstepB, voffB); PG8_STAGE(PG8_SA(1, 0), a3, voffA);
;             PG8_WAIT_V(8); PG8_WAIT_L(0); PG8_BAR; PG8_MMA(1, 0, At, B0); PG8_MMA(1, 1, At, B1); PG8_BAR; PG8_SCHED;
;     ...
;         if constexpr (ALIGN_EPI) { if (wr == 0) PG8_BAR; }
.Lbt1_13:
	s_waitcnt vmcnt(8)
	s_waitcnt lgkmcnt(0)
	s_barrier
	s_setprio 0
	s_waitcnt lgkmcnt(0)
	v_mfma_f32_16x16x32_bf16 v[64:67], v[148:151], v[190:193], v[64:67]
	v_mfma_f32_16x16x32_bf16 v[60:63], v[156:159], v[190:193], v[60:63]
	v_mfma_f32_16x16x32_bf16 v[48:51], v[148:151], v[198:201], v[48:51]
	v_mfma_f32_16x16x32_bf16 v[44:47], v[156:159], v[198:201], v[44:47]
	v_mfma_f32_16x16x32_bf16 v[32:35], v[148:151], v[216:219], v[32:35]
	v_mfma_f32_16x16x32_bf16 v[28:31], v[156:159], v[216:219], v[28:31]
	v_mfma_f32_16x16x32_bf16 v[16:19], v[148:151], v[224:227], v[16:19]
	v_mfma_f32_16x16x32_bf16 v[12:15], v[156:159], v[224:227], v[12:15]
	v_mfma_f32_16x16x32_bf16 v[64:67], v[152:155], v[194:197], v[64:67]
	v_mfma_f32_16x16x32_bf16 v[60:63], v[160:163], v[194:197], v[60:63]
	v_mfma_f32_16x16x32_bf16 v[48:51], v[152:155], v[212:215], v[48:51]
	v_mfma_f32_16x16x32_bf16 v[44:47], v[160:163], v[212:215], v[44:47]
	v_mfma_f32_16x16x32_bf16 v[32:35], v[152:155], v[220:223], v[32:35]
	v_mfma_f32_16x16x32_bf16 v[28:31], v[160:163], v[220:223], v[28:31]
	v_mfma_f32_16x16x32_bf16 v[16:19], v[152:155], v[228:231], v[16:19]
	v_mfma_f32_16x16x32_bf16 v[12:15], v[160:163], v[228:231], v[12:15]
	s_setprio 1
	s_setprio 0
	v_mfma_f32_16x16x32_bf16 v[56:59], v[164:167], v[190:193], v[56:59]
	v_mfma_f32_16x16x32_bf16 v[52:55], v[182:185], v[190:193], v[52:55]
	v_mfma_f32_16x16x32_bf16 v[40:43], v[164:167], v[198:201], v[40:43]
	v_mfma_f32_16x16x32_bf16 v[36:39], v[182:185], v[198:201], v[36:39]
	v_mfma_f32_16x16x32_bf16 v[24:27], v[164:167], v[216:219], v[24:27]
	v_mfma_f32_16x16x32_bf16 v[20:23], v[182:185], v[216:219], v[20:23]
	v_mfma_f32_16x16x32_bf16 v[8:11], v[164:167], v[224:227], v[8:11]
	v_mfma_f32_16x16x32_bf16 v[4:7], v[182:185], v[224:227], v[4:7]
	v_mfma_f32_16x16x32_bf16 v[56:59], v[178:181], v[194:197], v[56:59]
	v_mfma_f32_16x16x32_bf16 v[52:55], v[186:189], v[194:197], v[52:55]
	v_mfma_f32_16x16x32_bf16 v[40:43], v[178:181], v[212:215], v[40:43]
	v_mfma_f32_16x16x32_bf16 v[36:39], v[186:189], v[212:215], v[36:39]
	v_mfma_f32_16x16x32_bf16 v[24:27], v[178:181], v[220:223], v[24:27]
	v_mfma_f32_16x16x32_bf16 v[20:23], v[186:189], v[220:223], v[20:23]
	v_mfma_f32_16x16x32_bf16 v[8:11], v[178:181], v[228:231], v[8:11]
	v_mfma_f32_16x16x32_bf16 v[4:7], v[186:189], v[228:231], v[4:7]
	s_setprio 1
	s_barrier
	s_add_i32 s67, s67, 2
	s_add_u32 s10, s10, 0x100
	s_addc_u32 s11, s11, 0
	s_add_u32 s43, s43, 0x100
	s_addc_u32 s66, s66, 0
	s_cmp_gt_u32 s67, 13
	s_cbranch_scc0 .LBB0_616
	s_and_b64 vcc, exec, s[36:37]
	s_cbranch_vccz .LBB0_619
	s_barrier

;     DI bool next(int i, Unit& u) const { const int L = i * 32 + rank; if (L >= ppg * nN) return false; u.pm = ppg * grp + (L % ppg); const int p0 = L / ppg, p1 = p0 + rot; u.pn = rev ? nN - 1 - p0 : (p1 >= nN ? p1 - nN : p1); return true; }
; #define PG8_LDA(dst, b, h) do { _Pragma("unroll") for (int m = 0; m < 4; ++m) _Pragma("unroll") for (int k = 0; k < 2; ++k) dst[m][k] = *(const PG8_LAS bf16x8*)(lds + PG8_SA(b, h) + aoff + m * 2048 + k * 1024); } while (0)
; template <class Epi, class Sched, bool ALIGN_EPI = false, bool SP2 = false>
; __device__ __forceinline__ void gemm_phase(PG8_LAS unsigned char* lds, const Gemm g, const Sched& S, const Epi& E, const int tid) {
;     ...
;         const bool has_next = S.next(ui + 1, nxt);
;         const char* nA = has_next ? (const char*)g.A + (size_t)nxt.pm * tstep : cA; const char* nB = has_next ? (const char*)g.Bt + (size_t)nxt.pn * tstep : cB;
;         for (int t = 0; t < nt; t += 2) {
;             const bool last = (t == nt - 2);
;             const char* a1 = cA + (size_t)(t + 1) * kstep;
;             const char* a2 = last ? nA : cA + (size_t)(t + 2) * kstep; const char* b2 = last ? nB : cB + (size_t)(t + 2) * kstep;
;             const char* a3 = a2 + kstep; const char* b3 = b2 + kstep;
;             if (last && has_next) S.a_ready(nxt);
;             if constexpr (SP2) {
;             PG8_LDB(B0, 0, 0); PG8_LDB(B1, 0, 1); PG8_SCHED; PG8_LDA(At, 0, 0); PG8_STAGE(PG8_SA(1, 1), a1 + hstep, voffA);
;             PG8_WAIT_V(8); PG8_WAIT_L(0); PG8_BAR; PG8_MMA(0, 0, At, B0); PG8_MMA(0, 1, At, B1); PG8_BAR; PG8_SCHED;
;             PG8_LDA(At, 0, 1); PG8_STAGE(PG8_SB(0, 0), b2, voffB); PG8_STAGE(PG8_SB(0, 1), b2 + hstepB, voffB); PG8_STAGE(PG8_SA(0, 0), a2, voffA);
;             PG8_WAIT_V(8); PG8_WAIT_L(0); PG8_BAR; PG8_MMA(1, 0, At, B0); PG8_MMA(1, 1, At, B1); PG8_BAR; PG8_SCHED;
;             PG8_LDB(B0, 1, 0); PG8_LDB(B1, 1, 1); PG8_SCHED; PG8_LDA(At, 1, 0); PG8_STAGE(PG8_SA(0, 1), a2 + hstep, voffA);
;             PG8_WAIT_V(8); PG8_WAIT_L(0); PG8_BAR; PG8_MMA(0, 0, At, B0); PG8_MMA(0, 1, At, B1); PG8_BAR; PG8_SCHED;
;             PG8_LDA(At, 1, 1); PG8_STAGE(PG8_SB(1, 0), b3, voffB); PG8_STAGE(PG8_SB(1, 1), b3 + hstepB, voffB); PG8_STAGE(PG8_SA(1, 0), a3, voffA);
;             PG8_WAIT_V(8); PG8_WAIT_L(0); PG8_BAR; PG8_MMA(1, 0, At, B0); PG8_MMA(1, 1, At, B1); PG8_BAR; PG8_SCHED;
.LBB0_979:
	s_add_u32 s36, s38, 0xfffc0080
	s_addc_u32 s37, s39, -1
	s_add_i32 s81, 0, 0x10000
	s_cmp_eq_u32 s80, 12
	s_cselect_b32 s41, s19, s37
	s_cselect_b32 s40, s25, s36
	v_add_u32_e32 v150, s81, v158
	s_cselect_b32 s37, s17, s79
	s_cselect_b32 s36, s76, s78
	s_cmp_eq_u32 s80, 12
	s_cselect_b32 s32, 1, 0
	s_andn2_b32 s32, s32, s30
	s_add_i32 s84, 0, 0x14000
	ds_read_b128 v[146:149], v150
	ds_read_b128 v[162:165], v150 offset:1024
	ds_read_b128 v[170:173], v150 offset:2048
	ds_read_b128 v[174:177], v150 offset:3072
	v_add_u32_e32 v150, s84, v158
	ds_read_b128 v[178:181], v150
	ds_read_b128 v[182:185], v150 offset:1024
	ds_read_b128 v[186:189], v150 offset:2048
	ds_read_b128 v[190:193], v150 offset:3072
	v_lshl_add_u64 v[150:151], s[38:39], 0, v[142:143]
	s_add_i32 m0, s29, 0xc000
	ds_read_b128 v[194:197], v160
	ds_read_b128 v[198:201], v160 offset:1024
	ds_read_b128 v[212:215], v160 offset:2048
	ds_read_b128 v[216:219], v160 offset:3072
	ds_read_b128 v[220:223], v160 offset:4096
	ds_read_b128 v[224:227], v160 offset:5120
	ds_read_b128 v[228:231], v160 offset:6144
	ds_read_b128 v[232:235], v160 offset:7168
	global_load_lds_dwordx4 v[150:151], off
	v_lshl_add_u64 v[150:151], s[38:39], 0, v[144:145]
	s_add_i32 m0, s29, 0xe000
	s_nop 0
	global_load_lds_dwordx4 v[150:151], off
	s_waitcnt vmcnt(8)
	s_waitcnt lgkmcnt(0)
	s_barrier
	s_setprio 0
	s_waitcnt lgkmcnt(0)
	v_mfma_f32_16x16x32_bf16 v[120:123], v[146:149], v[194:197], v[120:123]
	v_mfma_f32_16x16x32_bf16 v[128:131], v[170:173], v[194:197], v[128:131]
	v_mfma_f32_16x16x32_bf16 v[100:103], v[146:149], v[212:215], v[100:103]
	v_mfma_f32_16x16x32_bf16 v[108:111], v[170:173], v[212:215], v[108:111]
	v_mfma_f32_16x16x32_bf16 v[84:87], v[146:149], v[220:223], v[84:87]
	v_mfma_f32_16x16x32_bf16 v[92:95], v[170:173], v[220:223], v[92:95]
	v_mfma_f32_16x16x32_bf16 v[68:71], v[146:149], v[228:231], v[68:71]
	v_mfma_f32_16x16x32_bf16 v[76:79], v[170:173], v[228:231], v[76:79]
	v_mfma_f32_16x16x32_bf16 v[120:123], v[162:165], v[198:201], v[120:123]
	v_mfma_f32_16x16x32_bf16 v[128:131], v[174:177], v[198:201], v[128:131]
	v_mfma_f32_16x16x32_bf16 v[100:103], v[162:165], v[216:219], v[100:103]
	v_mfma_f32_16x16x32_bf16 v[108:111], v[174:177], v[216:219], v[108:111]
	v_mfma_f32_16x16x32_bf16 v[84:87], v[162:165], v[224:227], v[84:87]
	v_mfma_f32_16x16x32_bf16 v[92:95], v[174:177], v[224:227], v[92:95]
	v_mfma_f32_16x16x32_bf16 v[68:71], v[162:165], v[232:235], v[68:71]
	v_mfma_f32_16x16x32_bf16 v[76:79], v[174:177], v[232:235], v[76:79]
	s_setprio 1
	s_setprio 0
	v_mfma_f32_16x16x32_bf16 v[116:119], v[178:181], v[194:197], v[116:119]
	v_mfma_f32_16x16x32_bf16 v[124:127], v[186:189], v[194:197], v[124:127]
	v_mfma_f32_16x16x32_bf16 v[104:107], v[178:181], v[212:215], v[104:107]
	v_mfma_f32_16x16x32_bf16 v[112:115], v[186:189], v[212:215], v[112:115]
	v_mfma_f32_16x16x32_bf16 v[88:91], v[178:181], v[220:223], v[88:91]
	v_mfma_f32_16x16x32_bf16 v[96:99], v[186:189], v[220:223], v[96:99]
	v_mfma_f32_16x16x32_bf16 v[72:75], v[178:181], v[228:231], v[72:75]
	v_mfma_f32_16x16x32_bf16 v[80:83], v[186:189], v[228:231], v[80:83]
	v_mfma_f32_16x16x32_bf16 v[116:119], v[182:185], v[198:201], v[116:119]
	v_mfma_f32_16x16x32_bf16 v[124:127], v[190:193], v[198:201], v[124:127]
	v_mfma_f32_16x16x32_bf16 v[104:107], v[182:185], v[216:219], v[104:107]
	v_mfma_f32_16x16x32_bf16 v[112:115], v[190:193], v[216:219], v[112:115]
	v_mfma_f32_16x16x32_bf16 v[88:91], v[182:185], v[224:227], v[88:91]
	v_mfma_f32_16x16x32_bf16 v[96:99], v[190:193], v[224:227], v[96:99]
	v_mfma_f32_16x16x32_bf16 v[72:75], v[182:185], v[232:235], v[72:75]
	v_mfma_f32_16x16x32_bf16 v[80:83], v[190:193], v[232:235], v[80:83]
	s_setprio 1
	s_barrier
	s_add_i32 s81, s81, s43
	v_lshl_add_u64 v[150:151], s[36:37], 0, v[136:137]
	s_mov_b32 m0, s81
	ds_read_b128 v[194:197], v160 offset:16384
	ds_read_b128 v[198:201], v160 offset:17408
	ds_read_b128 v[212:215], v160 offset:18432
	ds_read_b128 v[216:219], v160 offset:19456
	ds_read_b128 v[220:223], v160 offset:20480
	ds_read_b128 v[224:227], v160 offset:21504
	ds_read_b128 v[228:231], v160 offset:22528
	ds_read_b128 v[232:235], v160 offset:23552
	s_cmp_lg_u32 s32, 0
	s_cbranch_scc1 .Lbt2_0
	global_load_lds_dwordx4 v[150:151], off

; #define PG8_STAGE(bufoff, gbase, voff) do { _Pragma("unroll") for (int _i = 0; _i < 2; ++_i) \
;         __builtin_amdgcn_global_load_lds((const unsigned*)((const char*)(gbase) + (voff)[_i]), (PG8_LAS unsigned*)(lds + (bufoff) + ldsw + _i * 8192), 16, 0, 0); } while (0)
; #define PG8_LDA(dst, b, h) do { _Pragma("unroll") for (int m = 0; m < 4; ++m) _Pragma("unroll") for (int k = 0; k < 2; ++k) dst[m][k] = *(const PG8_LAS bf16x8*)(lds + PG8_SA(b, h) + aoff + m * 2048 + k * 1024); } while (0)
; #define PG8_LDB(dst, b, h) do { _Pragma("unroll") for (int n = 0; n < 2; ++n) _Pragma("unroll") for (int k = 0; k < 2; ++k) dst[n][k] = *(const PG8_LAS bf16x8*)(lds + PG8_SB(b, h) + boff + n * 2048 + k * 1024); } while (0)
; #define PG8_MMA(ai, bj, At, Bt) do { __builtin_amdgcn_s_setprio(1); _Pragma("unroll") for (int m = 0; m < 4; ++m) _Pragma("unroll") for (int n = 0; n < 2; ++n) _Pragma("unroll") for (int k = 0; k < 2; ++k) \
;         acc[ai][bj][m][n] = __builtin_amdgcn_mfma_f32_16x16x32_bf16(Bt[n][k], At[m][k], acc[ai][bj][m][n], 0, 0, 0); __builtin_amdgcn_s_setprio(0); } while (0)
; template <class Epi, class Sched, bool ALIGN_EPI = false, bool SP2 = false>
; __device__ __forceinline__ void gemm_phase(PG8_LAS unsigned char* lds, const Gemm g, const Sched& S, const Epi& E, const int tid) {
;     ...
;             if constexpr (SP2) {
;             PG8_LDB(B0, 0, 0); PG8_LDB(B1, 0, 1); PG8_SCHED; PG8_LDA(At, 0, 0); PG8_STAGE(PG8_SA(1, 1), a1 + hstep, voffA);
;             PG8_WAIT_V(8); PG8_WAIT_L(0); PG8_BAR; PG8_MMA(0, 0, At, B0); PG8_MMA(0, 1, At, B1); PG8_BAR; PG8_SCHED;
;             PG8_LDA(At, 0, 1); PG8_STAGE(PG8_SB(0, 0), b2, voffB); PG8_STAGE(PG8_SB(0, 1), b2 + hstepB, voffB); PG8_STAGE(PG8_SA(0, 0), a2, voffA);
;             PG8_WAIT_V(8); PG8_WAIT_L(0); PG8_BAR; PG8_MMA(1, 0, At, B0); PG8_MMA(1, 1, At, B1); PG8_BAR; PG8_SCHED;
;             PG8_LDB(B0, 1, 0); PG8_LDB(B1, 1, 1); PG8_SCHED; PG8_LDA(At, 1, 0); PG8_STAGE(PG8_SA(0, 1), a2 + hstep, voffA);
;             PG8_WAIT_V(8); PG8_WAIT_L(0); PG8_BAR; PG8_MMA(0, 0, At, B0); PG8_MMA(0, 1, At, B1); PG8_BAR; PG8_SCHED;
;             PG8_LDA(At, 1, 1); PG8_STAGE(PG8_SB(1, 0), b3, voffB); PG8_STAGE(PG8_SB(1, 1), b3 + hstepB, voffB); PG8_STAGE(PG8_SA(1, 0), a3, voffA);
;             PG8_WAIT_V(8); PG8_WAIT_L(0); PG8_BAR; PG8_MMA(1, 0, At, B0); PG8_MMA(1, 1, At, B1); PG8_BAR; PG8_SCHED;
.Lbw2_2:
	s_waitcnt lgkmcnt(0)
	s_barrier
	s_setprio 0
	s_waitcnt lgkmcnt(0)
	v_mfma_f32_16x16x32_bf16 v[52:55], v[146:149], v[194:197], v[52:55]
	v_mfma_f32_16x16x32_bf16 v[60:63], v[170:173], v[194:197], v[60:63]
	v_mfma_f32_16x16x32_bf16 v[36:39], v[146:149], v[212:215], v[36:39]
	v_mfma_f32_16x16x32_bf16 v[44:47], v[170:173], v[212:215], v[44:47]
	v_mfma_f32_16x16x32_bf16 v[20:23], v[146:149], v[220:223], v[20:23]
	v_mfma_f32_16x16x32_bf16 v[28:31], v[170:173], v[220:223], v[28:31]
	v_mfma_f32_16x16x32_bf16 v[4:7], v[146:149], v[228:231], v[4:7]
	v_mfma_f32_16x16x32_bf16 v[12:15], v[170:173], v[228:231], v[12:15]
	v_mfma_f32_16x16x32_bf16 v[52:55], v[162:165], v[198:201], v[52:55]
	v_mfma_f32_16x16x32_bf16 v[60:63], v[174:177], v[198:201], v[60:63]
	v_mfma_f32_16x16x32_bf16 v[36:39], v[162:165], v[216:219], v[36:39]
	v_mfma_f32_16x16x32_bf16 v[44:47], v[174:177], v[216:219], v[44:47]
	v_mfma_f32_16x16x32_bf16 v[20:23], v[162:165], v[224:227], v[20:23]
	v_mfma_f32_16x16x32_bf16 v[28:31], v[174:177], v[224:227], v[28:31]
	v_mfma_f32_16x16x32_bf16 v[4:7], v[162:165], v[232:235], v[4:7]
	v_mfma_f32_16x16x32_bf16 v[12:15], v[174:177], v[232:235], v[12:15]
	s_setprio 1
	s_setprio 0
	v_mfma_f32_16x16x32_bf16 v[56:59], v[178:181], v[194:197], v[56:59]
	v_mfma_f32_16x16x32_bf16 v[64:67], v[186:189], v[194:197], v[64:67]
	v_mfma_f32_16x16x32_bf16 v[40:43], v[178:181], v[212:215], v[40:43]
	v_mfma_f32_16x16x32_bf16 v[48:51], v[186:189], v[212:215], v[48:51]
	v_mfma_f32_16x16x32_bf16 v[24:27], v[178:181], v[220:223], v[24:27]
	v_mfma_f32_16x16x32_bf16 v[32:35], v[186:189], v[220:223], v[32:35]
	v_mfma_f32_16x16x32_bf16 v[8:11], v[178:181], v[228:231], v[8:11]
	v_mfma_f32_16x16x32_bf16 v[16:19], v[186:189], v[228:231], v[16:19]
	v_mfma_f32_16x16x32_bf16 v[56:59], v[182:185], v[198:201], v[56:59]
	v_mfma_f32_16x16x32_bf16 v[64:67], v[190:193], v[198:201], v[64:67]
	v_mfma_f32_16x16x32_bf16 v[40:43], v[182:185], v[216:219], v[40:43]
	v_mfma_f32_16x16x32_bf16 v[48:51], v[190:193], v[216:219], v[48:51]
	v_mfma_f32_16x16x32_bf16 v[24:27], v[182:185], v[224:227], v[24:27]
	v_mfma_f32_16x16x32_bf16 v[32:35], v[190:193], v[224:227], v[32:35]
	v_mfma_f32_16x16x32_bf16 v[8:11], v[182:185], v[232:235], v[8:11]
	v_mfma_f32_16x16x32_bf16 v[16:19], v[190:193], v[232:235], v[16:19]
	s_setprio 1
	s_barrier
	s_add_i32 s81, 0, 0x18000
	v_add_u32_e32 v161, s81, v158
	s_add_i32 s82, 0, 0x1c000
	ds_read_b128 v[146:149], v161
	ds_read_b128 v[162:165], v161 offset:1024
	ds_read_b128 v[170:173], v161 offset:2048
	ds_read_b128 v[174:177], v161 offset:3072
	v_add_u32_e32 v161, s82, v158
	ds_read_b128 v[178:181], v161
	ds_read_b128 v[182:185], v161 offset:1024
	ds_read_b128 v[186:189], v161 offset:2048
	ds_read_b128 v[190:193], v161 offset:3072
	s_add_u32 s40, s40, 0x40000
	s_addc_u32 s41, s41, 0
	s_mov_b32 m0, s62
	v_lshl_add_u64 v[240:241], s[40:41], 0, v[134:135]
	ds_read_b128 v[194:197], v160 offset:32768
	ds_read_b128 v[198:201], v160 offset:33792
	ds_read_b128 v[212:215], v160 offset:34816
	ds_read_b128 v[216:219], v160 offset:35840
	ds_read_b128 v[220:223], v160 offset:36864
	ds_read_b128 v[224:227], v160 offset:37888
	ds_read_b128 v[228:231], v160 offset:38912
	ds_read_b128 v[232:235], v160 offset:39936
	s_cmp_lg_u32 s32, 0
	s_cbranch_scc1 .Lbt2_6
	global_load_lds_dwordx4 v[240:241], off

; #define PG8_STAGE(bufoff, gbase, voff) do { _Pragma("unroll") for (int _i = 0; _i < 2; ++_i) \
;         __builtin_amdgcn_global_load_lds((const unsigned*)((const char*)(gbase) + (voff)[_i]), (PG8_LAS unsigned*)(lds + (bufoff) + ldsw + _i * 8192), 16, 0, 0); } while (0)
; #define PG8_LDA(dst, b, h) do { _Pragma("unroll") for (int m = 0; m < 4; ++m) _Pragma("unroll") for (int k = 0; k < 2; ++k) dst[m][k] = *(const PG8_LAS bf16x8*)(lds + PG8_SA(b, h) + aoff + m * 2048 + k * 1024); } while (0)
; #define PG8_LDB(dst, b, h) do { _Pragma("unroll") for (int n = 0; n < 2; ++n) _Pragma("unroll") for (int k = 0; k < 2; ++k) dst[n][k] = *(const PG8_LAS bf16x8*)(lds + PG8_SB(b, h) + boff + n * 2048 + k * 1024); } while (0)
; #define PG8_MMA(ai, bj, At, Bt) do { __builtin_amdgcn_s_setprio(1); _Pragma("unroll") for (int m = 0; m < 4; ++m) _Pragma("unroll") for (int n = 0; n < 2; ++n) _Pragma("unroll") for (int k = 0; k < 2; ++k) \
;         acc[ai][bj][m][n] = __builtin_amdgcn_mfma_f32_16x16x32_bf16(Bt[n][k], At[m][k], acc[ai][bj][m][n], 0, 0, 0); __builtin_amdgcn_s_setprio(0); } while (0)
; template <class Epi, class Sched, bool ALIGN_EPI = false, bool SP2 = false>
; __device__ __forceinline__ void gemm_phase(PG8_LAS unsigned char* lds, const Gemm g, const Sched& S, const Epi& E, const int tid) {
;     ...
;             if constexpr (SP2) {
;             PG8_LDB(B0, 0, 0); PG8_LDB(B1, 0, 1); PG8_SCHED; PG8_LDA(At, 0, 0); PG8_STAGE(PG8_SA(1, 1), a1 + hstep, voffA);
;             PG8_WAIT_V(8); PG8_WAIT_L(0); PG8_BAR; PG8_MMA(0, 0, At, B0); PG8_MMA(0, 1, At, B1); PG8_BAR; PG8_SCHED;
;             PG8_LDA(At, 0, 1); PG8_STAGE(PG8_SB(0, 0), b2, voffB); PG8_STAGE(PG8_SB(0, 1), b2 + hstepB, voffB); PG8_STAGE(PG8_SA(0, 0), a2, voffA);
;             PG8_WAIT_V(8); PG8_WAIT_L(0); PG8_BAR; PG8_MMA(1, 0, At, B0); PG8_MMA(1, 1, At, B1); PG8_BAR; PG8_SCHED;
;             PG8_LDB(B0, 1, 0); PG8_LDB(B1, 1, 1); PG8_SCHED; PG8_LDA(At, 1, 0); PG8_STAGE(PG8_SA(0, 1), a2 + hstep, voffA);
;             PG8_WAIT_V(8); PG8_WAIT_L(0); PG8_BAR; PG8_MMA(0, 0, At, B0); PG8_MMA(0, 1, At, B1); PG8_BAR; PG8_SCHED;
;             PG8_LDA(At, 1, 1); PG8_STAGE(PG8_SB(1, 0), b3, voffB); PG8_STAGE(PG8_SB(1, 1), b3 + hstepB, voffB); PG8_STAGE(PG8_SA(1, 0), a3, voffA);
;             PG8_WAIT_V(8); PG8_WAIT_L(0); PG8_BAR; PG8_MMA(1, 0, At, B0); PG8_MMA(1, 1, At, B1); PG8_BAR; PG8_SCHED;
.Lbw2_0:
	s_waitcnt lgkmcnt(0)
	s_barrier
	s_setprio 0
	s_waitcnt lgkmcnt(0)
	v_mfma_f32_16x16x32_bf16 v[120:123], v[146:149], v[194:197], v[120:123]
	v_mfma_f32_16x16x32_bf16 v[128:131], v[170:173], v[194:197], v[128:131]
	v_mfma_f32_16x16x32_bf16 v[100:103], v[146:149], v[212:215], v[100:103]
	v_mfma_f32_16x16x32_bf16 v[108:111], v[170:173], v[212:215], v[108:111]
	v_mfma_f32_16x16x32_bf16 v[84:87], v[146:149], v[220:223], v[84:87]
	v_mfma_f32_16x16x32_bf16 v[92:95], v[170:173], v[220:223], v[92:95]
	v_mfma_f32_16x16x32_bf16 v[68:71], v[146:149], v[228:231], v[68:71]
	v_mfma_f32_16x16x32_bf16 v[76:79], v[170:173], v[228:231], v[76:79]
	v_mfma_f32_16x16x32_bf16 v[120:123], v[162:165], v[198:201], v[120:123]
	v_mfma_f32_16x16x32_bf16 v[128:131], v[174:177], v[198:201], v[128:131]
	v_mfma_f32_16x16x32_bf16 v[100:103], v[162:165], v[216:219], v[100:103]
	v_mfma_f32_16x16x32_bf16 v[108:111], v[174:177], v[216:219], v[108:111]
	v_mfma_f32_16x16x32_bf16 v[84:87], v[162:165], v[224:227], v[84:87]
	v_mfma_f32_16x16x32_bf16 v[92:95], v[174:177], v[224:227], v[92:95]
	v_mfma_f32_16x16x32_bf16 v[68:71], v[162:165], v[232:235], v[68:71]
	v_mfma_f32_16x16x32_bf16 v[76:79], v[174:177], v[232:235], v[76:79]
	s_setprio 1
	s_setprio 0
	v_mfma_f32_16x16x32_bf16 v[116:119], v[178:181], v[194:197], v[116:119]
	v_mfma_f32_16x16x32_bf16 v[124:127], v[186:189], v[194:197], v[124:127]
	v_mfma_f32_16x16x32_bf16 v[104:107], v[178:181], v[212:215], v[104:107]
	v_mfma_f32_16x16x32_bf16 v[112:115], v[186:189], v[212:215], v[112:115]
	v_mfma_f32_16x16x32_bf16 v[88:91], v[178:181], v[220:223], v[88:91]
	v_mfma_f32_16x16x32_bf16 v[96:99], v[186:189], v[220:223], v[96:99]
	v_mfma_f32_16x16x32_bf16 v[72:75], v[178:181], v[228:231], v[72:75]
	v_mfma_f32_16x16x32_bf16 v[80:83], v[186:189], v[228:231], v[80:83]
	v_mfma_f32_16x16x32_bf16 v[116:119], v[182:185], v[198:201], v[116:119]
	v_mfma_f32_16x16x32_bf16 v[124:127], v[190:193], v[198:201], v[124:127]
	v_mfma_f32_16x16x32_bf16 v[104:107], v[182:185], v[216:219], v[104:107]
	v_mfma_f32_16x16x32_bf16 v[112:115], v[190:193], v[216:219], v[112:115]
	v_mfma_f32_16x16x32_bf16 v[88:91], v[182:185], v[224:227], v[88:91]
	v_mfma_f32_16x16x32_bf16 v[96:99], v[190:193], v[224:227], v[96:99]
	v_mfma_f32_16x16x32_bf16 v[72:75], v[182:185], v[232:235], v[72:75]
	v_mfma_f32_16x16x32_bf16 v[80:83], v[190:193], v[232:235], v[80:83]
	s_setprio 1
	s_barrier
	s_add_i32 s40, s81, s43
	v_lshl_add_u64 v[150:151], v[150:151], 0, s[52:53]
	s_mov_b32 m0, s40
	ds_read_b128 v[194:197], v160 offset:49152
	ds_read_b128 v[198:201], v160 offset:50176
	ds_read_b128 v[212:215], v160 offset:51200
	ds_read_b128 v[216:219], v160 offset:52224
	ds_read_b128 v[220:223], v160 offset:53248
	ds_read_b128 v[224:227], v160 offset:54272
	ds_read_b128 v[228:231], v160 offset:55296
	ds_read_b128 v[232:235], v160 offset:56320
	s_cmp_lg_u32 s32, 0
	s_cbranch_scc1 .Lbt2_8
	global_load_lds_dwordx4 v[150:151], off

; #define PG8_STAGE(bufoff, gbase, voff) do { _Pragma("unroll") for (int _i = 0; _i < 2; ++_i) \
;         __builtin_amdgcn_global_load_lds((const unsigned*)((const char*)(gbase) + (voff)[_i]), (PG8_LAS unsigned*)(lds + (bufoff) + ldsw + _i * 8192), 16, 0, 0); } while (0)
; #define PG8_LDA(dst, b, h) do { _Pragma("unroll") for (int m = 0; m < 4; ++m) _Pragma("unroll") for (int k = 0; k < 2; ++k) dst[m][k] = *(const PG8_LAS bf16x8*)(lds + PG8_SA(b, h) + aoff + m * 2048 + k * 1024); } while (0)
; #define PG8_WAIT_V(n) asm volatile("s_waitcnt vmcnt(" #n ")" ::: "memory")
; #define PG8_WAIT_L(n) asm volatile("s_waitcnt lgkmcnt(" #n ")" ::: "memory")
; template <class Epi, class Sched, bool ALIGN_EPI = false, bool SP2 = false>
; __device__ __forceinline__ void gemm_phase(PG8_LAS unsigned char* lds, const Gemm g, const Sched& S, const Epi& E, const int tid) {
;     ...
;         for (int t = 0; t < nt; t += 2) {
;             const bool last = (t == nt - 2);
;             const char* a1 = cA + (size_t)(t + 1) * kstep;
;             const char* a2 = last ? nA : cA + (size_t)(t + 2) * kstep; const char* b2 = last ? nB : cB + (size_t)(t + 2) * kstep;
;             const char* a3 = a2 + kstep; const char* b3 = b2 + kstep;
;             if (last && has_next) S.a_ready(nxt);
;             if constexpr (SP2) {
;             PG8_LDB(B0, 0, 0); PG8_LDB(B1, 0, 1); PG8_SCHED; PG8_LDA(At, 0, 0); PG8_STAGE(PG8_SA(1, 1), a1 + hstep, voffA);
;             PG8_WAIT_V(8); PG8_WAIT_L(0); PG8_BAR; PG8_MMA(0, 0, At, B0); PG8_MMA(0, 1, At, B1); PG8_BAR; PG8_SCHED;
;             PG8_LDA(At, 0, 1); PG8_STAGE(PG8_SB(0, 0), b2, voffB); PG8_STAGE(PG8_SB(0, 1), b2 + hstepB, voffB); PG8_STAGE(PG8_SA(0, 0), a2, voffA);
;             PG8_WAIT_V(8); PG8_WAIT_L(0); PG8_BAR; PG8_MMA(1, 0, At, B0); PG8_MMA(1, 1, At, B1); PG8_BAR; PG8_SCHED;
;             PG8_LDB(B0, 1, 0); PG8_LDB(B1, 1, 1); PG8_SCHED; PG8_LDA(At, 1, 0); PG8_STAGE(PG8_SA(0, 1), a2 + hstep, voffA);
;             PG8_WAIT_V(8); PG8_WAIT_L(0); PG8_BAR; PG8_MMA(0, 0, At, B0); PG8_MMA(0, 1, At, B1); PG8_BAR; PG8_SCHED;
;             PG8_LDA(At, 1, 1); PG8_STAGE(PG8_SB(1, 0), b3, voffB); PG8_STAGE(PG8_SB(1, 1), b3 + hstepB, voffB); PG8_STAGE(PG8_SA(1, 0), a3, voffA);
;             PG8_WAIT_V(8); PG8_WAIT_L(0); PG8_BAR; PG8_MMA(1, 0, At, B0); PG8_MMA(1, 1, At, B1); PG8_BAR; PG8_SCHED;
;     ...
;         if constexpr (ALIGN_EPI) { if (wr == 0) PG8_BAR; }
.Lbt2_13:
	s_waitcnt vmcnt(8)
	s_waitcnt lgkmcnt(0)
	s_barrier
	s_setprio 0
	s_waitcnt lgkmcnt(0)
	v_mfma_f32_16x16x32_bf16 v[52:55], v[146:149], v[194:197], v[52:55]
	v_mfma_f32_16x16x32_bf16 v[60:63], v[170:173], v[194:197], v[60:63]
	v_mfma_f32_16x16x32_bf16 v[36:39], v[146:149], v[212:215], v[36:39]
	v_mfma_f32_16x16x32_bf16 v[44:47], v[170:173], v[212:215], v[44:47]
	v_mfma_f32_16x16x32_bf16 v[20:23], v[146:149], v[220:223], v[20:23]
	v_mfma_f32_16x16x32_bf16 v[28:31], v[170:173], v[220:223], v[28:31]
	v_mfma_f32_16x16x32_bf16 v[4:7], v[146:149], v[228:231], v[4:7]
	v_mfma_f32_16x16x32_bf16 v[12:15], v[170:173], v[228:231], v[12:15]
	v_mfma_f32_16x16x32_bf16 v[52:55], v[162:165], v[198:201], v[52:55]
	v_mfma_f32_16x16x32_bf16 v[60:63], v[174:177], v[198:201], v[60:63]
	v_mfma_f32_16x16x32_bf16 v[36:39], v[162:165], v[216:219], v[36:39]
	v_mfma_f32_16x16x32_bf16 v[44:47], v[174:177], v[216:219], v[44:47]
	v_mfma_f32_16x16x32_bf16 v[20:23], v[162:165], v[224:227], v[20:23]
	v_mfma_f32_16x16x32_bf16 v[28:31], v[174:177], v[224:227], v[28:31]
	v_mfma_f32_16x16x32_bf16 v[4:7], v[162:165], v[232:235], v[4:7]
	v_mfma_f32_16x16x32_bf16 v[12:15], v[174:177], v[232:235], v[12:15]
	s_setprio 1
	s_setprio 0
	v_mfma_f32_16x16x32_bf16 v[56:59], v[178:181], v[194:197], v[56:59]
	v_mfma_f32_16x16x32_bf16 v[64:67], v[186:189], v[194:197], v[64:67]
	v_mfma_f32_16x16x32_bf16 v[40:43], v[178:181], v[212:215], v[40:43]
	v_mfma_f32_16x16x32_bf16 v[48:51], v[186:189], v[212:215], v[48:51]
	v_mfma_f32_16x16x32_bf16 v[24:27], v[178:181], v[220:223], v[24:27]
	v_mfma_f32_16x16x32_bf16 v[32:35], v[186:189], v[220:223], v[32:35]
	v_mfma_f32_16x16x32_bf16 v[8:11], v[178:181], v[228:231], v[8:11]
	v_mfma_f32_16x16x32_bf16 v[16:19], v[186:189], v[228:231], v[16:19]
	v_mfma_f32_16x16x32_bf16 v[56:59], v[182:185], v[198:201], v[56:59]
	v_mfma_f32_16x16x32_bf16 v[64:67], v[190:193], v[198:201], v[64:67]
	v_mfma_f32_16x16x32_bf16 v[40:43], v[182:185], v[216:219], v[40:43]
	v_mfma_f32_16x16x32_bf16 v[48:51], v[190:193], v[216:219], v[48:51]
	v_mfma_f32_16x16x32_bf16 v[24:27], v[182:185], v[224:227], v[24:27]
	v_mfma_f32_16x16x32_bf16 v[32:35], v[190:193], v[224:227], v[32:35]
	v_mfma_f32_16x16x32_bf16 v[8:11], v[182:185], v[232:235], v[8:11]
	v_mfma_f32_16x16x32_bf16 v[16:19], v[190:193], v[232:235], v[16:19]
	s_setprio 1
	s_barrier
	s_add_i32 s80, s80, 2
	s_add_u32 s38, s38, 0x100
	s_addc_u32 s39, s39, 0
	s_add_u32 s78, s78, 0x100
	s_addc_u32 s79, s79, 0
	s_cmp_gt_u32 s80, 13
	s_cbranch_scc0 .LBB0_979
	s_and_b64 vcc, exec, s[14:15]
	s_cbranch_vccz .LBB0_982
	s_barrier

;     DI bool next(int i, Unit& u) const { const int L = i * 32 + rank; if (L >= ppg * nN) return false; u.pm = ppg * grp + (L % ppg); const int p0 = L / ppg, p1 = p0 + rot; u.pn = rev ? nN - 1 - p0 : (p1 >= nN ? p1 - nN : p1); return true; }
; #define PG8_LDA(dst, b, h) do { _Pragma("unroll") for (int m = 0; m < 4; ++m) _Pragma("unroll") for (int k = 0; k < 2; ++k) dst[m][k] = *(const PG8_LAS bf16x8*)(lds + PG8_SA(b, h) + aoff + m * 2048 + k * 1024); } while (0)
; template <class Epi, class Sched, bool ALIGN_EPI = false, bool SP2 = false>
; __device__ __forceinline__ void gemm_phase(PG8_LAS unsigned char* lds, const Gemm g, const Sched& S, const Epi& E, const int tid) {
;     ...
;         const bool has_next = S.next(ui + 1, nxt);
;         const char* nA = has_next ? (const char*)g.A + (size_t)nxt.pm * tstep : cA; const char* nB = has_next ? (const char*)g.Bt + (size_t)nxt.pn * tstep : cB;
;         for (int t = 0; t < nt; t += 2) {
;             const bool last = (t == nt - 2);
;             const char* a1 = cA + (size_t)(t + 1) * kstep;
;             const char* a2 = last ? nA : cA + (size_t)(t + 2) * kstep; const char* b2 = last ? nB : cB + (size_t)(t + 2) * kstep;
;             const char* a3 = a2 + kstep; const char* b3 = b2 + kstep;
;             if (last && has_next) S.a_ready(nxt);
;             if constexpr (SP2) {
;             PG8_LDB(B0, 0, 0); PG8_LDB(B1, 0, 1); PG8_SCHED; PG8_LDA(At, 0, 0); PG8_STAGE(PG8_SA(1, 1), a1 + hstep, voffA);
;             PG8_WAIT_V(8); PG8_WAIT_L(0); PG8_BAR; PG8_MMA(0, 0, At, B0); PG8_MMA(0, 1, At, B1); PG8_BAR; PG8_SCHED;
;             PG8_LDA(At, 0, 1); PG8_STAGE(PG8_SB(0, 0), b2, voffB); PG8_STAGE(PG8_SB(0, 1), b2 + hstepB, voffB); PG8_STAGE(PG8_SA(0, 0), a2, voffA);
;             PG8_WAIT_V(8); PG8_WAIT_L(0); PG8_BAR; PG8_MMA(1, 0, At, B0); PG8_MMA(1, 1, At, B1); PG8_BAR; PG8_SCHED;
;             PG8_LDB(B0, 1, 0); PG8_LDB(B1, 1, 1); PG8_SCHED; PG8_LDA(At, 1, 0); PG8_STAGE(PG8_SA(0, 1), a2 + hstep, voffA);
;             PG8_WAIT_V(8); PG8_WAIT_L(0); PG8_BAR; PG8_MMA(0, 0, At, B0); PG8_MMA(0, 1, At, B1); PG8_BAR; PG8_SCHED;
;             PG8_LDA(At, 1, 1); PG8_STAGE(PG8_SB(1, 0), b3, voffB); PG8_STAGE(PG8_SB(1, 1), b3 + hstepB, voffB); PG8_STAGE(PG8_SA(1, 0), a3, voffA);
;             PG8_WAIT_V(8); PG8_WAIT_L(0); PG8_BAR; PG8_MMA(1, 0, At, B0); PG8_MMA(1, 1, At, B1); PG8_BAR; PG8_SCHED;
.LBB0_1108:
	s_add_u32 s42, s40, 0xfffc0080
	s_addc_u32 s43, s41, -1
	s_add_i32 s84, 0, 0x10000
	s_cmp_eq_u32 s83, 12
	s_cselect_b32 s55, s23, s43
	s_cselect_b32 s54, s79, s42
	v_add_u32_e32 v163, s84, v157
	s_cselect_b32 s43, s21, s82
	s_cselect_b32 s42, s80, s81
	s_cmp_eq_u32 s83, 12
	s_cselect_b32 s32, 1, 0
	s_andn2_b32 s32, s32, s28
	s_add_i32 s86, 0, 0x14000
	ds_read_b128 v[146:149], v163
	ds_read_b128 v[164:167], v163 offset:1024
	ds_read_b128 v[170:173], v163 offset:2048
	ds_read_b128 v[174:177], v163 offset:3072
	v_add_u32_e32 v163, s86, v157
	ds_read_b128 v[178:181], v163
	ds_read_b128 v[182:185], v163 offset:1024
	ds_read_b128 v[186:189], v163 offset:2048
	ds_read_b128 v[190:193], v163 offset:3072
	v_lshl_add_u64 v[236:237], s[40:41], 0, v[142:143]
	s_add_i32 m0, s37, 0xc000
	ds_read_b128 v[194:197], v162
	ds_read_b128 v[198:201], v162 offset:1024
	ds_read_b128 v[212:215], v162 offset:2048
	ds_read_b128 v[216:219], v162 offset:3072
	ds_read_b128 v[220:223], v162 offset:4096
	ds_read_b128 v[224:227], v162 offset:5120
	ds_read_b128 v[228:231], v162 offset:6144
	ds_read_b128 v[232:235], v162 offset:7168
	global_load_lds_dwordx4 v[236:237], off
	v_lshl_add_u64 v[236:237], s[40:41], 0, v[144:145]
	s_add_i32 m0, s37, 0xe000
	s_nop 0
	global_load_lds_dwordx4 v[236:237], off
	s_waitcnt vmcnt(8)
	s_waitcnt lgkmcnt(0)
	s_barrier
	s_setprio 0
	s_waitcnt lgkmcnt(0)
	v_mfma_f32_16x16x32_bf16 v[128:131], v[146:149], v[194:197], v[128:131]
	v_mfma_f32_16x16x32_bf16 v[124:127], v[170:173], v[194:197], v[124:127]
	v_mfma_f32_16x16x32_bf16 v[112:115], v[146:149], v[212:215], v[112:115]
	v_mfma_f32_16x16x32_bf16 v[108:111], v[170:173], v[212:215], v[108:111]
	v_mfma_f32_16x16x32_bf16 v[96:99], v[146:149], v[220:223], v[96:99]
	v_mfma_f32_16x16x32_bf16 v[92:95], v[170:173], v[220:223], v[92:95]
	v_mfma_f32_16x16x32_bf16 v[80:83], v[146:149], v[228:231], v[80:83]
	v_mfma_f32_16x16x32_bf16 v[76:79], v[170:173], v[228:231], v[76:79]
	v_mfma_f32_16x16x32_bf16 v[128:131], v[164:167], v[198:201], v[128:131]
	v_mfma_f32_16x16x32_bf16 v[124:127], v[174:177], v[198:201], v[124:127]
	v_mfma_f32_16x16x32_bf16 v[112:115], v[164:167], v[216:219], v[112:115]
	v_mfma_f32_16x16x32_bf16 v[108:111], v[174:177], v[216:219], v[108:111]
	v_mfma_f32_16x16x32_bf16 v[96:99], v[164:167], v[224:227], v[96:99]
	v_mfma_f32_16x16x32_bf16 v[92:95], v[174:177], v[224:227], v[92:95]
	v_mfma_f32_16x16x32_bf16 v[80:83], v[164:167], v[232:235], v[80:83]
	v_mfma_f32_16x16x32_bf16 v[76:79], v[174:177], v[232:235], v[76:79]
	s_setprio 1
	s_setprio 0
	v_mfma_f32_16x16x32_bf16 v[120:123], v[178:181], v[194:197], v[120:123]
	v_mfma_f32_16x16x32_bf16 v[116:119], v[186:189], v[194:197], v[116:119]
	v_mfma_f32_16x16x32_bf16 v[104:107], v[178:181], v[212:215], v[104:107]
	v_mfma_f32_16x16x32_bf16 v[100:103], v[186:189], v[212:215], v[100:103]
	v_mfma_f32_16x16x32_bf16 v[88:91], v[178:181], v[220:223], v[88:91]
	v_mfma_f32_16x16x32_bf16 v[84:87], v[186:189], v[220:223], v[84:87]
	v_mfma_f32_16x16x32_bf16 v[72:75], v[178:181], v[228:231], v[72:75]
	v_mfma_f32_16x16x32_bf16 v[68:71], v[186:189], v[228:231], v[68:71]
	v_mfma_f32_16x16x32_bf16 v[120:123], v[182:185], v[198:201], v[120:123]
	v_mfma_f32_16x16x32_bf16 v[116:119], v[190:193], v[198:201], v[116:119]
	v_mfma_f32_16x16x32_bf16 v[104:107], v[182:185], v[216:219], v[104:107]
	v_mfma_f32_16x16x32_bf16 v[100:103], v[190:193], v[216:219], v[100:103]
	v_mfma_f32_16x16x32_bf16 v[88:91], v[182:185], v[224:227], v[88:91]
	v_mfma_f32_16x16x32_bf16 v[84:87], v[190:193], v[224:227], v[84:87]
	v_mfma_f32_16x16x32_bf16 v[72:75], v[182:185], v[232:235], v[72:75]
	v_mfma_f32_16x16x32_bf16 v[68:71], v[190:193], v[232:235], v[68:71]
	s_setprio 1
	s_barrier
	s_add_i32 s84, s84, s63
	v_lshl_add_u64 v[236:237], s[42:43], 0, v[138:139]
	s_mov_b32 m0, s84
	ds_read_b128 v[194:197], v162 offset:16384
	ds_read_b128 v[198:201], v162 offset:17408
	ds_read_b128 v[212:215], v162 offset:18432
	ds_read_b128 v[216:219], v162 offset:19456
	ds_read_b128 v[220:223], v162 offset:20480
	ds_read_b128 v[224:227], v162 offset:21504
	ds_read_b128 v[228:231], v162 offset:22528
	ds_read_b128 v[232:235], v162 offset:23552
	s_cmp_lg_u32 s32, 0
	s_cbranch_scc1 .Lbt3_0
	global_load_lds_dwordx4 v[236:237], off

; #define PG8_STAGE(bufoff, gbase, voff) do { _Pragma("unroll") for (int _i = 0; _i < 2; ++_i) \
;         __builtin_amdgcn_global_load_lds((const unsigned*)((const char*)(gbase) + (voff)[_i]), (PG8_LAS unsigned*)(lds + (bufoff) + ldsw + _i * 8192), 16, 0, 0); } while (0)
; #define PG8_LDA(dst, b, h) do { _Pragma("unroll") for (int m = 0; m < 4; ++m) _Pragma("unroll") for (int k = 0; k < 2; ++k) dst[m][k] = *(const PG8_LAS bf16x8*)(lds + PG8_SA(b, h) + aoff + m * 2048 + k * 1024); } while (0)
; #define PG8_LDB(dst, b, h) do { _Pragma("unroll") for (int n = 0; n < 2; ++n) _Pragma("unroll") for (int k = 0; k < 2; ++k) dst[n][k] = *(const PG8_LAS bf16x8*)(lds + PG8_SB(b, h) + boff + n * 2048 + k * 1024); } while (0)
; #define PG8_MMA(ai, bj, At, Bt) do { __builtin_amdgcn_s_setprio(1); _Pragma("unroll") for (int m = 0; m < 4; ++m) _Pragma("unroll") for (int n = 0; n < 2; ++n) _Pragma("unroll") for (int k = 0; k < 2; ++k) \
;         acc[ai][bj][m][n] = __builtin_amdgcn_mfma_f32_16x16x32_bf16(Bt[n][k], At[m][k], acc[ai][bj][m][n], 0, 0, 0); __builtin_amdgcn_s_setprio(0); } while (0)
; template <class Epi, class Sched, bool ALIGN_EPI = false, bool SP2 = false>
; __device__ __forceinline__ void gemm_phase(PG8_LAS unsigned char* lds, const Gemm g, const Sched& S, const Epi& E, const int tid) {
;     ...
;             if constexpr (SP2) {
;             PG8_LDB(B0, 0, 0); PG8_LDB(B1, 0, 1); PG8_SCHED; PG8_LDA(At, 0, 0); PG8_STAGE(PG8_SA(1, 1), a1 + hstep, voffA);
;             PG8_WAIT_V(8); PG8_WAIT_L(0); PG8_BAR; PG8_MMA(0, 0, At, B0); PG8_MMA(0, 1, At, B1); PG8_BAR; PG8_SCHED;
;             PG8_LDA(At, 0, 1); PG8_STAGE(PG8_SB(0, 0), b2, voffB); PG8_STAGE(PG8_SB(0, 1), b2 + hstepB, voffB); PG8_STAGE(PG8_SA(0, 0), a2, voffA);
;             PG8_WAIT_V(8); PG8_WAIT_L(0); PG8_BAR; PG8_MMA(1, 0, At, B0); PG8_MMA(1, 1, At, B1); PG8_BAR; PG8_SCHED;
;             PG8_LDB(B0, 1, 0); PG8_LDB(B1, 1, 1); PG8_SCHED; PG8_LDA(At, 1, 0); PG8_STAGE(PG8_SA(0, 1), a2 + hstep, voffA);
;             PG8_WAIT_V(8); PG8_WAIT_L(0); PG8_BAR; PG8_MMA(0, 0, At, B0); PG8_MMA(0, 1, At, B1); PG8_BAR; PG8_SCHED;
;             PG8_LDA(At, 1, 1); PG8_STAGE(PG8_SB(1, 0), b3, voffB); PG8_STAGE(PG8_SB(1, 1), b3 + hstepB, voffB); PG8_STAGE(PG8_SA(1, 0), a3, voffA);
;             PG8_WAIT_V(8); PG8_WAIT_L(0); PG8_BAR; PG8_MMA(1, 0, At, B0); PG8_MMA(1, 1, At, B1); PG8_BAR; PG8_SCHED;
.Lbw3_2:
	s_waitcnt lgkmcnt(0)
	s_barrier
	s_setprio 0
	s_waitcnt lgkmcnt(0)
	v_mfma_f32_16x16x32_bf16 v[64:67], v[146:149], v[194:197], v[64:67]
	v_mfma_f32_16x16x32_bf16 v[60:63], v[170:173], v[194:197], v[60:63]
	v_mfma_f32_16x16x32_bf16 v[48:51], v[146:149], v[212:215], v[48:51]
	v_mfma_f32_16x16x32_bf16 v[44:47], v[170:173], v[212:215], v[44:47]
	v_mfma_f32_16x16x32_bf16 v[32:35], v[146:149], v[220:223], v[32:35]
	v_mfma_f32_16x16x32_bf16 v[28:31], v[170:173], v[220:223], v[28:31]
	v_mfma_f32_16x16x32_bf16 v[16:19], v[146:149], v[228:231], v[16:19]
	v_mfma_f32_16x16x32_bf16 v[12:15], v[170:173], v[228:231], v[12:15]
	v_mfma_f32_16x16x32_bf16 v[64:67], v[164:167], v[198:201], v[64:67]
	v_mfma_f32_16x16x32_bf16 v[60:63], v[174:177], v[198:201], v[60:63]
	v_mfma_f32_16x16x32_bf16 v[48:51], v[164:167], v[216:219], v[48:51]
	v_mfma_f32_16x16x32_bf16 v[44:47], v[174:177], v[216:219], v[44:47]
	v_mfma_f32_16x16x32_bf16 v[32:35], v[164:167], v[224:227], v[32:35]
	v_mfma_f32_16x16x32_bf16 v[28:31], v[174:177], v[224:227], v[28:31]
	v_mfma_f32_16x16x32_bf16 v[16:19], v[164:167], v[232:235], v[16:19]
	v_mfma_f32_16x16x32_bf16 v[12:15], v[174:177], v[232:235], v[12:15]
	s_setprio 1
	s_setprio 0
	v_mfma_f32_16x16x32_bf16 v[56:59], v[178:181], v[194:197], v[56:59]
	v_mfma_f32_16x16x32_bf16 v[52:55], v[186:189], v[194:197], v[52:55]
	v_mfma_f32_16x16x32_bf16 v[40:43], v[178:181], v[212:215], v[40:43]
	v_mfma_f32_16x16x32_bf16 v[36:39], v[186:189], v[212:215], v[36:39]
	v_mfma_f32_16x16x32_bf16 v[24:27], v[178:181], v[220:223], v[24:27]
	v_mfma_f32_16x16x32_bf16 v[20:23], v[186:189], v[220:223], v[20:23]
	v_mfma_f32_16x16x32_bf16 v[8:11], v[178:181], v[228:231], v[8:11]
	v_mfma_f32_16x16x32_bf16 v[4:7], v[186:189], v[228:231], v[4:7]
	v_mfma_f32_16x16x32_bf16 v[56:59], v[182:185], v[198:201], v[56:59]
	v_mfma_f32_16x16x32_bf16 v[52:55], v[190:193], v[198:201], v[52:55]
	v_mfma_f32_16x16x32_bf16 v[40:43], v[182:185], v[216:219], v[40:43]
	v_mfma_f32_16x16x32_bf16 v[36:39], v[190:193], v[216:219], v[36:39]
	v_mfma_f32_16x16x32_bf16 v[24:27], v[182:185], v[224:227], v[24:27]
	v_mfma_f32_16x16x32_bf16 v[20:23], v[190:193], v[224:227], v[20:23]
	v_mfma_f32_16x16x32_bf16 v[8:11], v[182:185], v[232:235], v[8:11]
	v_mfma_f32_16x16x32_bf16 v[4:7], v[190:193], v[232:235], v[4:7]
	s_setprio 1
	s_barrier
	s_add_i32 s84, 0, 0x18000
	v_add_u32_e32 v163, s84, v157
	s_add_i32 s85, 0, 0x1c000
	ds_read_b128 v[146:149], v163
	ds_read_b128 v[164:167], v163 offset:1024
	ds_read_b128 v[170:173], v163 offset:2048
	ds_read_b128 v[174:177], v163 offset:3072
	v_add_u32_e32 v163, s85, v157
	ds_read_b128 v[178:181], v163
	ds_read_b128 v[182:185], v163 offset:1024
	ds_read_b128 v[186:189], v163 offset:2048
	ds_read_b128 v[190:193], v163 offset:3072
	s_add_u32 s54, s54, 0x40000
	s_addc_u32 s55, s55, 0
	s_mov_b32 m0, s65
	v_lshl_add_u64 v[244:245], s[54:55], 0, v[140:141]
	ds_read_b128 v[194:197], v162 offset:32768
	ds_read_b128 v[198:201], v162 offset:33792
	ds_read_b128 v[212:215], v162 offset:34816
	ds_read_b128 v[216:219], v162 offset:35840
	ds_read_b128 v[220:223], v162 offset:36864
	ds_read_b128 v[224:227], v162 offset:37888
	ds_read_b128 v[228:231], v162 offset:38912
	ds_read_b128 v[232:235], v162 offset:39936
	s_cmp_lg_u32 s32, 0
	s_cbranch_scc1 .Lbt3_6
	global_load_lds_dwordx4 v[244:245], off

; #define PG8_STAGE(bufoff, gbase, voff) do { _Pragma("unroll") for (int _i = 0; _i < 2; ++_i) \
;         __builtin_amdgcn_global_load_lds((const unsigned*)((const char*)(gbase) + (voff)[_i]), (PG8_LAS unsigned*)(lds + (bufoff) + ldsw + _i * 8192), 16, 0, 0); } while (0)
; #define PG8_LDA(dst, b, h) do { _Pragma("unroll") for (int m = 0; m < 4; ++m) _Pragma("unroll") for (int k = 0; k < 2; ++k) dst[m][k] = *(const PG8_LAS bf16x8*)(lds + PG8_SA(b, h) + aoff + m * 2048 + k * 1024); } while (0)
; #define PG8_LDB(dst, b, h) do { _Pragma("unroll") for (int n = 0; n < 2; ++n) _Pragma("unroll") for (int k = 0; k < 2; ++k) dst[n][k] = *(const PG8_LAS bf16x8*)(lds + PG8_SB(b, h) + boff + n * 2048 + k * 1024); } while (0)
; #define PG8_MMA(ai, bj, At, Bt) do { __builtin_amdgcn_s_setprio(1); _Pragma("unroll") for (int m = 0; m < 4; ++m) _Pragma("unroll") for (int n = 0; n < 2; ++n) _Pragma("unroll") for (int k = 0; k < 2; ++k) \
;         acc[ai][bj][m][n] = __builtin_amdgcn_mfma_f32_16x16x32_bf16(Bt[n][k], At[m][k], acc[ai][bj][m][n], 0, 0, 0); __builtin_amdgcn_s_setprio(0); } while (0)
; template <class Epi, class Sched, bool ALIGN_EPI = false, bool SP2 = false>
; __device__ __forceinline__ void gemm_phase(PG8_LAS unsigned char* lds, const Gemm g, const Sched& S, const Epi& E, const int tid) {
;     ...
;             if constexpr (SP2) {
;             PG8_LDB(B0, 0, 0); PG8_LDB(B1, 0, 1); PG8_SCHED; PG8_LDA(At, 0, 0); PG8_STAGE(PG8_SA(1, 1), a1 + hstep, voffA);
;             PG8_WAIT_V(8); PG8_WAIT_L(0); PG8_BAR; PG8_MMA(0, 0, At, B0); PG8_MMA(0, 1, At, B1); PG8_BAR; PG8_SCHED;
;             PG8_LDA(At, 0, 1); PG8_STAGE(PG8_SB(0, 0), b2, voffB); PG8_STAGE(PG8_SB(0, 1), b2 + hstepB, voffB); PG8_STAGE(PG8_SA(0, 0), a2, voffA);
;             PG8_WAIT_V(8); PG8_WAIT_L(0); PG8_BAR; PG8_MMA(1, 0, At, B0); PG8_MMA(1, 1, At, B1); PG8_BAR; PG8_SCHED;
;             PG8_LDB(B0, 1, 0); PG8_LDB(B1, 1, 1); PG8_SCHED; PG8_LDA(At, 1, 0); PG8_STAGE(PG8_SA(0, 1), a2 + hstep, voffA);
;             PG8_WAIT_V(8); PG8_WAIT_L(0); PG8_BAR; PG8_MMA(0, 0, At, B0); PG8_MMA(0, 1, At, B1); PG8_BAR; PG8_SCHED;
;             PG8_LDA(At, 1, 1); PG8_STAGE(PG8_SB(1, 0), b3, voffB); PG8_STAGE(PG8_SB(1, 1), b3 + hstepB, voffB); PG8_STAGE(PG8_SA(1, 0), a3, voffA);
;             PG8_WAIT_V(8); PG8_WAIT_L(0); PG8_BAR; PG8_MMA(1, 0, At, B0); PG8_MMA(1, 1, At, B1); PG8_BAR; PG8_SCHED;
.Lbw3_0:
	s_waitcnt lgkmcnt(0)
	s_barrier
	s_setprio 0
	s_waitcnt lgkmcnt(0)
	v_mfma_f32_16x16x32_bf16 v[128:131], v[146:149], v[194:197], v[128:131]
	v_mfma_f32_16x16x32_bf16 v[124:127], v[170:173], v[194:197], v[124:127]
	v_mfma_f32_16x16x32_bf16 v[112:115], v[146:149], v[212:215], v[112:115]
	v_mfma_f32_16x16x32_bf16 v[108:111], v[170:173], v[212:215], v[108:111]
	v_mfma_f32_16x16x32_bf16 v[96:99], v[146:149], v[220:223], v[96:99]
	v_mfma_f32_16x16x32_bf16 v[92:95], v[170:173], v[220:223], v[92:95]
	v_mfma_f32_16x16x32_bf16 v[80:83], v[146:149], v[228:231], v[80:83]
	v_mfma_f32_16x16x32_bf16 v[76:79], v[170:173], v[228:231], v[76:79]
	v_mfma_f32_16x16x32_bf16 v[128:131], v[164:167], v[198:201], v[128:131]
	v_mfma_f32_16x16x32_bf16 v[124:127], v[174:177], v[198:201], v[124:127]
	v_mfma_f32_16x16x32_bf16 v[112:115], v[164:167], v[216:219], v[112:115]
	v_mfma_f32_16x16x32_bf16 v[108:111], v[174:177], v[216:219], v[108:111]
	v_mfma_f32_16x16x32_bf16 v[96:99], v[164:167], v[224:227], v[96:99]
	v_mfma_f32_16x16x32_bf16 v[92:95], v[174:177], v[224:227], v[92:95]
	v_mfma_f32_16x16x32_bf16 v[80:83], v[164:167], v[232:235], v[80:83]
	v_mfma_f32_16x16x32_bf16 v[76:79], v[174:177], v[232:235], v[76:79]
	s_setprio 1
	s_setprio 0
	v_mfma_f32_16x16x32_bf16 v[120:123], v[178:181], v[194:197], v[120:123]
	v_mfma_f32_16x16x32_bf16 v[116:119], v[186:189], v[194:197], v[116:119]
	v_mfma_f32_16x16x32_bf16 v[104:107], v[178:181], v[212:215], v[104:107]
	v_mfma_f32_16x16x32_bf16 v[100:103], v[186:189], v[212:215], v[100:103]
	v_mfma_f32_16x16x32_bf16 v[88:91], v[178:181], v[220:223], v[88:91]
	v_mfma_f32_16x16x32_bf16 v[84:87], v[186:189], v[220:223], v[84:87]
	v_mfma_f32_16x16x32_bf16 v[72:75], v[178:181], v[228:231], v[72:75]
	v_mfma_f32_16x16x32_bf16 v[68:71], v[186:189], v[228:231], v[68:71]
	v_mfma_f32_16x16x32_bf16 v[120:123], v[182:185], v[198:201], v[120:123]
	v_mfma_f32_16x16x32_bf16 v[116:119], v[190:193], v[198:201], v[116:119]
	v_mfma_f32_16x16x32_bf16 v[104:107], v[182:185], v[216:219], v[104:107]
	v_mfma_f32_16x16x32_bf16 v[100:103], v[190:193], v[216:219], v[100:103]
	v_mfma_f32_16x16x32_bf16 v[88:91], v[182:185], v[224:227], v[88:91]
	v_mfma_f32_16x16x32_bf16 v[84:87], v[190:193], v[224:227], v[84:87]
	v_mfma_f32_16x16x32_bf16 v[72:75], v[182:185], v[232:235], v[72:75]
	v_mfma_f32_16x16x32_bf16 v[68:71], v[190:193], v[232:235], v[68:71]
	s_setprio 1
	s_barrier
	s_add_i32 s54, s84, s63
	v_lshl_add_u64 v[236:237], v[236:237], 0, s[52:53]
	s_mov_b32 m0, s54
	ds_read_b128 v[194:197], v162 offset:49152
	ds_read_b128 v[198:201], v162 offset:50176
	ds_read_b128 v[212:215], v162 offset:51200
	ds_read_b128 v[216:219], v162 offset:52224
	ds_read_b128 v[220:223], v162 offset:53248
	ds_read_b128 v[224:227], v162 offset:54272
	ds_read_b128 v[228:231], v162 offset:55296
	ds_read_b128 v[232:235], v162 offset:56320
	s_cmp_lg_u32 s32, 0
	s_cbranch_scc1 .Lbt3_8
	global_load_lds_dwordx4 v[236:237], off

; #define PG8_STAGE(bufoff, gbase, voff) do { _Pragma("unroll") for (int _i = 0; _i < 2; ++_i) \
;         __builtin_amdgcn_global_load_lds((const unsigned*)((const char*)(gbase) + (voff)[_i]), (PG8_LAS unsigned*)(lds + (bufoff) + ldsw + _i * 8192), 16, 0, 0); } while (0)
; #define PG8_LDA(dst, b, h) do { _Pragma("unroll") for (int m = 0; m < 4; ++m) _Pragma("unroll") for (int k = 0; k < 2; ++k) dst[m][k] = *(const PG8_LAS bf16x8*)(lds + PG8_SA(b, h) + aoff + m * 2048 + k * 1024); } while (0)
; #define PG8_WAIT_V(n) asm volatile("s_waitcnt vmcnt(" #n ")" ::: "memory")
; #define PG8_WAIT_L(n) asm volatile("s_waitcnt lgkmcnt(" #n ")" ::: "memory")
; template <class Epi, class Sched, bool ALIGN_EPI = false, bool SP2 = false>
; __device__ __forceinline__ void gemm_phase(PG8_LAS unsigned char* lds, const Gemm g, const Sched& S, const Epi& E, const int tid) {
;     ...
;         for (int t = 0; t < nt; t += 2) {
;             const bool last = (t == nt - 2);
;             const char* a1 = cA + (size_t)(t + 1) * kstep;
;             const char* a2 = last ? nA : cA + (size_t)(t + 2) * kstep; const char* b2 = last ? nB : cB + (size_t)(t + 2) * kstep;
;             const char* a3 = a2 + kstep; const char* b3 = b2 + kstep;
;             if (last && has_next) S.a_ready(nxt);
;             if constexpr (SP2) {
;             PG8_LDB(B0, 0, 0); PG8_LDB(B1, 0, 1); PG8_SCHED; PG8_LDA(At, 0, 0); PG8_STAGE(PG8_SA(1, 1), a1 + hstep, voffA);
;             PG8_WAIT_V(8); PG8_WAIT_L(0); PG8_BAR; PG8_MMA(0, 0, At, B0); PG8_MMA(0, 1, At, B1); PG8_BAR; PG8_SCHED;
;             PG8_LDA(At, 0, 1); PG8_STAGE(PG8_SB(0, 0), b2, voffB); PG8_STAGE(PG8_SB(0, 1), b2 + hstepB, voffB); PG8_STAGE(PG8_SA(0, 0), a2, voffA);
;             PG8_WAIT_V(8); PG8_WAIT_L(0); PG8_BAR; PG8_MMA(1, 0, At, B0); PG8_MMA(1, 1, At, B1); PG8_BAR; PG8_SCHED;
;             PG8_LDB(B0, 1, 0); PG8_LDB(B1, 1, 1); PG8_SCHED; PG8_LDA(At, 1, 0); PG8_STAGE(PG8_SA(0, 1), a2 + hstep, voffA);
;             PG8_WAIT_V(8); PG8_WAIT_L(0); PG8_BAR; PG8_MMA(0, 0, At, B0); PG8_MMA(0, 1, At, B1); PG8_BAR; PG8_SCHED;
;             PG8_LDA(At, 1, 1); PG8_STAGE(PG8_SB(1, 0), b3, voffB); PG8_STAGE(PG8_SB(1, 1), b3 + hstepB, voffB); PG8_STAGE(PG8_SA(1, 0), a3, voffA);
;             PG8_WAIT_V(8); PG8_WAIT_L(0); PG8_BAR; PG8_MMA(1, 0, At, B0); PG8_MMA(1, 1, At, B1); PG8_BAR; PG8_SCHED;
;     ...
;         if constexpr (ALIGN_EPI) { if (wr == 0) PG8_BAR; }
.Lbt3_13:
	s_waitcnt vmcnt(8)
	s_waitcnt lgkmcnt(0)
	s_barrier
	s_setprio 0
	s_waitcnt lgkmcnt(0)
	v_mfma_f32_16x16x32_bf16 v[64:67], v[146:149], v[194:197], v[64:67]
	v_mfma_f32_16x16x32_bf16 v[60:63], v[170:173], v[194:197], v[60:63]
	v_mfma_f32_16x16x32_bf16 v[48:51], v[146:149], v[212:215], v[48:51]
	v_mfma_f32_16x16x32_bf16 v[44:47], v[170:173], v[212:215], v[44:47]
	v_mfma_f32_16x16x32_bf16 v[32:35], v[146:149], v[220:223], v[32:35]
	v_mfma_f32_16x16x32_bf16 v[28:31], v[170:173], v[220:223], v[28:31]
	v_mfma_f32_16x16x32_bf16 v[16:19], v[146:149], v[228:231], v[16:19]
	v_mfma_f32_16x16x32_bf16 v[12:15], v[170:173], v[228:231], v[12:15]
	v_mfma_f32_16x16x32_bf16 v[64:67], v[164:167], v[198:201], v[64:67]
	v_mfma_f32_16x16x32_bf16 v[60:63], v[174:177], v[198:201], v[60:63]
	v_mfma_f32_16x16x32_bf16 v[48:51], v[164:167], v[216:219], v[48:51]
	v_mfma_f32_16x16x32_bf16 v[44:47], v[174:177], v[216:219], v[44:47]
	v_mfma_f32_16x16x32_bf16 v[32:35], v[164:167], v[224:227], v[32:35]
	v_mfma_f32_16x16x32_bf16 v[28:31], v[174:177], v[224:227], v[28:31]
	v_mfma_f32_16x16x32_bf16 v[16:19], v[164:167], v[232:235], v[16:19]
	v_mfma_f32_16x16x32_bf16 v[12:15], v[174:177], v[232:235], v[12:15]
	s_setprio 1
	s_setprio 0
	v_mfma_f32_16x16x32_bf16 v[56:59], v[178:181], v[194:197], v[56:59]
	v_mfma_f32_16x16x32_bf16 v[52:55], v[186:189], v[194:197], v[52:55]
	v_mfma_f32_16x16x32_bf16 v[40:43], v[178:181], v[212:215], v[40:43]
	v_mfma_f32_16x16x32_bf16 v[36:39], v[186:189], v[212:215], v[36:39]
	v_mfma_f32_16x16x32_bf16 v[24:27], v[178:181], v[220:223], v[24:27]
	v_mfma_f32_16x16x32_bf16 v[20:23], v[186:189], v[220:223], v[20:23]
	v_mfma_f32_16x16x32_bf16 v[8:11], v[178:181], v[228:231], v[8:11]
	v_mfma_f32_16x16x32_bf16 v[4:7], v[186:189], v[228:231], v[4:7]
	v_mfma_f32_16x16x32_bf16 v[56:59], v[182:185], v[198:201], v[56:59]
	v_mfma_f32_16x16x32_bf16 v[52:55], v[190:193], v[198:201], v[52:55]
	v_mfma_f32_16x16x32_bf16 v[40:43], v[182:185], v[216:219], v[40:43]
	v_mfma_f32_16x16x32_bf16 v[36:39], v[190:193], v[216:219], v[36:39]
	v_mfma_f32_16x16x32_bf16 v[24:27], v[182:185], v[224:227], v[24:27]
	v_mfma_f32_16x16x32_bf16 v[20:23], v[190:193], v[224:227], v[20:23]
	v_mfma_f32_16x16x32_bf16 v[8:11], v[182:185], v[232:235], v[8:11]
	v_mfma_f32_16x16x32_bf16 v[4:7], v[190:193], v[232:235], v[4:7]
	s_setprio 1
	s_barrier
	s_add_i32 s83, s83, 2
	s_add_u32 s40, s40, 0x100
	s_addc_u32 s41, s41, 0
	s_add_u32 s81, s81, 0x100
	s_addc_u32 s82, s82, 0
	s_cmp_gt_u32 s83, 13
	s_cbranch_scc0 .LBB0_1108
	s_and_b64 vcc, exec, s[18:19]
	s_cbranch_vccz .LBB0_1111
	s_barrier

;     DI bool next(int i, Unit& u) const { const int L = i * 32 + rank; if (L >= ppg * nN) return false; u.pm = ppg * grp + (L % ppg); const int p0 = L / ppg, p1 = p0 + rot; u.pn = rev ? nN - 1 - p0 : (p1 >= nN ? p1 - nN : p1); return true; }
; #define PG8_LDA(dst, b, h) do { _Pragma("unroll") for (int m = 0; m < 4; ++m) _Pragma("unroll") for (int k = 0; k < 2; ++k) dst[m][k] = *(const PG8_LAS bf16x8*)(lds + PG8_SA(b, h) + aoff + m * 2048 + k * 1024); } while (0)
; template <class Epi, class Sched, bool ALIGN_EPI = false, bool SP2 = false>
; __device__ __forceinline__ void gemm_phase(PG8_LAS unsigned char* lds, const Gemm g, const Sched& S, const Epi& E, const int tid) {
;     ...
;         const bool has_next = S.next(ui + 1, nxt);
;         const char* nA = has_next ? (const char*)g.A + (size_t)nxt.pm * tstep : cA; const char* nB = has_next ? (const char*)g.Bt + (size_t)nxt.pn * tstep : cB;
;         for (int t = 0; t < nt; t += 2) {
;             const bool last = (t == nt - 2);
;             const char* a1 = cA + (size_t)(t + 1) * kstep;
;             const char* a2 = last ? nA : cA + (size_t)(t + 2) * kstep; const char* b2 = last ? nB : cB + (size_t)(t + 2) * kstep;
;             const char* a3 = a2 + kstep; const char* b3 = b2 + kstep;
;             if (last && has_next) S.a_ready(nxt);
;             if constexpr (SP2) {
;             PG8_LDB(B0, 0, 0); PG8_LDB(B1, 0, 1); PG8_SCHED; PG8_LDA(At, 0, 0); PG8_STAGE(PG8_SA(1, 1), a1 + hstep, voffA);
;             PG8_WAIT_V(8); PG8_WAIT_L(0); PG8_BAR; PG8_MMA(0, 0, At, B0); PG8_MMA(0, 1, At, B1); PG8_BAR; PG8_SCHED;
;             PG8_LDA(At, 0, 1); PG8_STAGE(PG8_SB(0, 0), b2, voffB); PG8_STAGE(PG8_SB(0, 1), b2 + hstepB, voffB); PG8_STAGE(PG8_SA(0, 0), a2, voffA);
;             PG8_WAIT_V(8); PG8_WAIT_L(0); PG8_BAR; PG8_MMA(1, 0, At, B0); PG8_MMA(1, 1, At, B1); PG8_BAR; PG8_SCHED;
;             PG8_LDB(B0, 1, 0); PG8_LDB(B1, 1, 1); PG8_SCHED; PG8_LDA(At, 1, 0); PG8_STAGE(PG8_SA(0, 1), a2 + hstep, voffA);
;             PG8_WAIT_V(8); PG8_WAIT_L(0); PG8_BAR; PG8_MMA(0, 0, At, B0); PG8_MMA(0, 1, At, B1); PG8_BAR; PG8_SCHED;
;             PG8_LDA(At, 1, 1); PG8_STAGE(PG8_SB(1, 0), b3, voffB); PG8_STAGE(PG8_SB(1, 1), b3 + hstepB, voffB); PG8_STAGE(PG8_SA(1, 0), a3, voffA);
;             PG8_WAIT_V(8); PG8_WAIT_L(0); PG8_BAR; PG8_MMA(1, 0, At, B0); PG8_MMA(1, 1, At, B1); PG8_BAR; PG8_SCHED;
.LBB0_1266:
	s_add_u32 s38, s40, 0xfffc0080
	s_addc_u32 s39, s41, -1
	s_add_i32 s83, 0, 0x10000
	s_cmp_eq_u32 s82, 12
	s_cselect_b32 s43, s21, s39
	s_cselect_b32 s42, s29, s38
	v_add_u32_e32 v150, s83, v158
	s_cselect_b32 s39, s19, s81
	s_cselect_b32 s38, s79, s80
	s_cmp_eq_u32 s82, 12
	s_cselect_b32 s32, 1, 0
	s_andn2_b32 s32, s32, s36
	s_add_i32 s86, 0, 0x14000
	ds_read_b128 v[146:149], v150
	ds_read_b128 v[162:165], v150 offset:1024
	ds_read_b128 v[170:173], v150 offset:2048
	ds_read_b128 v[174:177], v150 offset:3072
	v_add_u32_e32 v150, s86, v158
	ds_read_b128 v[178:181], v150
	ds_read_b128 v[182:185], v150 offset:1024
	ds_read_b128 v[186:189], v150 offset:2048
	ds_read_b128 v[190:193], v150 offset:3072
	v_lshl_add_u64 v[150:151], s[40:41], 0, v[142:143]
	s_add_i32 m0, s31, 0xc000
	ds_read_b128 v[194:197], v160
	ds_read_b128 v[198:201], v160 offset:1024
	ds_read_b128 v[212:215], v160 offset:2048
	ds_read_b128 v[216:219], v160 offset:3072
	ds_read_b128 v[220:223], v160 offset:4096
	ds_read_b128 v[224:227], v160 offset:5120
	ds_read_b128 v[228:231], v160 offset:6144
	ds_read_b128 v[232:235], v160 offset:7168
	global_load_lds_dwordx4 v[150:151], off
	v_lshl_add_u64 v[150:151], s[40:41], 0, v[144:145]
	s_add_i32 m0, s31, 0xe000
	s_nop 0
	global_load_lds_dwordx4 v[150:151], off
	s_waitcnt vmcnt(8)
	s_waitcnt lgkmcnt(0)
	s_barrier
	s_setprio 0
	s_waitcnt lgkmcnt(0)
	v_mfma_f32_16x16x32_bf16 v[120:123], v[146:149], v[194:197], v[120:123]
	v_mfma_f32_16x16x32_bf16 v[128:131], v[170:173], v[194:197], v[128:131]
	v_mfma_f32_16x16x32_bf16 v[100:103], v[146:149], v[212:215], v[100:103]
	v_mfma_f32_16x16x32_bf16 v[108:111], v[170:173], v[212:215], v[108:111]
	v_mfma_f32_16x16x32_bf16 v[84:87], v[146:149], v[220:223], v[84:87]
	v_mfma_f32_16x16x32_bf16 v[92:95], v[170:173], v[220:223], v[92:95]
	v_mfma_f32_16x16x32_bf16 v[68:71], v[146:149], v[228:231], v[68:71]
	v_mfma_f32_16x16x32_bf16 v[76:79], v[170:173], v[228:231], v[76:79]
	v_mfma_f32_16x16x32_bf16 v[120:123], v[162:165], v[198:201], v[120:123]
	v_mfma_f32_16x16x32_bf16 v[128:131], v[174:177], v[198:201], v[128:131]
	v_mfma_f32_16x16x32_bf16 v[100:103], v[162:165], v[216:219], v[100:103]
	v_mfma_f32_16x16x32_bf16 v[108:111], v[174:177], v[216:219], v[108:111]
	v_mfma_f32_16x16x32_bf16 v[84:87], v[162:165], v[224:227], v[84:87]
	v_mfma_f32_16x16x32_bf16 v[92:95], v[174:177], v[224:227], v[92:95]
	v_mfma_f32_16x16x32_bf16 v[68:71], v[162:165], v[232:235], v[68:71]
	v_mfma_f32_16x16x32_bf16 v[76:79], v[174:177], v[232:235], v[76:79]
	s_setprio 1
	s_setprio 0
	v_mfma_f32_16x16x32_bf16 v[116:119], v[178:181], v[194:197], v[116:119]
	v_mfma_f32_16x16x32_bf16 v[124:127], v[186:189], v[194:197], v[124:127]
	v_mfma_f32_16x16x32_bf16 v[104:107], v[178:181], v[212:215], v[104:107]
	v_mfma_f32_16x16x32_bf16 v[112:115], v[186:189], v[212:215], v[112:115]
	v_mfma_f32_16x16x32_bf16 v[88:91], v[178:181], v[220:223], v[88:91]
	v_mfma_f32_16x16x32_bf16 v[96:99], v[186:189], v[220:223], v[96:99]
	v_mfma_f32_16x16x32_bf16 v[72:75], v[178:181], v[228:231], v[72:75]
	v_mfma_f32_16x16x32_bf16 v[80:83], v[186:189], v[228:231], v[80:83]
	v_mfma_f32_16x16x32_bf16 v[116:119], v[182:185], v[198:201], v[116:119]
	v_mfma_f32_16x16x32_bf16 v[124:127], v[190:193], v[198:201], v[124:127]
	v_mfma_f32_16x16x32_bf16 v[104:107], v[182:185], v[216:219], v[104:107]
	v_mfma_f32_16x16x32_bf16 v[112:115], v[190:193], v[216:219], v[112:115]
	v_mfma_f32_16x16x32_bf16 v[88:91], v[182:185], v[224:227], v[88:91]
	v_mfma_f32_16x16x32_bf16 v[96:99], v[190:193], v[224:227], v[96:99]
	v_mfma_f32_16x16x32_bf16 v[72:75], v[182:185], v[232:235], v[72:75]
	v_mfma_f32_16x16x32_bf16 v[80:83], v[190:193], v[232:235], v[80:83]
	s_setprio 1
	s_barrier
	s_add_i32 s83, s83, s55
	v_lshl_add_u64 v[150:151], s[38:39], 0, v[136:137]
	s_mov_b32 m0, s83
	ds_read_b128 v[194:197], v160 offset:16384
	ds_read_b128 v[198:201], v160 offset:17408
	ds_read_b128 v[212:215], v160 offset:18432
	ds_read_b128 v[216:219], v160 offset:19456
	ds_read_b128 v[220:223], v160 offset:20480
	ds_read_b128 v[224:227], v160 offset:21504
	ds_read_b128 v[228:231], v160 offset:22528
	ds_read_b128 v[232:235], v160 offset:23552
	s_cmp_lg_u32 s32, 0
	s_cbranch_scc1 .Lbt4_0
	global_load_lds_dwordx4 v[150:151], off

; #define PG8_STAGE(bufoff, gbase, voff) do { _Pragma("unroll") for (int _i = 0; _i < 2; ++_i) \
;         __builtin_amdgcn_global_load_lds((const unsigned*)((const char*)(gbase) + (voff)[_i]), (PG8_LAS unsigned*)(lds + (bufoff) + ldsw + _i * 8192), 16, 0, 0); } while (0)
; #define PG8_LDA(dst, b, h) do { _Pragma("unroll") for (int m = 0; m < 4; ++m) _Pragma("unroll") for (int k = 0; k < 2; ++k) dst[m][k] = *(const PG8_LAS bf16x8*)(lds + PG8_SA(b, h) + aoff + m * 2048 + k * 1024); } while (0)
; #define PG8_LDB(dst, b, h) do { _Pragma("unroll") for (int n = 0; n < 2; ++n) _Pragma("unroll") for (int k = 0; k < 2; ++k) dst[n][k] = *(const PG8_LAS bf16x8*)(lds + PG8_SB(b, h) + boff + n * 2048 + k * 1024); } while (0)
; #define PG8_MMA(ai, bj, At, Bt) do { __builtin_amdgcn_s_setprio(1); _Pragma("unroll") for (int m = 0; m < 4; ++m) _Pragma("unroll") for (int n = 0; n < 2; ++n) _Pragma("unroll") for (int k = 0; k < 2; ++k) \
;         acc[ai][bj][m][n] = __builtin_amdgcn_mfma_f32_16x16x32_bf16(Bt[n][k], At[m][k], acc[ai][bj][m][n], 0, 0, 0); __builtin_amdgcn_s_setprio(0); } while (0)
; template <class Epi, class Sched, bool ALIGN_EPI = false, bool SP2 = false>
; __device__ __forceinline__ void gemm_phase(PG8_LAS unsigned char* lds, const Gemm g, const Sched& S, const Epi& E, const int tid) {
;     ...
;             if constexpr (SP2) {
;             PG8_LDB(B0, 0, 0); PG8_LDB(B1, 0, 1); PG8_SCHED; PG8_LDA(At, 0, 0); PG8_STAGE(PG8_SA(1, 1), a1 + hstep, voffA);
;             PG8_WAIT_V(8); PG8_WAIT_L(0); PG8_BAR; PG8_MMA(0, 0, At, B0); PG8_MMA(0, 1, At, B1); PG8_BAR; PG8_SCHED;
;             PG8_LDA(At, 0, 1); PG8_STAGE(PG8_SB(0, 0), b2, voffB); PG8_STAGE(PG8_SB(0, 1), b2 + hstepB, voffB); PG8_STAGE(PG8_SA(0, 0), a2, voffA);
;             PG8_WAIT_V(8); PG8_WAIT_L(0); PG8_BAR; PG8_MMA(1, 0, At, B0); PG8_MMA(1, 1, At, B1); PG8_BAR; PG8_SCHED;
;             PG8_LDB(B0, 1, 0); PG8_LDB(B1, 1, 1); PG8_SCHED; PG8_LDA(At, 1, 0); PG8_STAGE(PG8_SA(0, 1), a2 + hstep, voffA);
;             PG8_WAIT_V(8); PG8_WAIT_L(0); PG8_BAR; PG8_MMA(0, 0, At, B0); PG8_MMA(0, 1, At, B1); PG8_BAR; PG8_SCHED;
;             PG8_LDA(At, 1, 1); PG8_STAGE(PG8_SB(1, 0), b3, voffB); PG8_STAGE(PG8_SB(1, 1), b3 + hstepB, voffB); PG8_STAGE(PG8_SA(1, 0), a3, voffA);
;             PG8_WAIT_V(8); PG8_WAIT_L(0); PG8_BAR; PG8_MMA(1, 0, At, B0); PG8_MMA(1, 1, At, B1); PG8_BAR; PG8_SCHED;
.Lbw4_2:
	s_waitcnt lgkmcnt(0)
	s_barrier
	s_setprio 0
	s_waitcnt lgkmcnt(0)
	v_mfma_f32_16x16x32_bf16 v[52:55], v[146:149], v[194:197], v[52:55]
	v_mfma_f32_16x16x32_bf16 v[60:63], v[170:173], v[194:197], v[60:63]
	v_mfma_f32_16x16x32_bf16 v[36:39], v[146:149], v[212:215], v[36:39]
	v_mfma_f32_16x16x32_bf16 v[44:47], v[170:173], v[212:215], v[44:47]
	v_mfma_f32_16x16x32_bf16 v[20:23], v[146:149], v[220:223], v[20:23]
	v_mfma_f32_16x16x32_bf16 v[28:31], v[170:173], v[220:223], v[28:31]
	v_mfma_f32_16x16x32_bf16 v[4:7], v[146:149], v[228:231], v[4:7]
	v_mfma_f32_16x16x32_bf16 v[12:15], v[170:173], v[228:231], v[12:15]
	v_mfma_f32_16x16x32_bf16 v[52:55], v[162:165], v[198:201], v[52:55]
	v_mfma_f32_16x16x32_bf16 v[60:63], v[174:177], v[198:201], v[60:63]
	v_mfma_f32_16x16x32_bf16 v[36:39], v[162:165], v[216:219], v[36:39]
	v_mfma_f32_16x16x32_bf16 v[44:47], v[174:177], v[216:219], v[44:47]
	v_mfma_f32_16x16x32_bf16 v[20:23], v[162:165], v[224:227], v[20:23]
	v_mfma_f32_16x16x32_bf16 v[28:31], v[174:177], v[224:227], v[28:31]
	v_mfma_f32_16x16x32_bf16 v[4:7], v[162:165], v[232:235], v[4:7]
	v_mfma_f32_16x16x32_bf16 v[12:15], v[174:177], v[232:235], v[12:15]
	s_setprio 1
	s_setprio 0
	v_mfma_f32_16x16x32_bf16 v[56:59], v[178:181], v[194:197], v[56:59]
	v_mfma_f32_16x16x32_bf16 v[64:67], v[186:189], v[194:197], v[64:67]
	v_mfma_f32_16x16x32_bf16 v[40:43], v[178:181], v[212:215], v[40:43]
	v_mfma_f32_16x16x32_bf16 v[48:51], v[186:189], v[212:215], v[48:51]
	v_mfma_f32_16x16x32_bf16 v[24:27], v[178:181], v[220:223], v[24:27]
	v_mfma_f32_16x16x32_bf16 v[32:35], v[186:189], v[220:223], v[32:35]
	v_mfma_f32_16x16x32_bf16 v[8:11], v[178:181], v[228:231], v[8:11]
	v_mfma_f32_16x16x32_bf16 v[16:19], v[186:189], v[228:231], v[16:19]
	v_mfma_f32_16x16x32_bf16 v[56:59], v[182:185], v[198:201], v[56:59]
	v_mfma_f32_16x16x32_bf16 v[64:67], v[190:193], v[198:201], v[64:67]
	v_mfma_f32_16x16x32_bf16 v[40:43], v[182:185], v[216:219], v[40:43]
	v_mfma_f32_16x16x32_bf16 v[48:51], v[190:193], v[216:219], v[48:51]
	v_mfma_f32_16x16x32_bf16 v[24:27], v[182:185], v[224:227], v[24:27]
	v_mfma_f32_16x16x32_bf16 v[32:35], v[190:193], v[224:227], v[32:35]
	v_mfma_f32_16x16x32_bf16 v[8:11], v[182:185], v[232:235], v[8:11]
	v_mfma_f32_16x16x32_bf16 v[16:19], v[190:193], v[232:235], v[16:19]
	s_setprio 1
	s_barrier
	s_add_i32 s83, 0, 0x18000
	v_add_u32_e32 v161, s83, v158
	s_add_i32 s84, 0, 0x1c000
	ds_read_b128 v[146:149], v161
	ds_read_b128 v[162:165], v161 offset:1024
	ds_read_b128 v[170:173], v161 offset:2048
	ds_read_b128 v[174:177], v161 offset:3072
	v_add_u32_e32 v161, s84, v158
	ds_read_b128 v[178:181], v161
	ds_read_b128 v[182:185], v161 offset:1024
	ds_read_b128 v[186:189], v161 offset:2048
	ds_read_b128 v[190:193], v161 offset:3072
	s_add_u32 s42, s42, 0x40000
	s_addc_u32 s43, s43, 0
	s_mov_b32 m0, s64
	v_lshl_add_u64 v[240:241], s[42:43], 0, v[134:135]
	ds_read_b128 v[194:197], v160 offset:32768
	ds_read_b128 v[198:201], v160 offset:33792
	ds_read_b128 v[212:215], v160 offset:34816
	ds_read_b128 v[216:219], v160 offset:35840
	ds_read_b128 v[220:223], v160 offset:36864
	ds_read_b128 v[224:227], v160 offset:37888
	ds_read_b128 v[228:231], v160 offset:38912
	ds_read_b128 v[232:235], v160 offset:39936
	s_cmp_lg_u32 s32, 0
	s_cbranch_scc1 .Lbt4_6
	global_load_lds_dwordx4 v[240:241], off

; #define PG8_STAGE(bufoff, gbase, voff) do { _Pragma("unroll") for (int _i = 0; _i < 2; ++_i) \
;         __builtin_amdgcn_global_load_lds((const unsigned*)((const char*)(gbase) + (voff)[_i]), (PG8_LAS unsigned*)(lds + (bufoff) + ldsw + _i * 8192), 16, 0, 0); } while (0)
; #define PG8_LDA(dst, b, h) do { _Pragma("unroll") for (int m = 0; m < 4; ++m) _Pragma("unroll") for (int k = 0; k < 2; ++k) dst[m][k] = *(const PG8_LAS bf16x8*)(lds + PG8_SA(b, h) + aoff + m * 2048 + k * 1024); } while (0)
; #define PG8_LDB(dst, b, h) do { _Pragma("unroll") for (int n = 0; n < 2; ++n) _Pragma("unroll") for (int k = 0; k < 2; ++k) dst[n][k] = *(const PG8_LAS bf16x8*)(lds + PG8_SB(b, h) + boff + n * 2048 + k * 1024); } while (0)
; #define PG8_MMA(ai, bj, At, Bt) do { __builtin_amdgcn_s_setprio(1); _Pragma("unroll") for (int m = 0; m < 4; ++m) _Pragma("unroll") for (int n = 0; n < 2; ++n) _Pragma("unroll") for (int k = 0; k < 2; ++k) \
;         acc[ai][bj][m][n] = __builtin_amdgcn_mfma_f32_16x16x32_bf16(Bt[n][k], At[m][k], acc[ai][bj][m][n], 0, 0, 0); __builtin_amdgcn_s_setprio(0); } while (0)
; template <class Epi, class Sched, bool ALIGN_EPI = false, bool SP2 = false>
; __device__ __forceinline__ void gemm_phase(PG8_LAS unsigned char* lds, const Gemm g, const Sched& S, const Epi& E, const int tid) {
;     ...
;             if constexpr (SP2) {
;             PG8_LDB(B0, 0, 0); PG8_LDB(B1, 0, 1); PG8_SCHED; PG8_LDA(At, 0, 0); PG8_STAGE(PG8_SA(1, 1), a1 + hstep, voffA);
;             PG8_WAIT_V(8); PG8_WAIT_L(0); PG8_BAR; PG8_MMA(0, 0, At, B0); PG8_MMA(0, 1, At, B1); PG8_BAR; PG8_SCHED;
;             PG8_LDA(At, 0, 1); PG8_STAGE(PG8_SB(0, 0), b2, voffB); PG8_STAGE(PG8_SB(0, 1), b2 + hstepB, voffB); PG8_STAGE(PG8_SA(0, 0), a2, voffA);
;             PG8_WAIT_V(8); PG8_WAIT_L(0); PG8_BAR; PG8_MMA(1, 0, At, B0); PG8_MMA(1, 1, At, B1); PG8_BAR; PG8_SCHED;
;             PG8_LDB(B0, 1, 0); PG8_LDB(B1, 1, 1); PG8_SCHED; PG8_LDA(At, 1, 0); PG8_STAGE(PG8_SA(0, 1), a2 + hstep, voffA);
;             PG8_WAIT_V(8); PG8_WAIT_L(0); PG8_BAR; PG8_MMA(0, 0, At, B0); PG8_MMA(0, 1, At, B1); PG8_BAR; PG8_SCHED;
;             PG8_LDA(At, 1, 1); PG8_STAGE(PG8_SB(1, 0), b3, voffB); PG8_STAGE(PG8_SB(1, 1), b3 + hstepB, voffB); PG8_STAGE(PG8_SA(1, 0), a3, voffA);
;             PG8_WAIT_V(8); PG8_WAIT_L(0); PG8_BAR; PG8_MMA(1, 0, At, B0); PG8_MMA(1, 1, At, B1); PG8_BAR; PG8_SCHED;
.Lbw4_0:
	s_waitcnt lgkmcnt(0)
	s_barrier
	s_setprio 0
	s_waitcnt lgkmcnt(0)
	v_mfma_f32_16x16x32_bf16 v[120:123], v[146:149], v[194:197], v[120:123]
	v_mfma_f32_16x16x32_bf16 v[128:131], v[170:173], v[194:197], v[128:131]
	v_mfma_f32_16x16x32_bf16 v[100:103], v[146:149], v[212:215], v[100:103]
	v_mfma_f32_16x16x32_bf16 v[108:111], v[170:173], v[212:215], v[108:111]
	v_mfma_f32_16x16x32_bf16 v[84:87], v[146:149], v[220:223], v[84:87]
	v_mfma_f32_16x16x32_bf16 v[92:95], v[170:173], v[220:223], v[92:95]
	v_mfma_f32_16x16x32_bf16 v[68:71], v[146:149], v[228:231], v[68:71]
	v_mfma_f32_16x16x32_bf16 v[76:79], v[170:173], v[228:231], v[76:79]
	v_mfma_f32_16x16x32_bf16 v[120:123], v[162:165], v[198:201], v[120:123]
	v_mfma_f32_16x16x32_bf16 v[128:131], v[174:177], v[198:201], v[128:131]
	v_mfma_f32_16x16x32_bf16 v[100:103], v[162:165], v[216:219], v[100:103]
	v_mfma_f32_16x16x32_bf16 v[108:111], v[174:177], v[216:219], v[108:111]
	v_mfma_f32_16x16x32_bf16 v[84:87], v[162:165], v[224:227], v[84:87]
	v_mfma_f32_16x16x32_bf16 v[92:95], v[174:177], v[224:227], v[92:95]
	v_mfma_f32_16x16x32_bf16 v[68:71], v[162:165], v[232:235], v[68:71]
	v_mfma_f32_16x16x32_bf16 v[76:79], v[174:177], v[232:235], v[76:79]
	s_setprio 1
	s_setprio 0
	v_mfma_f32_16x16x32_bf16 v[116:119], v[178:181], v[194:197], v[116:119]
	v_mfma_f32_16x16x32_bf16 v[124:127], v[186:189], v[194:197], v[124:127]
	v_mfma_f32_16x16x32_bf16 v[104:107], v[178:181], v[212:215], v[104:107]
	v_mfma_f32_16x16x32_bf16 v[112:115], v[186:189], v[212:215], v[112:115]
	v_mfma_f32_16x16x32_bf16 v[88:91], v[178:181], v[220:223], v[88:91]
	v_mfma_f32_16x16x32_bf16 v[96:99], v[186:189], v[220:223], v[96:99]
	v_mfma_f32_16x16x32_bf16 v[72:75], v[178:181], v[228:231], v[72:75]
	v_mfma_f32_16x16x32_bf16 v[80:83], v[186:189], v[228:231], v[80:83]
	v_mfma_f32_16x16x32_bf16 v[116:119], v[182:185], v[198:201], v[116:119]
	v_mfma_f32_16x16x32_bf16 v[124:127], v[190:193], v[198:201], v[124:127]
	v_mfma_f32_16x16x32_bf16 v[104:107], v[182:185], v[216:219], v[104:107]
	v_mfma_f32_16x16x32_bf16 v[112:115], v[190:193], v[216:219], v[112:115]
	v_mfma_f32_16x16x32_bf16 v[88:91], v[182:185], v[224:227], v[88:91]
	v_mfma_f32_16x16x32_bf16 v[96:99], v[190:193], v[224:227], v[96:99]
	v_mfma_f32_16x16x32_bf16 v[72:75], v[182:185], v[232:235], v[72:75]
	v_mfma_f32_16x16x32_bf16 v[80:83], v[190:193], v[232:235], v[80:83]
	s_setprio 1
	s_barrier
	s_add_i32 s42, s83, s55
	v_lshl_add_u64 v[150:151], v[150:151], 0, s[52:53]
	s_mov_b32 m0, s42
	ds_read_b128 v[194:197], v160 offset:49152
	ds_read_b128 v[198:201], v160 offset:50176
	ds_read_b128 v[212:215], v160 offset:51200
	ds_read_b128 v[216:219], v160 offset:52224
	ds_read_b128 v[220:223], v160 offset:53248
	ds_read_b128 v[224:227], v160 offset:54272
	ds_read_b128 v[228:231], v160 offset:55296
	ds_read_b128 v[232:235], v160 offset:56320
	s_cmp_lg_u32 s32, 0
	s_cbranch_scc1 .Lbt4_8
	global_load_lds_dwordx4 v[150:151], off

; #define PG8_STAGE(bufoff, gbase, voff) do { _Pragma("unroll") for (int _i = 0; _i < 2; ++_i) \
;         __builtin_amdgcn_global_load_lds((const unsigned*)((const char*)(gbase) + (voff)[_i]), (PG8_LAS unsigned*)(lds + (bufoff) + ldsw + _i * 8192), 16, 0, 0); } while (0)
; #define PG8_LDA(dst, b, h) do { _Pragma("unroll") for (int m = 0; m < 4; ++m) _Pragma("unroll") for (int k = 0; k < 2; ++k) dst[m][k] = *(const PG8_LAS bf16x8*)(lds + PG8_SA(b, h) + aoff + m * 2048 + k * 1024); } while (0)
; #define PG8_WAIT_V(n) asm volatile("s_waitcnt vmcnt(" #n ")" ::: "memory")
; #define PG8_WAIT_L(n) asm volatile("s_waitcnt lgkmcnt(" #n ")" ::: "memory")
; template <class Epi, class Sched, bool ALIGN_EPI = false, bool SP2 = false>
; __device__ __forceinline__ void gemm_phase(PG8_LAS unsigned char* lds, const Gemm g, const Sched& S, const Epi& E, const int tid) {
;     ...
;         for (int t = 0; t < nt; t += 2) {
;             const bool last = (t == nt - 2);
;             const char* a1 = cA + (size_t)(t + 1) * kstep;
;             const char* a2 = last ? nA : cA + (size_t)(t + 2) * kstep; const char* b2 = last ? nB : cB + (size_t)(t + 2) * kstep;
;             const char* a3 = a2 + kstep; const char* b3 = b2 + kstep;
;             if (last && has_next) S.a_ready(nxt);
;             if constexpr (SP2) {
;             PG8_LDB(B0, 0, 0); PG8_LDB(B1, 0, 1); PG8_SCHED; PG8_LDA(At, 0, 0); PG8_STAGE(PG8_SA(1, 1), a1 + hstep, voffA);
;             PG8_WAIT_V(8); PG8_WAIT_L(0); PG8_BAR; PG8_MMA(0, 0, At, B0); PG8_MMA(0, 1, At, B1); PG8_BAR; PG8_SCHED;
;             PG8_LDA(At, 0, 1); PG8_STAGE(PG8_SB(0, 0), b2, voffB); PG8_STAGE(PG8_SB(0, 1), b2 + hstepB, voffB); PG8_STAGE(PG8_SA(0, 0), a2, voffA);
;             PG8_WAIT_V(8); PG8_WAIT_L(0); PG8_BAR; PG8_MMA(1, 0, At, B0); PG8_MMA(1, 1, At, B1); PG8_BAR; PG8_SCHED;
;             PG8_LDB(B0, 1, 0); PG8_LDB(B1, 1, 1); PG8_SCHED; PG8_LDA(At, 1, 0); PG8_STAGE(PG8_SA(0, 1), a2 + hstep, voffA);
;             PG8_WAIT_V(8); PG8_WAIT_L(0); PG8_BAR; PG8_MMA(0, 0, At, B0); PG8_MMA(0, 1, At, B1); PG8_BAR; PG8_SCHED;
;             PG8_LDA(At, 1, 1); PG8_STAGE(PG8_SB(1, 0), b3, voffB); PG8_STAGE(PG8_SB(1, 1), b3 + hstepB, voffB); PG8_STAGE(PG8_SA(1, 0), a3, voffA);
;             PG8_WAIT_V(8); PG8_WAIT_L(0); PG8_BAR; PG8_MMA(1, 0, At, B0); PG8_MMA(1, 1, At, B1); PG8_BAR; PG8_SCHED;
;     ...
;         if constexpr (ALIGN_EPI) { if (wr == 0) PG8_BAR; }
.Lbt4_13:
	s_waitcnt vmcnt(8)
	s_waitcnt lgkmcnt(0)
	s_barrier
	s_setprio 0
	s_waitcnt lgkmcnt(0)
	v_mfma_f32_16x16x32_bf16 v[52:55], v[146:149], v[194:197], v[52:55]
	v_mfma_f32_16x16x32_bf16 v[60:63], v[170:173], v[194:197], v[60:63]
	v_mfma_f32_16x16x32_bf16 v[36:39], v[146:149], v[212:215], v[36:39]
	v_mfma_f32_16x16x32_bf16 v[44:47], v[170:173], v[212:215], v[44:47]
	v_mfma_f32_16x16x32_bf16 v[20:23], v[146:149], v[220:223], v[20:23]
	v_mfma_f32_16x16x32_bf16 v[28:31], v[170:173], v[220:223], v[28:31]
	v_mfma_f32_16x16x32_bf16 v[4:7], v[146:149], v[228:231], v[4:7]
	v_mfma_f32_16x16x32_bf16 v[12:15], v[170:173], v[228:231], v[12:15]
	v_mfma_f32_16x16x32_bf16 v[52:55], v[162:165], v[198:201], v[52:55]
	v_mfma_f32_16x16x32_bf16 v[60:63], v[174:177], v[198:201], v[60:63]
	v_mfma_f32_16x16x32_bf16 v[36:39], v[162:165], v[216:219], v[36:39]
	v_mfma_f32_16x16x32_bf16 v[44:47], v[174:177], v[216:219], v[44:47]
	v_mfma_f32_16x16x32_bf16 v[20:23], v[162:165], v[224:227], v[20:23]
	v_mfma_f32_16x16x32_bf16 v[28:31], v[174:177], v[224:227], v[28:31]
	v_mfma_f32_16x16x32_bf16 v[4:7], v[162:165], v[232:235], v[4:7]
	v_mfma_f32_16x16x32_bf16 v[12:15], v[174:177], v[232:235], v[12:15]
	s_setprio 1
	s_setprio 0
	v_mfma_f32_16x16x32_bf16 v[56:59], v[178:181], v[194:197], v[56:59]
	v_mfma_f32_16x16x32_bf16 v[64:67], v[186:189], v[194:197], v[64:67]
	v_mfma_f32_16x16x32_bf16 v[40:43], v[178:181], v[212:215], v[40:43]
	v_mfma_f32_16x16x32_bf16 v[48:51], v[186:189], v[212:215], v[48:51]
	v_mfma_f32_16x16x32_bf16 v[24:27], v[178:181], v[220:223], v[24:27]
	v_mfma_f32_16x16x32_bf16 v[32:35], v[186:189], v[220:223], v[32:35]
	v_mfma_f32_16x16x32_bf16 v[8:11], v[178:181], v[228:231], v[8:11]
	v_mfma_f32_16x16x32_bf16 v[16:19], v[186:189], v[228:231], v[16:19]
	v_mfma_f32_16x16x32_bf16 v[56:59], v[182:185], v[198:201], v[56:59]
	v_mfma_f32_16x16x32_bf16 v[64:67], v[190:193], v[198:201], v[64:67]
	v_mfma_f32_16x16x32_bf16 v[40:43], v[182:185], v[216:219], v[40:43]
	v_mfma_f32_16x16x32_bf16 v[48:51], v[190:193], v[216:219], v[48:51]
	v_mfma_f32_16x16x32_bf16 v[24:27], v[182:185], v[224:227], v[24:27]
	v_mfma_f32_16x16x32_bf16 v[32:35], v[190:193], v[224:227], v[32:35]
	v_mfma_f32_16x16x32_bf16 v[8:11], v[182:185], v[232:235], v[8:11]
	v_mfma_f32_16x16x32_bf16 v[16:19], v[190:193], v[232:235], v[16:19]
	s_setprio 1
	s_barrier
	s_add_i32 s82, s82, 2
	s_add_u32 s40, s40, 0x100
	s_addc_u32 s41, s41, 0
	s_add_u32 s80, s80, 0x100
	s_addc_u32 s81, s81, 0
	s_cmp_gt_u32 s82, 13
	s_cbranch_scc0 .LBB0_1266
	s_and_b64 vcc, exec, s[16:17]
	s_cbranch_vccz .LBB0_1269
	s_barrier

;     DI bool next(int i, Unit& u) const { const int L = i * 32 + rank; if (L >= ppg * nN) return false; u.pm = ppg * grp + (L % ppg); const int p0 = L / ppg, p1 = p0 + rot; u.pn = rev ? nN - 1 - p0 : (p1 >= nN ? p1 - nN : p1); return true; }
; #define PG8_LDA(dst, b, h) do { _Pragma("unroll") for (int m = 0; m < 4; ++m) _Pragma("unroll") for (int k = 0; k < 2; ++k) dst[m][k] = *(const PG8_LAS bf16x8*)(lds + PG8_SA(b, h) + aoff + m * 2048 + k * 1024); } while (0)
; template <class Epi, class Sched, bool ALIGN_EPI = false, bool SP2 = false>
; __device__ __forceinline__ void gemm_phase(PG8_LAS unsigned char* lds, const Gemm g, const Sched& S, const Epi& E, const int tid) {
;     ...
;         const bool has_next = S.next(ui + 1, nxt);
;         const char* nA = has_next ? (const char*)g.A + (size_t)nxt.pm * tstep : cA; const char* nB = has_next ? (const char*)g.Bt + (size_t)nxt.pn * tstep : cB;
;         for (int t = 0; t < nt; t += 2) {
;             const bool last = (t == nt - 2);
;             const char* a1 = cA + (size_t)(t + 1) * kstep;
;             const char* a2 = last ? nA : cA + (size_t)(t + 2) * kstep; const char* b2 = last ? nB : cB + (size_t)(t + 2) * kstep;
;             const char* a3 = a2 + kstep; const char* b3 = b2 + kstep;
;             if (last && has_next) S.a_ready(nxt);
;             if constexpr (SP2) {
;             PG8_LDB(B0, 0, 0); PG8_LDB(B1, 0, 1); PG8_SCHED; PG8_LDA(At, 0, 0); PG8_STAGE(PG8_SA(1, 1), a1 + hstep, voffA);
;             PG8_WAIT_V(8); PG8_WAIT_L(0); PG8_BAR; PG8_MMA(0, 0, At, B0); PG8_MMA(0, 1, At, B1); PG8_BAR; PG8_SCHED;
;             PG8_LDA(At, 0, 1); PG8_STAGE(PG8_SB(0, 0), b2, voffB); PG8_STAGE(PG8_SB(0, 1), b2 + hstepB, voffB); PG8_STAGE(PG8_SA(0, 0), a2, voffA);
;             PG8_WAIT_V(8); PG8_WAIT_L(0); PG8_BAR; PG8_MMA(1, 0, At, B0); PG8_MMA(1, 1, At, B1); PG8_BAR; PG8_SCHED;
;             PG8_LDB(B0, 1, 0); PG8_LDB(B1, 1, 1); PG8_SCHED; PG8_LDA(At, 1, 0); PG8_STAGE(PG8_SA(0, 1), a2 + hstep, voffA);
;             PG8_WAIT_V(8); PG8_WAIT_L(0); PG8_BAR; PG8_MMA(0, 0, At, B0); PG8_MMA(0, 1, At, B1); PG8_BAR; PG8_SCHED;
;             PG8_LDA(At, 1, 1); PG8_STAGE(PG8_SB(1, 0), b3, voffB); PG8_STAGE(PG8_SB(1, 1), b3 + hstepB, voffB); PG8_STAGE(PG8_SA(1, 0), a3, voffA);
;             PG8_WAIT_V(8); PG8_WAIT_L(0); PG8_BAR; PG8_MMA(1, 0, At, B0); PG8_MMA(1, 1, At, B1); PG8_BAR; PG8_SCHED;
.LBB0_1380:
	s_lshl_b32 s98, s79, 7
	s_add_i32 s98, s98, s84
	s_add_i32 s99, s98, 0x100
	s_and_b32 s98, s98, 0x700
	s_and_b32 s99, s99, 0x700
	s_add_u32 s100, s30, s98
	s_addc_u32 s101, s31, 0
	s_add_u32 s36, s30, 0xfffbff80
	s_addc_u32 s37, s31, -1
	s_add_u32 s36, s36, s99
	s_addc_u32 s37, s37, 0
	s_add_u32 s92, s76, s99
	s_addc_u32 s93, s78, 0
	s_add_i32 s80, 0, 0x10000
	s_cmp_eq_u32 s79, 12
	s_cselect_b32 s39, s17, s37
	s_cselect_b32 s38, s66, s36
	v_add_u32_e32 v150, s80, v158
	s_cselect_b32 s37, s19, s93
	s_cselect_b32 s36, s67, s92
	s_cmp_eq_u32 s79, 12
	s_cselect_b32 s32, 1, 0
	s_andn2_b32 s32, s32, s22
	s_add_i32 s82, 0, 0x14000
	ds_read_b128 v[146:149], v150
	ds_read_b128 v[164:167], v150 offset:1024
	ds_read_b128 v[170:173], v150 offset:2048
	ds_read_b128 v[174:177], v150 offset:3072
	v_add_u32_e32 v150, s82, v158
	ds_read_b128 v[178:181], v150
	ds_read_b128 v[182:185], v150 offset:1024
	ds_read_b128 v[186:189], v150 offset:2048
	ds_read_b128 v[190:193], v150 offset:3072
	v_lshl_add_u64 v[150:151], s[100:101], 0, v[142:143]
	s_add_i32 m0, s29, 0xc000
	ds_read_b128 v[194:197], v163
	ds_read_b128 v[198:201], v163 offset:1024
	ds_read_b128 v[212:215], v163 offset:2048
	ds_read_b128 v[216:219], v163 offset:3072
	ds_read_b128 v[220:223], v163 offset:4096
	ds_read_b128 v[224:227], v163 offset:5120
	ds_read_b128 v[228:231], v163 offset:6144
	ds_read_b128 v[232:235], v163 offset:7168
	global_load_lds_dwordx4 v[150:151], off
	v_lshl_add_u64 v[150:151], s[100:101], 0, v[144:145]
	s_add_i32 m0, s29, 0xe000
	s_nop 0
	global_load_lds_dwordx4 v[150:151], off
	s_waitcnt vmcnt(8)
	s_waitcnt lgkmcnt(0)
	s_barrier
	s_setprio 0
	s_waitcnt lgkmcnt(0)
	v_mfma_f32_16x16x32_bf16 v[128:131], v[146:149], v[194:197], v[128:131]
	v_mfma_f32_16x16x32_bf16 v[124:127], v[170:173], v[194:197], v[124:127]
	v_mfma_f32_16x16x32_bf16 v[112:115], v[146:149], v[212:215], v[112:115]
	v_mfma_f32_16x16x32_bf16 v[108:111], v[170:173], v[212:215], v[108:111]
	v_mfma_f32_16x16x32_bf16 v[96:99], v[146:149], v[220:223], v[96:99]
	v_mfma_f32_16x16x32_bf16 v[92:95], v[170:173], v[220:223], v[92:95]
	v_mfma_f32_16x16x32_bf16 v[80:83], v[146:149], v[228:231], v[80:83]
	v_mfma_f32_16x16x32_bf16 v[76:79], v[170:173], v[228:231], v[76:79]
	v_mfma_f32_16x16x32_bf16 v[128:131], v[164:167], v[198:201], v[128:131]
	v_mfma_f32_16x16x32_bf16 v[124:127], v[174:177], v[198:201], v[124:127]
	v_mfma_f32_16x16x32_bf16 v[112:115], v[164:167], v[216:219], v[112:115]
	v_mfma_f32_16x16x32_bf16 v[108:111], v[174:177], v[216:219], v[108:111]
	v_mfma_f32_16x16x32_bf16 v[96:99], v[164:167], v[224:227], v[96:99]
	v_mfma_f32_16x16x32_bf16 v[92:95], v[174:177], v[224:227], v[92:95]
	v_mfma_f32_16x16x32_bf16 v[80:83], v[164:167], v[232:235], v[80:83]
	v_mfma_f32_16x16x32_bf16 v[76:79], v[174:177], v[232:235], v[76:79]
	s_setprio 1
	s_setprio 0
	v_mfma_f32_16x16x32_bf16 v[120:123], v[178:181], v[194:197], v[120:123]
	v_mfma_f32_16x16x32_bf16 v[116:119], v[186:189], v[194:197], v[116:119]
	v_mfma_f32_16x16x32_bf16 v[104:107], v[178:181], v[212:215], v[104:107]
	v_mfma_f32_16x16x32_bf16 v[100:103], v[186:189], v[212:215], v[100:103]
	v_mfma_f32_16x16x32_bf16 v[88:91], v[178:181], v[220:223], v[88:91]
	v_mfma_f32_16x16x32_bf16 v[84:87], v[186:189], v[220:223], v[84:87]
	v_mfma_f32_16x16x32_bf16 v[72:75], v[178:181], v[228:231], v[72:75]
	v_mfma_f32_16x16x32_bf16 v[68:71], v[186:189], v[228:231], v[68:71]
	v_mfma_f32_16x16x32_bf16 v[120:123], v[182:185], v[198:201], v[120:123]
	v_mfma_f32_16x16x32_bf16 v[116:119], v[190:193], v[198:201], v[116:119]
	v_mfma_f32_16x16x32_bf16 v[104:107], v[182:185], v[216:219], v[104:107]
	v_mfma_f32_16x16x32_bf16 v[100:103], v[190:193], v[216:219], v[100:103]
	v_mfma_f32_16x16x32_bf16 v[88:91], v[182:185], v[224:227], v[88:91]
	v_mfma_f32_16x16x32_bf16 v[84:87], v[190:193], v[224:227], v[84:87]
	v_mfma_f32_16x16x32_bf16 v[72:75], v[182:185], v[232:235], v[72:75]
	v_mfma_f32_16x16x32_bf16 v[68:71], v[190:193], v[232:235], v[68:71]
	s_setprio 1
	s_barrier
	s_add_i32 s80, s80, s42
	v_lshl_add_u64 v[150:151], s[36:37], 0, v[138:139]
	s_mov_b32 m0, s80
	ds_read_b128 v[194:197], v163 offset:16384
	ds_read_b128 v[198:201], v163 offset:17408
	ds_read_b128 v[212:215], v163 offset:18432
	ds_read_b128 v[216:219], v163 offset:19456
	ds_read_b128 v[220:223], v163 offset:20480
	ds_read_b128 v[224:227], v163 offset:21504
	ds_read_b128 v[228:231], v163 offset:22528
	ds_read_b128 v[232:235], v163 offset:23552
	s_cmp_lg_u32 s32, 0
	s_cbranch_scc1 .Lbt5_0
	global_load_lds_dwordx4 v[150:151], off

; #define PG8_STAGE(bufoff, gbase, voff) do { _Pragma("unroll") for (int _i = 0; _i < 2; ++_i) \
;         __builtin_amdgcn_global_load_lds((const unsigned*)((const char*)(gbase) + (voff)[_i]), (PG8_LAS unsigned*)(lds + (bufoff) + ldsw + _i * 8192), 16, 0, 0); } while (0)
; #define PG8_LDA(dst, b, h) do { _Pragma("unroll") for (int m = 0; m < 4; ++m) _Pragma("unroll") for (int k = 0; k < 2; ++k) dst[m][k] = *(const PG8_LAS bf16x8*)(lds + PG8_SA(b, h) + aoff + m * 2048 + k * 1024); } while (0)
; #define PG8_LDB(dst, b, h) do { _Pragma("unroll") for (int n = 0; n < 2; ++n) _Pragma("unroll") for (int k = 0; k < 2; ++k) dst[n][k] = *(const PG8_LAS bf16x8*)(lds + PG8_SB(b, h) + boff + n * 2048 + k * 1024); } while (0)
; #define PG8_MMA(ai, bj, At, Bt) do { __builtin_amdgcn_s_setprio(1); _Pragma("unroll") for (int m = 0; m < 4; ++m) _Pragma("unroll") for (int n = 0; n < 2; ++n) _Pragma("unroll") for (int k = 0; k < 2; ++k) \
;         acc[ai][bj][m][n] = __builtin_amdgcn_mfma_f32_16x16x32_bf16(Bt[n][k], At[m][k], acc[ai][bj][m][n], 0, 0, 0); __builtin_amdgcn_s_setprio(0); } while (0)
; template <class Epi, class Sched, bool ALIGN_EPI = false, bool SP2 = false>
; __device__ __forceinline__ void gemm_phase(PG8_LAS unsigned char* lds, const Gemm g, const Sched& S, const Epi& E, const int tid) {
;     ...
;             if constexpr (SP2) {
;             PG8_LDB(B0, 0, 0); PG8_LDB(B1, 0, 1); PG8_SCHED; PG8_LDA(At, 0, 0); PG8_STAGE(PG8_SA(1, 1), a1 + hstep, voffA);
;             PG8_WAIT_V(8); PG8_WAIT_L(0); PG8_BAR; PG8_MMA(0, 0, At, B0); PG8_MMA(0, 1, At, B1); PG8_BAR; PG8_SCHED;
;             PG8_LDA(At, 0, 1); PG8_STAGE(PG8_SB(0, 0), b2, voffB); PG8_STAGE(PG8_SB(0, 1), b2 + hstepB, voffB); PG8_STAGE(PG8_SA(0, 0), a2, voffA);
;             PG8_WAIT_V(8); PG8_WAIT_L(0); PG8_BAR; PG8_MMA(1, 0, At, B0); PG8_MMA(1, 1, At, B1); PG8_BAR; PG8_SCHED;
;             PG8_LDB(B0, 1, 0); PG8_LDB(B1, 1, 1); PG8_SCHED; PG8_LDA(At, 1, 0); PG8_STAGE(PG8_SA(0, 1), a2 + hstep, voffA);
;             PG8_WAIT_V(8); PG8_WAIT_L(0); PG8_BAR; PG8_MMA(0, 0, At, B0); PG8_MMA(0, 1, At, B1); PG8_BAR; PG8_SCHED;
;             PG8_LDA(At, 1, 1); PG8_STAGE(PG8_SB(1, 0), b3, voffB); PG8_STAGE(PG8_SB(1, 1), b3 + hstepB, voffB); PG8_STAGE(PG8_SA(1, 0), a3, voffA);
;             PG8_WAIT_V(8); PG8_WAIT_L(0); PG8_BAR; PG8_MMA(1, 0, At, B0); PG8_MMA(1, 1, At, B1); PG8_BAR; PG8_SCHED;
.Lbw5_2:
	s_waitcnt lgkmcnt(0)
	s_barrier
	s_setprio 0
	s_waitcnt lgkmcnt(0)
	v_mfma_f32_16x16x32_bf16 v[64:67], v[146:149], v[194:197], v[64:67]
	v_mfma_f32_16x16x32_bf16 v[60:63], v[170:173], v[194:197], v[60:63]
	v_mfma_f32_16x16x32_bf16 v[48:51], v[146:149], v[212:215], v[48:51]
	v_mfma_f32_16x16x32_bf16 v[44:47], v[170:173], v[212:215], v[44:47]
	v_mfma_f32_16x16x32_bf16 v[32:35], v[146:149], v[220:223], v[32:35]
	v_mfma_f32_16x16x32_bf16 v[28:31], v[170:173], v[220:223], v[28:31]
	v_mfma_f32_16x16x32_bf16 v[16:19], v[146:149], v[228:231], v[16:19]
	v_mfma_f32_16x16x32_bf16 v[12:15], v[170:173], v[228:231], v[12:15]
	v_mfma_f32_16x16x32_bf16 v[64:67], v[164:167], v[198:201], v[64:67]
	v_mfma_f32_16x16x32_bf16 v[60:63], v[174:177], v[198:201], v[60:63]
	v_mfma_f32_16x16x32_bf16 v[48:51], v[164:167], v[216:219], v[48:51]
	v_mfma_f32_16x16x32_bf16 v[44:47], v[174:177], v[216:219], v[44:47]
	v_mfma_f32_16x16x32_bf16 v[32:35], v[164:167], v[224:227], v[32:35]
	v_mfma_f32_16x16x32_bf16 v[28:31], v[174:177], v[224:227], v[28:31]
	v_mfma_f32_16x16x32_bf16 v[16:19], v[164:167], v[232:235], v[16:19]
	v_mfma_f32_16x16x32_bf16 v[12:15], v[174:177], v[232:235], v[12:15]
	s_setprio 1
	s_setprio 0
	v_mfma_f32_16x16x32_bf16 v[56:59], v[178:181], v[194:197], v[56:59]
	v_mfma_f32_16x16x32_bf16 v[52:55], v[186:189], v[194:197], v[52:55]
	v_mfma_f32_16x16x32_bf16 v[40:43], v[178:181], v[212:215], v[40:43]
	v_mfma_f32_16x16x32_bf16 v[36:39], v[186:189], v[212:215], v[36:39]
	v_mfma_f32_16x16x32_bf16 v[24:27], v[178:181], v[220:223], v[24:27]
	v_mfma_f32_16x16x32_bf16 v[20:23], v[186:189], v[220:223], v[20:23]
	v_mfma_f32_16x16x32_bf16 v[8:11], v[178:181], v[228:231], v[8:11]
	v_mfma_f32_16x16x32_bf16 v[4:7], v[186:189], v[228:231], v[4:7]
	v_mfma_f32_16x16x32_bf16 v[56:59], v[182:185], v[198:201], v[56:59]
	v_mfma_f32_16x16x32_bf16 v[52:55], v[190:193], v[198:201], v[52:55]
	v_mfma_f32_16x16x32_bf16 v[40:43], v[182:185], v[216:219], v[40:43]
	v_mfma_f32_16x16x32_bf16 v[36:39], v[190:193], v[216:219], v[36:39]
	v_mfma_f32_16x16x32_bf16 v[24:27], v[182:185], v[224:227], v[24:27]
	v_mfma_f32_16x16x32_bf16 v[20:23], v[190:193], v[224:227], v[20:23]
	v_mfma_f32_16x16x32_bf16 v[8:11], v[182:185], v[232:235], v[8:11]
	v_mfma_f32_16x16x32_bf16 v[4:7], v[190:193], v[232:235], v[4:7]
	s_setprio 1
	s_barrier
	s_add_i32 s80, 0, 0x18000
	s_add_i32 s81, 0, 0x1c000
	v_add_u32_e32 v174, s80, v158
	v_add_u32_e32 v190, s81, v158
	ds_read_b128 v[146:149], v174
	ds_read_b128 v[164:167], v174 offset:1024
	ds_read_b128 v[170:173], v174 offset:2048
	ds_read_b128 v[174:177], v174 offset:3072
	ds_read_b128 v[178:181], v190
	ds_read_b128 v[182:185], v190 offset:1024
	ds_read_b128 v[186:189], v190 offset:2048
	ds_read_b128 v[190:193], v190 offset:3072
	s_add_u32 s38, s38, 0x40000
	s_addc_u32 s39, s39, 0
	s_mov_b32 m0, s55
	v_lshl_add_u64 v[242:243], s[38:39], 0, v[140:141]
	ds_read_b128 v[194:197], v163 offset:32768
	ds_read_b128 v[198:201], v163 offset:33792
	ds_read_b128 v[212:215], v163 offset:34816
	ds_read_b128 v[216:219], v163 offset:35840
	ds_read_b128 v[220:223], v163 offset:36864
	ds_read_b128 v[224:227], v163 offset:37888
	ds_read_b128 v[228:231], v163 offset:38912
	ds_read_b128 v[232:235], v163 offset:39936
	s_cmp_lg_u32 s32, 0
	s_cbranch_scc1 .Lbt5_6
	global_load_lds_dwordx4 v[242:243], off

; #define PG8_STAGE(bufoff, gbase, voff) do { _Pragma("unroll") for (int _i = 0; _i < 2; ++_i) \
;         __builtin_amdgcn_global_load_lds((const unsigned*)((const char*)(gbase) + (voff)[_i]), (PG8_LAS unsigned*)(lds + (bufoff) + ldsw + _i * 8192), 16, 0, 0); } while (0)
; #define PG8_LDA(dst, b, h) do { _Pragma("unroll") for (int m = 0; m < 4; ++m) _Pragma("unroll") for (int k = 0; k < 2; ++k) dst[m][k] = *(const PG8_LAS bf16x8*)(lds + PG8_SA(b, h) + aoff + m * 2048 + k * 1024); } while (0)
; #define PG8_LDB(dst, b, h) do { _Pragma("unroll") for (int n = 0; n < 2; ++n) _Pragma("unroll") for (int k = 0; k < 2; ++k) dst[n][k] = *(const PG8_LAS bf16x8*)(lds + PG8_SB(b, h) + boff + n * 2048 + k * 1024); } while (0)
; #define PG8_MMA(ai, bj, At, Bt) do { __builtin_amdgcn_s_setprio(1); _Pragma("unroll") for (int m = 0; m < 4; ++m) _Pragma("unroll") for (int n = 0; n < 2; ++n) _Pragma("unroll") for (int k = 0; k < 2; ++k) \
;         acc[ai][bj][m][n] = __builtin_amdgcn_mfma_f32_16x16x32_bf16(Bt[n][k], At[m][k], acc[ai][bj][m][n], 0, 0, 0); __builtin_amdgcn_s_setprio(0); } while (0)
; template <class Epi, class Sched, bool ALIGN_EPI = false, bool SP2 = false>
; __device__ __forceinline__ void gemm_phase(PG8_LAS unsigned char* lds, const Gemm g, const Sched& S, const Epi& E, const int tid) {
;     ...
;             if constexpr (SP2) {
;             PG8_LDB(B0, 0, 0); PG8_LDB(B1, 0, 1); PG8_SCHED; PG8_LDA(At, 0, 0); PG8_STAGE(PG8_SA(1, 1), a1 + hstep, voffA);
;             PG8_WAIT_V(8); PG8_WAIT_L(0); PG8_BAR; PG8_MMA(0, 0, At, B0); PG8_MMA(0, 1, At, B1); PG8_BAR; PG8_SCHED;
;             PG8_LDA(At, 0, 1); PG8_STAGE(PG8_SB(0, 0), b2, voffB); PG8_STAGE(PG8_SB(0, 1), b2 + hstepB, voffB); PG8_STAGE(PG8_SA(0, 0), a2, voffA);
;             PG8_WAIT_V(8); PG8_WAIT_L(0); PG8_BAR; PG8_MMA(1, 0, At, B0); PG8_MMA(1, 1, At, B1); PG8_BAR; PG8_SCHED;
;             PG8_LDB(B0, 1, 0); PG8_LDB(B1, 1, 1); PG8_SCHED; PG8_LDA(At, 1, 0); PG8_STAGE(PG8_SA(0, 1), a2 + hstep, voffA);
;             PG8_WAIT_V(8); PG8_WAIT_L(0); PG8_BAR; PG8_MMA(0, 0, At, B0); PG8_MMA(0, 1, At, B1); PG8_BAR; PG8_SCHED;
;             PG8_LDA(At, 1, 1); PG8_STAGE(PG8_SB(1, 0), b3, voffB); PG8_STAGE(PG8_SB(1, 1), b3 + hstepB, voffB); PG8_STAGE(PG8_SA(1, 0), a3, voffA);
;             PG8_WAIT_V(8); PG8_WAIT_L(0); PG8_BAR; PG8_MMA(1, 0, At, B0); PG8_MMA(1, 1, At, B1); PG8_BAR; PG8_SCHED;
.Lbw5_0:
	s_waitcnt lgkmcnt(0)
	s_barrier
	s_setprio 0
	s_waitcnt lgkmcnt(0)
	v_mfma_f32_16x16x32_bf16 v[128:131], v[146:149], v[194:197], v[128:131]
	v_mfma_f32_16x16x32_bf16 v[124:127], v[170:173], v[194:197], v[124:127]
	v_mfma_f32_16x16x32_bf16 v[112:115], v[146:149], v[212:215], v[112:115]
	v_mfma_f32_16x16x32_bf16 v[108:111], v[170:173], v[212:215], v[108:111]
	v_mfma_f32_16x16x32_bf16 v[96:99], v[146:149], v[220:223], v[96:99]
	v_mfma_f32_16x16x32_bf16 v[92:95], v[170:173], v[220:223], v[92:95]
	v_mfma_f32_16x16x32_bf16 v[80:83], v[146:149], v[228:231], v[80:83]
	v_mfma_f32_16x16x32_bf16 v[76:79], v[170:173], v[228:231], v[76:79]
	v_mfma_f32_16x16x32_bf16 v[128:131], v[164:167], v[198:201], v[128:131]
	v_mfma_f32_16x16x32_bf16 v[124:127], v[174:177], v[198:201], v[124:127]
	v_mfma_f32_16x16x32_bf16 v[112:115], v[164:167], v[216:219], v[112:115]
	v_mfma_f32_16x16x32_bf16 v[108:111], v[174:177], v[216:219], v[108:111]
	v_mfma_f32_16x16x32_bf16 v[96:99], v[164:167], v[224:227], v[96:99]
	v_mfma_f32_16x16x32_bf16 v[92:95], v[174:177], v[224:227], v[92:95]
	v_mfma_f32_16x16x32_bf16 v[80:83], v[164:167], v[232:235], v[80:83]
	v_mfma_f32_16x16x32_bf16 v[76:79], v[174:177], v[232:235], v[76:79]
	s_setprio 1
	s_setprio 0
	v_mfma_f32_16x16x32_bf16 v[120:123], v[178:181], v[194:197], v[120:123]
	v_mfma_f32_16x16x32_bf16 v[116:119], v[186:189], v[194:197], v[116:119]
	v_mfma_f32_16x16x32_bf16 v[104:107], v[178:181], v[212:215], v[104:107]
	v_mfma_f32_16x16x32_bf16 v[100:103], v[186:189], v[212:215], v[100:103]
	v_mfma_f32_16x16x32_bf16 v[88:91], v[178:181], v[220:223], v[88:91]
	v_mfma_f32_16x16x32_bf16 v[84:87], v[186:189], v[220:223], v[84:87]
	v_mfma_f32_16x16x32_bf16 v[72:75], v[178:181], v[228:231], v[72:75]
	v_mfma_f32_16x16x32_bf16 v[68:71], v[186:189], v[228:231], v[68:71]
	v_mfma_f32_16x16x32_bf16 v[120:123], v[182:185], v[198:201], v[120:123]
	v_mfma_f32_16x16x32_bf16 v[116:119], v[190:193], v[198:201], v[116:119]
	v_mfma_f32_16x16x32_bf16 v[104:107], v[182:185], v[216:219], v[104:107]
	v_mfma_f32_16x16x32_bf16 v[100:103], v[190:193], v[216:219], v[100:103]
	v_mfma_f32_16x16x32_bf16 v[88:91], v[182:185], v[224:227], v[88:91]
	v_mfma_f32_16x16x32_bf16 v[84:87], v[190:193], v[224:227], v[84:87]
	v_mfma_f32_16x16x32_bf16 v[72:75], v[182:185], v[232:235], v[72:75]
	v_mfma_f32_16x16x32_bf16 v[68:71], v[190:193], v[232:235], v[68:71]
	s_setprio 1
	s_barrier
	s_add_i32 s38, s80, s42
	v_lshl_add_u64 v[150:151], v[150:151], 0, s[52:53]
	s_mov_b32 m0, s38
	ds_read_b128 v[194:197], v163 offset:49152
	ds_read_b128 v[198:201], v163 offset:50176
	ds_read_b128 v[212:215], v163 offset:51200
	ds_read_b128 v[216:219], v163 offset:52224
	ds_read_b128 v[220:223], v163 offset:53248
	ds_read_b128 v[224:227], v163 offset:54272
	ds_read_b128 v[228:231], v163 offset:55296
	ds_read_b128 v[232:235], v163 offset:56320
	s_cmp_lg_u32 s32, 0
	s_cbranch_scc1 .Lbt5_8
	global_load_lds_dwordx4 v[150:151], off

; #define PG8_STAGE(bufoff, gbase, voff) do { _Pragma("unroll") for (int _i = 0; _i < 2; ++_i) \
;         __builtin_amdgcn_global_load_lds((const unsigned*)((const char*)(gbase) + (voff)[_i]), (PG8_LAS unsigned*)(lds + (bufoff) + ldsw + _i * 8192), 16, 0, 0); } while (0)
; #define PG8_LDA(dst, b, h) do { _Pragma("unroll") for (int m = 0; m < 4; ++m) _Pragma("unroll") for (int k = 0; k < 2; ++k) dst[m][k] = *(const PG8_LAS bf16x8*)(lds + PG8_SA(b, h) + aoff + m * 2048 + k * 1024); } while (0)
; #define PG8_WAIT_V(n) asm volatile("s_waitcnt vmcnt(" #n ")" ::: "memory")
; #define PG8_WAIT_L(n) asm volatile("s_waitcnt lgkmcnt(" #n ")" ::: "memory")
; template <class Epi, class Sched, bool ALIGN_EPI = false, bool SP2 = false>
; __device__ __forceinline__ void gemm_phase(PG8_LAS unsigned char* lds, const Gemm g, const Sched& S, const Epi& E, const int tid) {
;     ...
;         for (int t = 0; t < nt; t += 2) {
;             const bool last = (t == nt - 2);
;             const char* a1 = cA + (size_t)(t + 1) * kstep;
;             const char* a2 = last ? nA : cA + (size_t)(t + 2) * kstep; const char* b2 = last ? nB : cB + (size_t)(t + 2) * kstep;
;             const char* a3 = a2 + kstep; const char* b3 = b2 + kstep;
;             if (last && has_next) S.a_ready(nxt);
;             if constexpr (SP2) {
;             PG8_LDB(B0, 0, 0); PG8_LDB(B1, 0, 1); PG8_SCHED; PG8_LDA(At, 0, 0); PG8_STAGE(PG8_SA(1, 1), a1 + hstep, voffA);
;             PG8_WAIT_V(8); PG8_WAIT_L(0); PG8_BAR; PG8_MMA(0, 0, At, B0); PG8_MMA(0, 1, At, B1); PG8_BAR; PG8_SCHED;
;             PG8_LDA(At, 0, 1); PG8_STAGE(PG8_SB(0, 0), b2, voffB); PG8_STAGE(PG8_SB(0, 1), b2 + hstepB, voffB); PG8_STAGE(PG8_SA(0, 0), a2, voffA);
;             PG8_WAIT_V(8); PG8_WAIT_L(0); PG8_BAR; PG8_MMA(1, 0, At, B0); PG8_MMA(1, 1, At, B1); PG8_BAR; PG8_SCHED;
;             PG8_LDB(B0, 1, 0); PG8_LDB(B1, 1, 1); PG8_SCHED; PG8_LDA(At, 1, 0); PG8_STAGE(PG8_SA(0, 1), a2 + hstep, voffA);
;             PG8_WAIT_V(8); PG8_WAIT_L(0); PG8_BAR; PG8_MMA(0, 0, At, B0); PG8_MMA(0, 1, At, B1); PG8_BAR; PG8_SCHED;
;             PG8_LDA(At, 1, 1); PG8_STAGE(PG8_SB(1, 0), b3, voffB); PG8_STAGE(PG8_SB(1, 1), b3 + hstepB, voffB); PG8_STAGE(PG8_SA(1, 0), a3, voffA);
;             PG8_WAIT_V(8); PG8_WAIT_L(0); PG8_BAR; PG8_MMA(1, 0, At, B0); PG8_MMA(1, 1, At, B1); PG8_BAR; PG8_SCHED;
;     ...
;         if constexpr (ALIGN_EPI) { if (wr == 0) PG8_BAR; }
.Lbt5_13:
	s_waitcnt vmcnt(8)
	s_waitcnt lgkmcnt(0)
	s_barrier
	s_setprio 0
	s_waitcnt lgkmcnt(0)
	v_mfma_f32_16x16x32_bf16 v[64:67], v[146:149], v[194:197], v[64:67]
	v_mfma_f32_16x16x32_bf16 v[60:63], v[170:173], v[194:197], v[60:63]
	v_mfma_f32_16x16x32_bf16 v[48:51], v[146:149], v[212:215], v[48:51]
	v_mfma_f32_16x16x32_bf16 v[44:47], v[170:173], v[212:215], v[44:47]
	v_mfma_f32_16x16x32_bf16 v[32:35], v[146:149], v[220:223], v[32:35]
	v_mfma_f32_16x16x32_bf16 v[28:31], v[170:173], v[220:223], v[28:31]
	v_mfma_f32_16x16x32_bf16 v[16:19], v[146:149], v[228:231], v[16:19]
	v_mfma_f32_16x16x32_bf16 v[12:15], v[170:173], v[228:231], v[12:15]
	v_mfma_f32_16x16x32_bf16 v[64:67], v[164:167], v[198:201], v[64:67]
	v_mfma_f32_16x16x32_bf16 v[60:63], v[174:177], v[198:201], v[60:63]
	v_mfma_f32_16x16x32_bf16 v[48:51], v[164:167], v[216:219], v[48:51]
	v_mfma_f32_16x16x32_bf16 v[44:47], v[174:177], v[216:219], v[44:47]
	v_mfma_f32_16x16x32_bf16 v[32:35], v[164:167], v[224:227], v[32:35]
	v_mfma_f32_16x16x32_bf16 v[28:31], v[174:177], v[224:227], v[28:31]
	v_mfma_f32_16x16x32_bf16 v[16:19], v[164:167], v[232:235], v[16:19]
	v_mfma_f32_16x16x32_bf16 v[12:15], v[174:177], v[232:235], v[12:15]
	s_setprio 1
	s_setprio 0
	v_mfma_f32_16x16x32_bf16 v[56:59], v[178:181], v[194:197], v[56:59]
	v_mfma_f32_16x16x32_bf16 v[52:55], v[186:189], v[194:197], v[52:55]
	v_mfma_f32_16x16x32_bf16 v[40:43], v[178:181], v[212:215], v[40:43]
	v_mfma_f32_16x16x32_bf16 v[36:39], v[186:189], v[212:215], v[36:39]
	v_mfma_f32_16x16x32_bf16 v[24:27], v[178:181], v[220:223], v[24:27]
	v_mfma_f32_16x16x32_bf16 v[20:23], v[186:189], v[220:223], v[20:23]
	v_mfma_f32_16x16x32_bf16 v[8:11], v[178:181], v[228:231], v[8:11]
	v_mfma_f32_16x16x32_bf16 v[4:7], v[186:189], v[228:231], v[4:7]
	v_mfma_f32_16x16x32_bf16 v[56:59], v[182:185], v[198:201], v[56:59]
	v_mfma_f32_16x16x32_bf16 v[52:55], v[190:193], v[198:201], v[52:55]
	v_mfma_f32_16x16x32_bf16 v[40:43], v[182:185], v[216:219], v[40:43]
	v_mfma_f32_16x16x32_bf16 v[36:39], v[190:193], v[216:219], v[36:39]
	v_mfma_f32_16x16x32_bf16 v[24:27], v[182:185], v[224:227], v[24:27]
	v_mfma_f32_16x16x32_bf16 v[20:23], v[190:193], v[224:227], v[20:23]
	v_mfma_f32_16x16x32_bf16 v[8:11], v[182:185], v[232:235], v[8:11]
	v_mfma_f32_16x16x32_bf16 v[4:7], v[190:193], v[232:235], v[4:7]
	s_setprio 1
	s_barrier
	s_add_i32 s79, s79, 2
	s_cmp_gt_u32 s79, 13
	s_cbranch_scc0 .LBB0_1380
	s_and_b64 vcc, exec, s[14:15]
	s_cbranch_vccz .LBB0_1383
	s_barrier

;     DI bool next(int i, Unit& u) const { const int L = i * 32 + rank; if (L >= ppg * nN) return false; u.pm = ppg * grp + (L % ppg); const int p0 = L / ppg, p1 = p0 + rot; u.pn = rev ? nN - 1 - p0 : (p1 >= nN ? p1 - nN : p1); return true; }
; #define PG8_LDA(dst, b, h) do { _Pragma("unroll") for (int m = 0; m < 4; ++m) _Pragma("unroll") for (int k = 0; k < 2; ++k) dst[m][k] = *(const PG8_LAS bf16x8*)(lds + PG8_SA(b, h) + aoff + m * 2048 + k * 1024); } while (0)
; template <class Epi, class Sched, bool ALIGN_EPI = false, bool SP2 = false>
; __device__ __forceinline__ void gemm_phase(PG8_LAS unsigned char* lds, const Gemm g, const Sched& S, const Epi& E, const int tid) {
;     ...
;         const bool has_next = S.next(ui + 1, nxt);
;         const char* nA = has_next ? (const char*)g.A + (size_t)nxt.pm * tstep : cA; const char* nB = has_next ? (const char*)g.Bt + (size_t)nxt.pn * tstep : cB;
;         for (int t = 0; t < nt; t += 2) {
;             const bool last = (t == nt - 2);
;             const char* a1 = cA + (size_t)(t + 1) * kstep;
;             const char* a2 = last ? nA : cA + (size_t)(t + 2) * kstep; const char* b2 = last ? nB : cB + (size_t)(t + 2) * kstep;
;             const char* a3 = a2 + kstep; const char* b3 = b2 + kstep;
;             if (last && has_next) S.a_ready(nxt);
;             if constexpr (SP2) {
;             PG8_LDB(B0, 0, 0); PG8_LDB(B1, 0, 1); PG8_SCHED; PG8_LDA(At, 0, 0); PG8_STAGE(PG8_SA(1, 1), a1 + hstep, voffA);
;             PG8_WAIT_V(8); PG8_WAIT_L(0); PG8_BAR; PG8_MMA(0, 0, At, B0); PG8_MMA(0, 1, At, B1); PG8_BAR; PG8_SCHED;
;             PG8_LDA(At, 0, 1); PG8_STAGE(PG8_SB(0, 0), b2, voffB); PG8_STAGE(PG8_SB(0, 1), b2 + hstepB, voffB); PG8_STAGE(PG8_SA(0, 0), a2, voffA);
;             PG8_WAIT_V(8); PG8_WAIT_L(0); PG8_BAR; PG8_MMA(1, 0, At, B0); PG8_MMA(1, 1, At, B1); PG8_BAR; PG8_SCHED;
;             PG8_LDB(B0, 1, 0); PG8_LDB(B1, 1, 1); PG8_SCHED; PG8_LDA(At, 1, 0); PG8_STAGE(PG8_SA(0, 1), a2 + hstep, voffA);
;             PG8_WAIT_V(8); PG8_WAIT_L(0); PG8_BAR; PG8_MMA(0, 0, At, B0); PG8_MMA(0, 1, At, B1); PG8_BAR; PG8_SCHED;
;             PG8_LDA(At, 1, 1); PG8_STAGE(PG8_SB(1, 0), b3, voffB); PG8_STAGE(PG8_SB(1, 1), b3 + hstepB, voffB); PG8_STAGE(PG8_SA(1, 0), a3, voffA);
;             PG8_WAIT_V(8); PG8_WAIT_L(0); PG8_BAR; PG8_MMA(1, 0, At, B0); PG8_MMA(1, 1, At, B1); PG8_BAR; PG8_SCHED;
.LBB0_1460:
	s_add_u32 s36, s38, 0xfff00080
	s_addc_u32 s37, s39, -1
	s_add_i32 s81, 0, 0x10000
	s_cmp_eq_u32 s80, 60
	s_cselect_b32 s41, s19, s37
	s_cselect_b32 s40, s25, s36
	v_add_u32_e32 v150, s81, v158
	s_cselect_b32 s37, s17, s79
	s_cselect_b32 s36, s76, s78
	s_cmp_eq_u32 s80, 60
	s_cselect_b32 s32, 1, 0
	s_andn2_b32 s32, s32, s30
	s_add_i32 s84, 0, 0x14000
	ds_read_b128 v[146:149], v150
	ds_read_b128 v[162:165], v150 offset:1024
	ds_read_b128 v[170:173], v150 offset:2048
	ds_read_b128 v[174:177], v150 offset:3072
	v_add_u32_e32 v150, s84, v158
	ds_read_b128 v[178:181], v150
	ds_read_b128 v[182:185], v150 offset:1024
	ds_read_b128 v[186:189], v150 offset:2048
	ds_read_b128 v[190:193], v150 offset:3072
	v_lshl_add_u64 v[150:151], s[38:39], 0, v[142:143]
	s_add_i32 m0, s29, 0xc000
	ds_read_b128 v[194:197], v160
	ds_read_b128 v[198:201], v160 offset:1024
	ds_read_b128 v[212:215], v160 offset:2048
	ds_read_b128 v[216:219], v160 offset:3072
	ds_read_b128 v[220:223], v160 offset:4096
	ds_read_b128 v[224:227], v160 offset:5120
	ds_read_b128 v[228:231], v160 offset:6144
	ds_read_b128 v[232:235], v160 offset:7168
	global_load_lds_dwordx4 v[150:151], off
	v_lshl_add_u64 v[150:151], s[38:39], 0, v[144:145]
	s_add_i32 m0, s29, 0xe000
	s_nop 0
	global_load_lds_dwordx4 v[150:151], off
	s_waitcnt vmcnt(8)
	s_waitcnt lgkmcnt(0)
	s_barrier
	s_setprio 0
	s_waitcnt lgkmcnt(0)
	v_mfma_f32_16x16x32_bf16 v[120:123], v[146:149], v[194:197], v[120:123]
	v_mfma_f32_16x16x32_bf16 v[128:131], v[170:173], v[194:197], v[128:131]
	v_mfma_f32_16x16x32_bf16 v[100:103], v[146:149], v[212:215], v[100:103]
	v_mfma_f32_16x16x32_bf16 v[108:111], v[170:173], v[212:215], v[108:111]
	v_mfma_f32_16x16x32_bf16 v[84:87], v[146:149], v[220:223], v[84:87]
	v_mfma_f32_16x16x32_bf16 v[92:95], v[170:173], v[220:223], v[92:95]
	v_mfma_f32_16x16x32_bf16 v[68:71], v[146:149], v[228:231], v[68:71]
	v_mfma_f32_16x16x32_bf16 v[76:79], v[170:173], v[228:231], v[76:79]
	v_mfma_f32_16x16x32_bf16 v[120:123], v[162:165], v[198:201], v[120:123]
	v_mfma_f32_16x16x32_bf16 v[128:131], v[174:177], v[198:201], v[128:131]
	v_mfma_f32_16x16x32_bf16 v[100:103], v[162:165], v[216:219], v[100:103]
	v_mfma_f32_16x16x32_bf16 v[108:111], v[174:177], v[216:219], v[108:111]
	v_mfma_f32_16x16x32_bf16 v[84:87], v[162:165], v[224:227], v[84:87]
	v_mfma_f32_16x16x32_bf16 v[92:95], v[174:177], v[224:227], v[92:95]
	v_mfma_f32_16x16x32_bf16 v[68:71], v[162:165], v[232:235], v[68:71]
	v_mfma_f32_16x16x32_bf16 v[76:79], v[174:177], v[232:235], v[76:79]
	s_setprio 1
	s_setprio 0
	v_mfma_f32_16x16x32_bf16 v[116:119], v[178:181], v[194:197], v[116:119]
	v_mfma_f32_16x16x32_bf16 v[124:127], v[186:189], v[194:197], v[124:127]
	v_mfma_f32_16x16x32_bf16 v[104:107], v[178:181], v[212:215], v[104:107]
	v_mfma_f32_16x16x32_bf16 v[112:115], v[186:189], v[212:215], v[112:115]
	v_mfma_f32_16x16x32_bf16 v[88:91], v[178:181], v[220:223], v[88:91]
	v_mfma_f32_16x16x32_bf16 v[96:99], v[186:189], v[220:223], v[96:99]
	v_mfma_f32_16x16x32_bf16 v[72:75], v[178:181], v[228:231], v[72:75]
	v_mfma_f32_16x16x32_bf16 v[80:83], v[186:189], v[228:231], v[80:83]
	v_mfma_f32_16x16x32_bf16 v[116:119], v[182:185], v[198:201], v[116:119]
	v_mfma_f32_16x16x32_bf16 v[124:127], v[190:193], v[198:201], v[124:127]
	v_mfma_f32_16x16x32_bf16 v[104:107], v[182:185], v[216:219], v[104:107]
	v_mfma_f32_16x16x32_bf16 v[112:115], v[190:193], v[216:219], v[112:115]
	v_mfma_f32_16x16x32_bf16 v[88:91], v[182:185], v[224:227], v[88:91]
	v_mfma_f32_16x16x32_bf16 v[96:99], v[190:193], v[224:227], v[96:99]
	v_mfma_f32_16x16x32_bf16 v[72:75], v[182:185], v[232:235], v[72:75]
	v_mfma_f32_16x16x32_bf16 v[80:83], v[190:193], v[232:235], v[80:83]
	s_setprio 1
	s_barrier
	s_add_i32 s81, s81, s43
	v_lshl_add_u64 v[150:151], s[36:37], 0, v[136:137]
	s_mov_b32 m0, s81
	ds_read_b128 v[194:197], v160 offset:16384
	ds_read_b128 v[198:201], v160 offset:17408
	ds_read_b128 v[212:215], v160 offset:18432
	ds_read_b128 v[216:219], v160 offset:19456
	ds_read_b128 v[220:223], v160 offset:20480
	ds_read_b128 v[224:227], v160 offset:21504
	ds_read_b128 v[228:231], v160 offset:22528
	ds_read_b128 v[232:235], v160 offset:23552
	s_cmp_lg_u32 s32, 0
	s_cbranch_scc1 .Lbt1460_0
	global_load_lds_dwordx4 v[150:151], off

; #define PG8_STAGE(bufoff, gbase, voff) do { _Pragma("unroll") for (int _i = 0; _i < 2; ++_i) \
;         __builtin_amdgcn_global_load_lds((const unsigned*)((const char*)(gbase) + (voff)[_i]), (PG8_LAS unsigned*)(lds + (bufoff) + ldsw + _i * 8192), 16, 0, 0); } while (0)
; #define PG8_LDA(dst, b, h) do { _Pragma("unroll") for (int m = 0; m < 4; ++m) _Pragma("unroll") for (int k = 0; k < 2; ++k) dst[m][k] = *(const PG8_LAS bf16x8*)(lds + PG8_SA(b, h) + aoff + m * 2048 + k * 1024); } while (0)
; #define PG8_LDB(dst, b, h) do { _Pragma("unroll") for (int n = 0; n < 2; ++n) _Pragma("unroll") for (int k = 0; k < 2; ++k) dst[n][k] = *(const PG8_LAS bf16x8*)(lds + PG8_SB(b, h) + boff + n * 2048 + k * 1024); } while (0)
; #define PG8_MMA(ai, bj, At, Bt) do { __builtin_amdgcn_s_setprio(1); _Pragma("unroll") for (int m = 0; m < 4; ++m) _Pragma("unroll") for (int n = 0; n < 2; ++n) _Pragma("unroll") for (int k = 0; k < 2; ++k) \
;         acc[ai][bj][m][n] = __builtin_amdgcn_mfma_f32_16x16x32_bf16(Bt[n][k], At[m][k], acc[ai][bj][m][n], 0, 0, 0); __builtin_amdgcn_s_setprio(0); } while (0)
; template <class Epi, class Sched, bool ALIGN_EPI = false, bool SP2 = false>
; __device__ __forceinline__ void gemm_phase(PG8_LAS unsigned char* lds, const Gemm g, const Sched& S, const Epi& E, const int tid) {
;     ...
;             if constexpr (SP2) {
;             PG8_LDB(B0, 0, 0); PG8_LDB(B1, 0, 1); PG8_SCHED; PG8_LDA(At, 0, 0); PG8_STAGE(PG8_SA(1, 1), a1 + hstep, voffA);
;             PG8_WAIT_V(8); PG8_WAIT_L(0); PG8_BAR; PG8_MMA(0, 0, At, B0); PG8_MMA(0, 1, At, B1); PG8_BAR; PG8_SCHED;
;             PG8_LDA(At, 0, 1); PG8_STAGE(PG8_SB(0, 0), b2, voffB); PG8_STAGE(PG8_SB(0, 1), b2 + hstepB, voffB); PG8_STAGE(PG8_SA(0, 0), a2, voffA);
;             PG8_WAIT_V(8); PG8_WAIT_L(0); PG8_BAR; PG8_MMA(1, 0, At, B0); PG8_MMA(1, 1, At, B1); PG8_BAR; PG8_SCHED;
;             PG8_LDB(B0, 1, 0); PG8_LDB(B1, 1, 1); PG8_SCHED; PG8_LDA(At, 1, 0); PG8_STAGE(PG8_SA(0, 1), a2 + hstep, voffA);
;             PG8_WAIT_V(8); PG8_WAIT_L(0); PG8_BAR; PG8_MMA(0, 0, At, B0); PG8_MMA(0, 1, At, B1); PG8_BAR; PG8_SCHED;
;             PG8_LDA(At, 1, 1); PG8_STAGE(PG8_SB(1, 0), b3, voffB); PG8_STAGE(PG8_SB(1, 1), b3 + hstepB, voffB); PG8_STAGE(PG8_SA(1, 0), a3, voffA);
;             PG8_WAIT_V(8); PG8_WAIT_L(0); PG8_BAR; PG8_MMA(1, 0, At, B0); PG8_MMA(1, 1, At, B1); PG8_BAR; PG8_SCHED;
.Lbw1460_2:
	s_waitcnt lgkmcnt(0)
	s_barrier
	s_setprio 0
	s_waitcnt lgkmcnt(0)
	v_mfma_f32_16x16x32_bf16 v[52:55], v[146:149], v[194:197], v[52:55]
	v_mfma_f32_16x16x32_bf16 v[60:63], v[170:173], v[194:197], v[60:63]
	v_mfma_f32_16x16x32_bf16 v[36:39], v[146:149], v[212:215], v[36:39]
	v_mfma_f32_16x16x32_bf16 v[44:47], v[170:173], v[212:215], v[44:47]
	v_mfma_f32_16x16x32_bf16 v[20:23], v[146:149], v[220:223], v[20:23]
	v_mfma_f32_16x16x32_bf16 v[28:31], v[170:173], v[220:223], v[28:31]
	v_mfma_f32_16x16x32_bf16 v[4:7], v[146:149], v[228:231], v[4:7]
	v_mfma_f32_16x16x32_bf16 v[12:15], v[170:173], v[228:231], v[12:15]
	v_mfma_f32_16x16x32_bf16 v[52:55], v[162:165], v[198:201], v[52:55]
	v_mfma_f32_16x16x32_bf16 v[60:63], v[174:177], v[198:201], v[60:63]
	v_mfma_f32_16x16x32_bf16 v[36:39], v[162:165], v[216:219], v[36:39]
	v_mfma_f32_16x16x32_bf16 v[44:47], v[174:177], v[216:219], v[44:47]
	v_mfma_f32_16x16x32_bf16 v[20:23], v[162:165], v[224:227], v[20:23]
	v_mfma_f32_16x16x32_bf16 v[28:31], v[174:177], v[224:227], v[28:31]
	v_mfma_f32_16x16x32_bf16 v[4:7], v[162:165], v[232:235], v[4:7]
	v_mfma_f32_16x16x32_bf16 v[12:15], v[174:177], v[232:235], v[12:15]
	s_setprio 1
	s_setprio 0
	v_mfma_f32_16x16x32_bf16 v[56:59], v[178:181], v[194:197], v[56:59]
	v_mfma_f32_16x16x32_bf16 v[64:67], v[186:189], v[194:197], v[64:67]
	v_mfma_f32_16x16x32_bf16 v[40:43], v[178:181], v[212:215], v[40:43]
	v_mfma_f32_16x16x32_bf16 v[48:51], v[186:189], v[212:215], v[48:51]
	v_mfma_f32_16x16x32_bf16 v[24:27], v[178:181], v[220:223], v[24:27]
	v_mfma_f32_16x16x32_bf16 v[32:35], v[186:189], v[220:223], v[32:35]
	v_mfma_f32_16x16x32_bf16 v[8:11], v[178:181], v[228:231], v[8:11]
	v_mfma_f32_16x16x32_bf16 v[16:19], v[186:189], v[228:231], v[16:19]
	v_mfma_f32_16x16x32_bf16 v[56:59], v[182:185], v[198:201], v[56:59]
	v_mfma_f32_16x16x32_bf16 v[64:67], v[190:193], v[198:201], v[64:67]
	v_mfma_f32_16x16x32_bf16 v[40:43], v[182:185], v[216:219], v[40:43]
	v_mfma_f32_16x16x32_bf16 v[48:51], v[190:193], v[216:219], v[48:51]
	v_mfma_f32_16x16x32_bf16 v[24:27], v[182:185], v[224:227], v[24:27]
	v_mfma_f32_16x16x32_bf16 v[32:35], v[190:193], v[224:227], v[32:35]
	v_mfma_f32_16x16x32_bf16 v[8:11], v[182:185], v[232:235], v[8:11]
	v_mfma_f32_16x16x32_bf16 v[16:19], v[190:193], v[232:235], v[16:19]
	s_setprio 1
	s_barrier
	s_add_i32 s81, 0, 0x18000
	v_add_u32_e32 v161, s81, v158
	s_add_i32 s82, 0, 0x1c000
	ds_read_b128 v[146:149], v161
	ds_read_b128 v[162:165], v161 offset:1024
	ds_read_b128 v[170:173], v161 offset:2048
	ds_read_b128 v[174:177], v161 offset:3072
	v_add_u32_e32 v161, s82, v158
	ds_read_b128 v[178:181], v161
	ds_read_b128 v[182:185], v161 offset:1024
	ds_read_b128 v[186:189], v161 offset:2048
	ds_read_b128 v[190:193], v161 offset:3072
	s_add_u32 s40, s40, 0x100000
	s_addc_u32 s41, s41, 0
	s_mov_b32 m0, s62
	v_lshl_add_u64 v[240:241], s[40:41], 0, v[134:135]
	ds_read_b128 v[194:197], v160 offset:32768
	ds_read_b128 v[198:201], v160 offset:33792
	ds_read_b128 v[212:215], v160 offset:34816
	ds_read_b128 v[216:219], v160 offset:35840
	ds_read_b128 v[220:223], v160 offset:36864
	ds_read_b128 v[224:227], v160 offset:37888
	ds_read_b128 v[228:231], v160 offset:38912
	ds_read_b128 v[232:235], v160 offset:39936
	s_cmp_lg_u32 s32, 0
	s_cbranch_scc1 .Lbt1460_6
	global_load_lds_dwordx4 v[240:241], off

; #define PG8_STAGE(bufoff, gbase, voff) do { _Pragma("unroll") for (int _i = 0; _i < 2; ++_i) \
;         __builtin_amdgcn_global_load_lds((const unsigned*)((const char*)(gbase) + (voff)[_i]), (PG8_LAS unsigned*)(lds + (bufoff) + ldsw + _i * 8192), 16, 0, 0); } while (0)
; #define PG8_LDA(dst, b, h) do { _Pragma("unroll") for (int m = 0; m < 4; ++m) _Pragma("unroll") for (int k = 0; k < 2; ++k) dst[m][k] = *(const PG8_LAS bf16x8*)(lds + PG8_SA(b, h) + aoff + m * 2048 + k * 1024); } while (0)
; #define PG8_WAIT_V(n) asm volatile("s_waitcnt vmcnt(" #n ")" ::: "memory")
; #define PG8_WAIT_L(n) asm volatile("s_waitcnt lgkmcnt(" #n ")" ::: "memory")
; template <class Epi, class Sched, bool ALIGN_EPI = false, bool SP2 = false>
; __device__ __forceinline__ void gemm_phase(PG8_LAS unsigned char* lds, const Gemm g, const Sched& S, const Epi& E, const int tid) {
;     ...
;         for (int t = 0; t < nt; t += 2) {
;             const bool last = (t == nt - 2);
;             const char* a1 = cA + (size_t)(t + 1) * kstep;
;             const char* a2 = last ? nA : cA + (size_t)(t + 2) * kstep; const char* b2 = last ? nB : cB + (size_t)(t + 2) * kstep;
;             const char* a3 = a2 + kstep; const char* b3 = b2 + kstep;
;             if (last && has_next) S.a_ready(nxt);
;             if constexpr (SP2) {
;             PG8_LDB(B0, 0, 0); PG8_LDB(B1, 0, 1); PG8_SCHED; PG8_LDA(At, 0, 0); PG8_STAGE(PG8_SA(1, 1), a1 + hstep, voffA);
;             PG8_WAIT_V(8); PG8_WAIT_L(0); PG8_BAR; PG8_MMA(0, 0, At, B0); PG8_MMA(0, 1, At, B1); PG8_BAR; PG8_SCHED;
;             PG8_LDA(At, 0, 1); PG8_STAGE(PG8_SB(0, 0), b2, voffB); PG8_STAGE(PG8_SB(0, 1), b2 + hstepB, voffB); PG8_STAGE(PG8_SA(0, 0), a2, voffA);
;             PG8_WAIT_V(8); PG8_WAIT_L(0); PG8_BAR; PG8_MMA(1, 0, At, B0); PG8_MMA(1, 1, At, B1); PG8_BAR; PG8_SCHED;
;             PG8_LDB(B0, 1, 0); PG8_LDB(B1, 1, 1); PG8_SCHED; PG8_LDA(At, 1, 0); PG8_STAGE(PG8_SA(0, 1), a2 + hstep, voffA);
;             PG8_WAIT_V(8); PG8_WAIT_L(0); PG8_BAR; PG8_MMA(0, 0, At, B0); PG8_MMA(0, 1, At, B1); PG8_BAR; PG8_SCHED;
;             PG8_LDA(At, 1, 1); PG8_STAGE(PG8_SB(1, 0), b3, voffB); PG8_STAGE(PG8_SB(1, 1), b3 + hstepB, voffB); PG8_STAGE(PG8_SA(1, 0), a3, voffA);
;             PG8_WAIT_V(8); PG8_WAIT_L(0); PG8_BAR; PG8_MMA(1, 0, At, B0); PG8_MMA(1, 1, At, B1); PG8_BAR; PG8_SCHED;
;     ...
;         if constexpr (ALIGN_EPI) { if (wr == 0) PG8_BAR; }
.Lbt1460_13:
	s_waitcnt vmcnt(8)
	s_waitcnt lgkmcnt(0)
	s_barrier
	s_setprio 0
	s_waitcnt lgkmcnt(0)
	v_mfma_f32_16x16x32_bf16 v[52:55], v[146:149], v[194:197], v[52:55]
	v_mfma_f32_16x16x32_bf16 v[60:63], v[170:173], v[194:197], v[60:63]
	v_mfma_f32_16x16x32_bf16 v[36:39], v[146:149], v[212:215], v[36:39]
	v_mfma_f32_16x16x32_bf16 v[44:47], v[170:173], v[212:215], v[44:47]
	v_mfma_f32_16x16x32_bf16 v[20:23], v[146:149], v[220:223], v[20:23]
	v_mfma_f32_16x16x32_bf16 v[28:31], v[170:173], v[220:223], v[28:31]
	v_mfma_f32_16x16x32_bf16 v[4:7], v[146:149], v[228:231], v[4:7]
	v_mfma_f32_16x16x32_bf16 v[12:15], v[170:173], v[228:231], v[12:15]
	v_mfma_f32_16x16x32_bf16 v[52:55], v[162:165], v[198:201], v[52:55]
	v_mfma_f32_16x16x32_bf16 v[60:63], v[174:177], v[198:201], v[60:63]
	v_mfma_f32_16x16x32_bf16 v[36:39], v[162:165], v[216:219], v[36:39]
	v_mfma_f32_16x16x32_bf16 v[44:47], v[174:177], v[216:219], v[44:47]
	v_mfma_f32_16x16x32_bf16 v[20:23], v[162:165], v[224:227], v[20:23]
	v_mfma_f32_16x16x32_bf16 v[28:31], v[174:177], v[224:227], v[28:31]
	v_mfma_f32_16x16x32_bf16 v[4:7], v[162:165], v[232:235], v[4:7]
	v_mfma_f32_16x16x32_bf16 v[12:15], v[174:177], v[232:235], v[12:15]
	s_setprio 1
	s_setprio 0
	v_mfma_f32_16x16x32_bf16 v[56:59], v[178:181], v[194:197], v[56:59]
	v_mfma_f32_16x16x32_bf16 v[64:67], v[186:189], v[194:197], v[64:67]
	v_mfma_f32_16x16x32_bf16 v[40:43], v[178:181], v[212:215], v[40:43]
	v_mfma_f32_16x16x32_bf16 v[48:51], v[186:189], v[212:215], v[48:51]
	v_mfma_f32_16x16x32_bf16 v[24:27], v[178:181], v[220:223], v[24:27]
	v_mfma_f32_16x16x32_bf16 v[32:35], v[186:189], v[220:223], v[32:35]
	v_mfma_f32_16x16x32_bf16 v[8:11], v[178:181], v[228:231], v[8:11]
	v_mfma_f32_16x16x32_bf16 v[16:19], v[186:189], v[228:231], v[16:19]
	v_mfma_f32_16x16x32_bf16 v[56:59], v[182:185], v[198:201], v[56:59]
	v_mfma_f32_16x16x32_bf16 v[64:67], v[190:193], v[198:201], v[64:67]
	v_mfma_f32_16x16x32_bf16 v[40:43], v[182:185], v[216:219], v[40:43]
	v_mfma_f32_16x16x32_bf16 v[48:51], v[190:193], v[216:219], v[48:51]
	v_mfma_f32_16x16x32_bf16 v[24:27], v[182:185], v[224:227], v[24:27]
	v_mfma_f32_16x16x32_bf16 v[32:35], v[190:193], v[224:227], v[32:35]
	v_mfma_f32_16x16x32_bf16 v[8:11], v[182:185], v[232:235], v[8:11]
	v_mfma_f32_16x16x32_bf16 v[16:19], v[190:193], v[232:235], v[16:19]
	s_setprio 1
	s_barrier
	s_add_i32 s80, s80, 2
	s_add_u32 s38, s38, 0x100
	s_addc_u32 s39, s39, 0
	s_add_u32 s78, s78, 0x100
	s_addc_u32 s79, s79, 0
	s_cmp_gt_u32 s80, 61
	s_cbranch_scc0 .LBB0_1460
	s_and_b64 vcc, exec, s[14:15]
	s_cbranch_vccz .LBB0_1463
	s_barrier
